# GEMM: first K-iteration peeled with SrcC=0 (no accumulator zeroing) and store-aware vmcnt in the peeled iteration (unit start no longer waits for the previous epilogue's stores)
# speedup vs baseline: 1.0714x; 1.0020x over previous
.LBB0_424:
	s_add_i32 s24, s14, 0x18000
	s_mov_b64 s[76:77], 0x80
	v_lshl_add_u64 v[6:7], v[6:7], 0, s[76:77]
	s_mov_b32 m0, s24
	s_add_i32 s25, s14, 0x1a000
	s_waitcnt vmcnt(2)
	s_mov_b32 s99, 0
	s_barrier
	global_load_lds_dwordx4 v[6:7], off
	v_lshl_add_u64 v[4:5], v[4:5], 0, s[76:77]
	s_mov_b32 m0, s25
	s_add_i32 s26, s14, 0x8000
	global_load_lds_dwordx4 v[4:5], off
	v_lshl_add_u64 v[4:5], v[8:9], 0, s[76:77]
	s_mov_b32 m0, s26
	s_add_i32 s27, s14, 0xa000
	global_load_lds_dwordx4 v[4:5], off
	v_lshl_add_u64 v[4:5], v[10:11], 0, s[76:77]
	s_mov_b32 m0, s27
	s_add_i32 s28, s14, 0x1c000
	global_load_lds_dwordx4 v[4:5], off
	v_lshl_add_u64 v[2:3], v[2:3], 0, s[76:77]
	s_mov_b32 m0, s28
	s_add_i32 s29, s14, 0x1e000
	global_load_lds_dwordx4 v[2:3], off
	v_lshl_add_u64 v[0:1], v[0:1], 0, s[76:77]
	s_mov_b32 m0, s29
	s_sext_i32_i8 s81, s0
	global_load_lds_dwordx4 v[0:1], off
	s_ashr_i32 s0, s3, 31
	v_bfe_u32 v145, v12, 4, 2
	s_lshr_b32 s0, s0, 26
	v_and_b32_e32 v144, 15, v12
	s_add_i32 s0, s3, s0
	v_lshlrev_b32_e32 v0, 4, v145
	v_lshlrev_b32_e32 v1, 2, v12
	s_ashr_i32 s30, s0, 6
	v_lshl_or_b32 v0, v144, 6, v0
	s_lshl_b32 s0, s34, 13
	v_and_b32_e32 v1, 32, v1
	v_bitop3_b32 v146, v0, s0, v1 bitop3:0xde
	s_lshl_b32 s0, s33, 5
	s_and_b32 s0, s0, 0x60
	s_lshl_b32 s4, s0, 7
	v_bitop3_b32 v2, v0, s4, v1 bitop3:0xde
	v_add_u32_e32 v0, v18, v16
	s_lshl_b32 s31, s34, 6
	v_add_lshl_u32 v0, v0, v17, 1
	v_mov_b32_e32 v1, v133
	s_cmp_gt_i32 s3, 63
	v_lshl_add_u64 v[136:137], s[8:9], 0, v[0:1]
	v_add_u32_e32 v0, v15, v13
	s_waitcnt vmcnt(6)
	s_cselect_b64 s[4:5], -1, 0
	s_add_i32 s33, s30, -2
	v_readlane_b32 s6, v246, 5
	v_add_lshl_u32 v0, v0, v14, 1
	s_cmpk_lt_u32 s1, 0x100
	v_readlane_b32 s7, v246, 6
	v_lshl_add_u64 v[138:139], s[8:9], 0, v[0:1]
	v_cndmask_b32_e64 v0, 0, 1, s[4:5]
	s_cselect_b64 s[78:79], -1, 0
	s_ashr_i32 s34, s31, 31
	s_ashr_i32 s35, s6, 31
	s_mov_b32 s68, s6
	v_mov_b64_e32 v[140:141], 0xc60
	v_mov_b64_e32 v[142:143], 0xc5f
	v_cmp_ne_u32_e64 s[6:7], 1, v0
	v_or_b32_e32 v147, 0x10000, v2
	v_add_u32_e32 v148, 0x10400, v2
	v_add_u32_e32 v149, 0x10800, v2
	v_add_u32_e32 v150, 0x10c00, v2
	v_or_b32_e32 v151, 0x14000, v2
	v_add_u32_e32 v152, 0x14400, v2
	v_add_u32_e32 v153, 0x14800, v2
	v_add_u32_e32 v154, 0x14c00, v2
	s_add_i32 s69, s14, 0xc000
	s_add_i32 s72, s14, 0xe000
	v_or_b32_e32 v155, 0x18000, v2
	v_add_u32_e32 v156, 0x18400, v2
	v_add_u32_e32 v157, 0x18800, v2
	v_add_u32_e32 v158, 0x18c00, v2
	v_or_b32_e32 v159, 0x1c000, v2
	v_add_u32_e32 v160, 0x1c400, v2
	v_add_u32_e32 v161, 0x1c800, v2
	v_add_u32_e32 v163, 0x1cc00, v2
	s_movk_i32 s73, 0x1600
	s_lshl_b32 s70, s0, 1
	s_mov_b32 s80, s71
	s_barrier
	s_branch .LBB0_427

.LBB0_433:
	s_and_b64 vcc, exec, s[6:7]
	s_cbranch_vccnz .Lkz_1
	s_branch .Lkp_1
.Lkz_1:
	v_mov_b32_e32 v127, 0
	v_mov_b32_e32 v126, v127
	v_mov_b32_e32 v125, v127
	v_mov_b32_e32 v124, v127
	v_mov_b32_e32 v119, v127
	v_mov_b32_e32 v118, v127
	v_mov_b32_e32 v117, v127
	v_mov_b32_e32 v116, v127
	v_mov_b32_e32 v111, v127
	v_mov_b32_e32 v110, v127
	v_mov_b32_e32 v109, v127
	v_mov_b32_e32 v108, v127
	v_mov_b32_e32 v103, v127
	v_mov_b32_e32 v102, v127
	v_mov_b32_e32 v101, v127
	v_mov_b32_e32 v100, v127
	v_mov_b32_e32 v95, v127
	v_mov_b32_e32 v94, v127
	v_mov_b32_e32 v93, v127
	v_mov_b32_e32 v92, v127
	v_mov_b32_e32 v87, v127
	v_mov_b32_e32 v86, v127
	v_mov_b32_e32 v85, v127
	v_mov_b32_e32 v84, v127
	v_mov_b32_e32 v79, v127
	v_mov_b32_e32 v78, v127
	v_mov_b32_e32 v77, v127
	v_mov_b32_e32 v76, v127
	v_mov_b32_e32 v71, v127
	v_mov_b32_e32 v70, v127
	v_mov_b32_e32 v69, v127
	v_mov_b32_e32 v68, v127
	v_mov_b32_e32 v123, v127
	v_mov_b32_e32 v122, v127
	v_mov_b32_e32 v121, v127
	v_mov_b32_e32 v120, v127
	v_mov_b32_e32 v115, v127
	v_mov_b32_e32 v114, v127
	v_mov_b32_e32 v113, v127
	v_mov_b32_e32 v112, v127
	v_mov_b32_e32 v107, v127
	v_mov_b32_e32 v106, v127
	v_mov_b32_e32 v105, v127
	v_mov_b32_e32 v104, v127
	v_mov_b32_e32 v99, v127
	v_mov_b32_e32 v98, v127
	v_mov_b32_e32 v97, v127
	v_mov_b32_e32 v96, v127
	v_mov_b32_e32 v91, v127
	v_mov_b32_e32 v90, v127
	v_mov_b32_e32 v89, v127
	v_mov_b32_e32 v88, v127
	v_mov_b32_e32 v83, v127
	v_mov_b32_e32 v82, v127
	v_mov_b32_e32 v81, v127
	v_mov_b32_e32 v80, v127
	v_mov_b32_e32 v75, v127
	v_mov_b32_e32 v74, v127
	v_mov_b32_e32 v73, v127
	v_mov_b32_e32 v72, v127
	v_mov_b32_e32 v67, v127
	v_mov_b32_e32 v66, v127
	v_mov_b32_e32 v65, v127
	v_mov_b32_e32 v64, v127
	v_mov_b32_e32 v63, v127
	v_mov_b32_e32 v62, v127
	v_mov_b32_e32 v61, v127
	v_mov_b32_e32 v60, v127
	v_mov_b32_e32 v55, v127
	v_mov_b32_e32 v54, v127
	v_mov_b32_e32 v53, v127
	v_mov_b32_e32 v52, v127
	v_mov_b32_e32 v47, v127
	v_mov_b32_e32 v46, v127
	v_mov_b32_e32 v45, v127
	v_mov_b32_e32 v44, v127
	v_mov_b32_e32 v39, v127
	v_mov_b32_e32 v38, v127
	v_mov_b32_e32 v37, v127
	v_mov_b32_e32 v36, v127
	v_mov_b32_e32 v31, v127
	v_mov_b32_e32 v30, v127
	v_mov_b32_e32 v29, v127
	v_mov_b32_e32 v28, v127
	v_mov_b32_e32 v23, v127
	v_mov_b32_e32 v22, v127
	v_mov_b32_e32 v21, v127
	v_mov_b32_e32 v20, v127
	v_mov_b32_e32 v15, v127
	v_mov_b32_e32 v14, v127
	v_mov_b32_e32 v13, v127
	v_mov_b32_e32 v12, v127
	v_mov_b32_e32 v7, v127
	v_mov_b32_e32 v6, v127
	v_mov_b32_e32 v5, v127
	v_mov_b32_e32 v4, v127
	v_mov_b32_e32 v59, v127
	v_mov_b32_e32 v58, v127
	v_mov_b32_e32 v57, v127
	v_mov_b32_e32 v56, v127
	v_mov_b32_e32 v51, v127
	v_mov_b32_e32 v50, v127
	v_mov_b32_e32 v49, v127
	v_mov_b32_e32 v48, v127
	v_mov_b32_e32 v43, v127
	v_mov_b32_e32 v42, v127
	v_mov_b32_e32 v41, v127
	v_mov_b32_e32 v40, v127
	v_mov_b32_e32 v35, v127
	v_mov_b32_e32 v34, v127
	v_mov_b32_e32 v33, v127
	v_mov_b32_e32 v32, v127
	v_mov_b32_e32 v27, v127
	v_mov_b32_e32 v26, v127
	v_mov_b32_e32 v25, v127
	v_mov_b32_e32 v24, v127
	v_mov_b32_e32 v19, v127
	v_mov_b32_e32 v18, v127
	v_mov_b32_e32 v17, v127
	v_mov_b32_e32 v16, v127
	v_mov_b32_e32 v11, v127
	v_mov_b32_e32 v10, v127
	v_mov_b32_e32 v9, v127
	v_mov_b32_e32 v8, v127
	v_mov_b32_e32 v3, v127
	v_mov_b32_e32 v2, v127
	v_mov_b32_e32 v1, v127
	v_mov_b32_e32 v0, v127
	s_branch .LBB0_436
.Lkp_1:
	s_add_u32 s92, s92, 0x80
	s_addc_u32 s93, s93, 0
	s_add_u32 s91, s94, 0x100
	s_addc_u32 vcc_lo, s95, 0
	s_mov_b32 s94, 0
	ds_read_b128 v[164:167], v147
	ds_read_b128 v[168:171], v148
	ds_read_b128 v[172:175], v149
	ds_read_b128 v[176:179], v150
	ds_read_b128 v[180:183], v151
	ds_read_b128 v[184:187], v152
	ds_read_b128 v[188:191], v153
	ds_read_b128 v[192:195], v154
	s_add_i32 vcc_hi, s94, 2
	s_add_u32 s52, s92, 0x80
	s_addc_u32 s53, s93, 0
	s_cmp_eq_u32 s33, s94
	s_cselect_b32 s94, s0, s52
	s_cselect_b32 s95, s1, s53
	s_cselect_b32 s53, s83, vcc_lo
	s_cselect_b32 s52, s82, s91
	s_mov_b32 m0, s69
	v_lshl_add_u64 v[228:229], s[92:93], 0, v[136:137]
	ds_read_b128 v[196:199], v146
	ds_read_b128 v[200:203], v146 offset:1024
	ds_read_b128 v[204:207], v146 offset:2048
	ds_read_b128 v[208:211], v146 offset:3072
	ds_read_b128 v[212:215], v146 offset:4096
	ds_read_b128 v[216:219], v146 offset:5120
	ds_read_b128 v[220:223], v146 offset:6144
	ds_read_b128 v[224:227], v146 offset:7168
	global_load_lds_dwordx4 v[228:229], off
	v_lshl_add_u64 v[228:229], s[92:93], 0, v[138:139]
	s_mov_b32 m0, s72
	s_nop 0
	global_load_lds_dwordx4 v[228:229], off
	s_cmp_lg_u32 s99, 0
	s_cbranch_scc1 .Lsw_1_0
	s_waitcnt vmcnt(8)
.Lsw_1_0:
	s_waitcnt vmcnt(16)
	s_waitcnt lgkmcnt(0)
	s_barrier
	s_setprio 1
	s_waitcnt lgkmcnt(0)
	v_mfma_f32_16x16x32_bf16 v[124:127], v[164:167], v[196:199], 0
	v_mfma_f32_16x16x32_bf16 v[116:119], v[172:175], v[196:199], 0
	v_mfma_f32_16x16x32_bf16 v[108:111], v[164:167], v[204:207], 0
	v_mfma_f32_16x16x32_bf16 v[100:103], v[172:175], v[204:207], 0
	v_mfma_f32_16x16x32_bf16 v[92:95], v[164:167], v[212:215], 0
	v_mfma_f32_16x16x32_bf16 v[84:87], v[172:175], v[212:215], 0
	v_mfma_f32_16x16x32_bf16 v[76:79], v[164:167], v[220:223], 0
	v_mfma_f32_16x16x32_bf16 v[68:71], v[172:175], v[220:223], 0
	v_mfma_f32_16x16x32_bf16 v[124:127], v[168:171], v[200:203], v[124:127]
	v_mfma_f32_16x16x32_bf16 v[116:119], v[176:179], v[200:203], v[116:119]
	v_mfma_f32_16x16x32_bf16 v[108:111], v[168:171], v[208:211], v[108:111]
	v_mfma_f32_16x16x32_bf16 v[100:103], v[176:179], v[208:211], v[100:103]
	v_mfma_f32_16x16x32_bf16 v[92:95], v[168:171], v[216:219], v[92:95]
	v_mfma_f32_16x16x32_bf16 v[84:87], v[176:179], v[216:219], v[84:87]
	v_mfma_f32_16x16x32_bf16 v[76:79], v[168:171], v[224:227], v[76:79]
	v_mfma_f32_16x16x32_bf16 v[68:71], v[176:179], v[224:227], v[68:71]
	s_setprio 0
	s_setprio 1
	v_mfma_f32_16x16x32_bf16 v[120:123], v[180:183], v[196:199], 0
	v_mfma_f32_16x16x32_bf16 v[112:115], v[188:191], v[196:199], 0
	v_mfma_f32_16x16x32_bf16 v[104:107], v[180:183], v[204:207], 0
	v_mfma_f32_16x16x32_bf16 v[96:99], v[188:191], v[204:207], 0
	v_mfma_f32_16x16x32_bf16 v[88:91], v[180:183], v[212:215], 0
	v_mfma_f32_16x16x32_bf16 v[80:83], v[188:191], v[212:215], 0
	v_mfma_f32_16x16x32_bf16 v[72:75], v[180:183], v[220:223], 0
	v_mfma_f32_16x16x32_bf16 v[64:67], v[188:191], v[220:223], 0
	v_mfma_f32_16x16x32_bf16 v[120:123], v[184:187], v[200:203], v[120:123]
	v_mfma_f32_16x16x32_bf16 v[112:115], v[192:195], v[200:203], v[112:115]
	v_mfma_f32_16x16x32_bf16 v[104:107], v[184:187], v[208:211], v[104:107]
	v_mfma_f32_16x16x32_bf16 v[96:99], v[192:195], v[208:211], v[96:99]
	v_mfma_f32_16x16x32_bf16 v[88:91], v[184:187], v[216:219], v[88:91]
	v_mfma_f32_16x16x32_bf16 v[80:83], v[192:195], v[216:219], v[80:83]
	v_mfma_f32_16x16x32_bf16 v[72:75], v[184:187], v[224:227], v[72:75]
	v_mfma_f32_16x16x32_bf16 v[64:67], v[192:195], v[224:227], v[64:67]
	s_setprio 0
	s_barrier
	s_mov_b32 m0, s17
	v_lshl_add_u64 v[228:229], s[52:53], 0, v[132:133]
	v_lshl_add_u64 v[230:231], s[52:53], 0, v[128:129]
	s_add_u32 s52, s52, s10
	ds_read_b128 v[196:199], v146 offset:16384
	ds_read_b128 v[200:203], v146 offset:17408
	ds_read_b128 v[204:207], v146 offset:18432
	ds_read_b128 v[208:211], v146 offset:19456
	ds_read_b128 v[212:215], v146 offset:20480
	ds_read_b128 v[216:219], v146 offset:21504
	ds_read_b128 v[220:223], v146 offset:22528
	ds_read_b128 v[224:227], v146 offset:23552
	global_load_lds_dwordx4 v[228:229], off
	s_mov_b32 m0, s18
	s_addc_u32 s53, s53, s11
	global_load_lds_dwordx4 v[230:231], off
	v_lshl_add_u64 v[232:233], s[52:53], 0, v[132:133]
	s_mov_b32 m0, s19
	v_lshl_add_u64 v[234:235], s[52:53], 0, v[128:129]
	global_load_lds_dwordx4 v[232:233], off
	s_mov_b32 m0, s20
	v_lshl_add_u64 v[236:237], s[94:95], 0, v[134:135]
	global_load_lds_dwordx4 v[234:235], off
	s_mov_b32 m0, s14
	v_lshl_add_u64 v[238:239], s[94:95], 0, v[130:131]
	global_load_lds_dwordx4 v[236:237], off
	s_mov_b32 m0, s21
	s_nop 0
	global_load_lds_dwordx4 v[238:239], off
	s_cmp_lg_u32 s99, 0
	s_cbranch_scc1 .Lsw_1_1
	s_waitcnt vmcnt(8)
.Lsw_1_1:
	s_waitcnt vmcnt(16)
	s_waitcnt lgkmcnt(0)
	s_barrier
	s_setprio 1
	s_waitcnt lgkmcnt(0)
	v_mfma_f32_16x16x32_bf16 v[60:63], v[164:167], v[196:199], 0
	v_mfma_f32_16x16x32_bf16 v[52:55], v[172:175], v[196:199], 0
	v_mfma_f32_16x16x32_bf16 v[44:47], v[164:167], v[204:207], 0
	v_mfma_f32_16x16x32_bf16 v[36:39], v[172:175], v[204:207], 0
	v_mfma_f32_16x16x32_bf16 v[28:31], v[164:167], v[212:215], 0
	v_mfma_f32_16x16x32_bf16 v[20:23], v[172:175], v[212:215], 0
	v_mfma_f32_16x16x32_bf16 v[12:15], v[164:167], v[220:223], 0
	v_mfma_f32_16x16x32_bf16 v[4:7], v[172:175], v[220:223], 0
	v_mfma_f32_16x16x32_bf16 v[60:63], v[168:171], v[200:203], v[60:63]
	v_mfma_f32_16x16x32_bf16 v[52:55], v[176:179], v[200:203], v[52:55]
	v_mfma_f32_16x16x32_bf16 v[44:47], v[168:171], v[208:211], v[44:47]
	v_mfma_f32_16x16x32_bf16 v[36:39], v[176:179], v[208:211], v[36:39]
	v_mfma_f32_16x16x32_bf16 v[28:31], v[168:171], v[216:219], v[28:31]
	v_mfma_f32_16x16x32_bf16 v[20:23], v[176:179], v[216:219], v[20:23]
	v_mfma_f32_16x16x32_bf16 v[12:15], v[168:171], v[224:227], v[12:15]
	v_mfma_f32_16x16x32_bf16 v[4:7], v[176:179], v[224:227], v[4:7]
	s_setprio 0
	s_setprio 1
	v_mfma_f32_16x16x32_bf16 v[56:59], v[180:183], v[196:199], 0
	v_mfma_f32_16x16x32_bf16 v[48:51], v[188:191], v[196:199], 0
	v_mfma_f32_16x16x32_bf16 v[40:43], v[180:183], v[204:207], 0
	v_mfma_f32_16x16x32_bf16 v[32:35], v[188:191], v[204:207], 0
	v_mfma_f32_16x16x32_bf16 v[24:27], v[180:183], v[212:215], 0
	v_mfma_f32_16x16x32_bf16 v[16:19], v[188:191], v[212:215], 0
	v_mfma_f32_16x16x32_bf16 v[8:11], v[180:183], v[220:223], 0
	v_mfma_f32_16x16x32_bf16 v[0:3], v[188:191], v[220:223], 0
	v_mfma_f32_16x16x32_bf16 v[56:59], v[184:187], v[200:203], v[56:59]
	v_mfma_f32_16x16x32_bf16 v[48:51], v[192:195], v[200:203], v[48:51]
	v_mfma_f32_16x16x32_bf16 v[40:43], v[184:187], v[208:211], v[40:43]
	v_mfma_f32_16x16x32_bf16 v[32:35], v[192:195], v[208:211], v[32:35]
	v_mfma_f32_16x16x32_bf16 v[24:27], v[184:187], v[216:219], v[24:27]
	v_mfma_f32_16x16x32_bf16 v[16:19], v[192:195], v[216:219], v[16:19]
	v_mfma_f32_16x16x32_bf16 v[8:11], v[184:187], v[224:227], v[8:11]
	v_mfma_f32_16x16x32_bf16 v[0:3], v[192:195], v[224:227], v[0:3]
	s_setprio 0
	s_barrier
	ds_read_b128 v[164:167], v155
	ds_read_b128 v[168:171], v156
	ds_read_b128 v[172:175], v157
	ds_read_b128 v[176:179], v158
	ds_read_b128 v[180:183], v159
	ds_read_b128 v[184:187], v160
	ds_read_b128 v[188:191], v161
	ds_read_b128 v[192:195], v163
	s_add_u32 s52, s94, s8
	s_addc_u32 s53, s95, s9
	s_mov_b32 m0, s22
	v_lshl_add_u64 v[240:241], s[52:53], 0, v[134:135]
	ds_read_b128 v[196:199], v146 offset:32768
	ds_read_b128 v[200:203], v146 offset:33792
	ds_read_b128 v[204:207], v146 offset:34816
	ds_read_b128 v[208:211], v146 offset:35840
	ds_read_b128 v[212:215], v146 offset:36864
	ds_read_b128 v[216:219], v146 offset:37888
	ds_read_b128 v[220:223], v146 offset:38912
	ds_read_b128 v[224:227], v146 offset:39936
	global_load_lds_dwordx4 v[240:241], off
	v_lshl_add_u64 v[240:241], s[52:53], 0, v[130:131]
	s_mov_b32 m0, s23
	s_nop 0
	global_load_lds_dwordx4 v[240:241], off
	s_waitcnt vmcnt(8)
	s_waitcnt lgkmcnt(0)
	s_barrier
	s_setprio 1
	s_waitcnt lgkmcnt(0)
	v_mfma_f32_16x16x32_bf16 v[124:127], v[164:167], v[196:199], v[124:127]
	v_mfma_f32_16x16x32_bf16 v[116:119], v[172:175], v[196:199], v[116:119]
	v_mfma_f32_16x16x32_bf16 v[108:111], v[164:167], v[204:207], v[108:111]
	v_mfma_f32_16x16x32_bf16 v[100:103], v[172:175], v[204:207], v[100:103]
	v_mfma_f32_16x16x32_bf16 v[92:95], v[164:167], v[212:215], v[92:95]
	v_mfma_f32_16x16x32_bf16 v[84:87], v[172:175], v[212:215], v[84:87]
	v_mfma_f32_16x16x32_bf16 v[76:79], v[164:167], v[220:223], v[76:79]
	v_mfma_f32_16x16x32_bf16 v[68:71], v[172:175], v[220:223], v[68:71]
	v_mfma_f32_16x16x32_bf16 v[124:127], v[168:171], v[200:203], v[124:127]
	v_mfma_f32_16x16x32_bf16 v[116:119], v[176:179], v[200:203], v[116:119]
	v_mfma_f32_16x16x32_bf16 v[108:111], v[168:171], v[208:211], v[108:111]
	v_mfma_f32_16x16x32_bf16 v[100:103], v[176:179], v[208:211], v[100:103]
	v_mfma_f32_16x16x32_bf16 v[92:95], v[168:171], v[216:219], v[92:95]
	v_mfma_f32_16x16x32_bf16 v[84:87], v[176:179], v[216:219], v[84:87]
	v_mfma_f32_16x16x32_bf16 v[76:79], v[168:171], v[224:227], v[76:79]
	v_mfma_f32_16x16x32_bf16 v[68:71], v[176:179], v[224:227], v[68:71]
	s_setprio 0
	s_setprio 1
	v_mfma_f32_16x16x32_bf16 v[120:123], v[180:183], v[196:199], v[120:123]
	v_mfma_f32_16x16x32_bf16 v[112:115], v[188:191], v[196:199], v[112:115]
	v_mfma_f32_16x16x32_bf16 v[104:107], v[180:183], v[204:207], v[104:107]
	v_mfma_f32_16x16x32_bf16 v[96:99], v[188:191], v[204:207], v[96:99]
	v_mfma_f32_16x16x32_bf16 v[88:91], v[180:183], v[212:215], v[88:91]
	v_mfma_f32_16x16x32_bf16 v[80:83], v[188:191], v[212:215], v[80:83]
	v_mfma_f32_16x16x32_bf16 v[72:75], v[180:183], v[220:223], v[72:75]
	v_mfma_f32_16x16x32_bf16 v[64:67], v[188:191], v[220:223], v[64:67]
	v_mfma_f32_16x16x32_bf16 v[120:123], v[184:187], v[200:203], v[120:123]
	v_mfma_f32_16x16x32_bf16 v[112:115], v[192:195], v[200:203], v[112:115]
	v_mfma_f32_16x16x32_bf16 v[104:107], v[184:187], v[208:211], v[104:107]
	v_mfma_f32_16x16x32_bf16 v[96:99], v[192:195], v[208:211], v[96:99]
	v_mfma_f32_16x16x32_bf16 v[88:91], v[184:187], v[216:219], v[88:91]
	v_mfma_f32_16x16x32_bf16 v[80:83], v[192:195], v[216:219], v[80:83]
	v_mfma_f32_16x16x32_bf16 v[72:75], v[184:187], v[224:227], v[72:75]
	v_mfma_f32_16x16x32_bf16 v[64:67], v[192:195], v[224:227], v[64:67]
	s_setprio 0
	s_barrier
	s_mov_b32 m0, s24
	v_lshl_add_u64 v[228:229], v[228:229], 0, s[76:77]
	ds_read_b128 v[196:199], v146 offset:49152
	ds_read_b128 v[200:203], v146 offset:50176
	ds_read_b128 v[204:207], v146 offset:51200
	ds_read_b128 v[208:211], v146 offset:52224
	ds_read_b128 v[212:215], v146 offset:53248
	ds_read_b128 v[216:219], v146 offset:54272
	ds_read_b128 v[220:223], v146 offset:55296
	ds_read_b128 v[224:227], v146 offset:56320
	global_load_lds_dwordx4 v[228:229], off
	v_lshl_add_u64 v[228:229], v[230:231], 0, s[76:77]
	s_mov_b32 m0, s25
	s_nop 0
	global_load_lds_dwordx4 v[228:229], off
	v_lshl_add_u64 v[228:229], v[232:233], 0, s[76:77]
	s_mov_b32 m0, s28
	s_nop 0
	global_load_lds_dwordx4 v[228:229], off
	v_lshl_add_u64 v[228:229], v[234:235], 0, s[76:77]
	s_mov_b32 m0, s29
	s_nop 0
	global_load_lds_dwordx4 v[228:229], off
	v_lshl_add_u64 v[228:229], v[236:237], 0, s[76:77]
	s_mov_b32 m0, s26
	s_nop 0
	global_load_lds_dwordx4 v[228:229], off
	v_lshl_add_u64 v[228:229], v[238:239], 0, s[76:77]
	s_mov_b32 m0, s27
	s_nop 0
	global_load_lds_dwordx4 v[228:229], off
	s_waitcnt vmcnt(8)
	s_waitcnt lgkmcnt(0)
	s_barrier
	s_setprio 1
	s_waitcnt lgkmcnt(0)
	v_mfma_f32_16x16x32_bf16 v[60:63], v[164:167], v[196:199], v[60:63]
	v_mfma_f32_16x16x32_bf16 v[52:55], v[172:175], v[196:199], v[52:55]
	v_mfma_f32_16x16x32_bf16 v[44:47], v[164:167], v[204:207], v[44:47]
	v_mfma_f32_16x16x32_bf16 v[36:39], v[172:175], v[204:207], v[36:39]
	v_mfma_f32_16x16x32_bf16 v[28:31], v[164:167], v[212:215], v[28:31]
	v_mfma_f32_16x16x32_bf16 v[20:23], v[172:175], v[212:215], v[20:23]
	v_mfma_f32_16x16x32_bf16 v[12:15], v[164:167], v[220:223], v[12:15]
	v_mfma_f32_16x16x32_bf16 v[4:7], v[172:175], v[220:223], v[4:7]
	v_mfma_f32_16x16x32_bf16 v[60:63], v[168:171], v[200:203], v[60:63]
	v_mfma_f32_16x16x32_bf16 v[52:55], v[176:179], v[200:203], v[52:55]
	v_mfma_f32_16x16x32_bf16 v[44:47], v[168:171], v[208:211], v[44:47]
	v_mfma_f32_16x16x32_bf16 v[36:39], v[176:179], v[208:211], v[36:39]
	v_mfma_f32_16x16x32_bf16 v[28:31], v[168:171], v[216:219], v[28:31]
	v_mfma_f32_16x16x32_bf16 v[20:23], v[176:179], v[216:219], v[20:23]
	v_mfma_f32_16x16x32_bf16 v[12:15], v[168:171], v[224:227], v[12:15]
	v_mfma_f32_16x16x32_bf16 v[4:7], v[176:179], v[224:227], v[4:7]
	s_setprio 0
	s_setprio 1
	v_mfma_f32_16x16x32_bf16 v[56:59], v[180:183], v[196:199], v[56:59]
	v_mfma_f32_16x16x32_bf16 v[48:51], v[188:191], v[196:199], v[48:51]
	v_mfma_f32_16x16x32_bf16 v[40:43], v[180:183], v[204:207], v[40:43]
	v_mfma_f32_16x16x32_bf16 v[32:35], v[188:191], v[204:207], v[32:35]
	v_mfma_f32_16x16x32_bf16 v[24:27], v[180:183], v[212:215], v[24:27]
	v_mfma_f32_16x16x32_bf16 v[16:19], v[188:191], v[212:215], v[16:19]
	v_mfma_f32_16x16x32_bf16 v[8:11], v[180:183], v[220:223], v[8:11]
	v_mfma_f32_16x16x32_bf16 v[0:3], v[188:191], v[220:223], v[0:3]
	v_mfma_f32_16x16x32_bf16 v[56:59], v[184:187], v[200:203], v[56:59]
	v_mfma_f32_16x16x32_bf16 v[48:51], v[192:195], v[200:203], v[48:51]
	v_mfma_f32_16x16x32_bf16 v[40:43], v[184:187], v[208:211], v[40:43]
	v_mfma_f32_16x16x32_bf16 v[32:35], v[192:195], v[208:211], v[32:35]
	v_mfma_f32_16x16x32_bf16 v[24:27], v[184:187], v[216:219], v[24:27]
	v_mfma_f32_16x16x32_bf16 v[16:19], v[192:195], v[216:219], v[16:19]
	v_mfma_f32_16x16x32_bf16 v[8:11], v[184:187], v[224:227], v[8:11]
	v_mfma_f32_16x16x32_bf16 v[0:3], v[192:195], v[224:227], v[0:3]
	s_setprio 0
	s_barrier
	s_add_u32 s92, s92, 0x100
	s_addc_u32 s93, s93, 0
	s_add_u32 s91, s91, 0x100
	s_addc_u32 vcc_lo, vcc_lo, 0
	s_cmp_ge_i32 vcc_hi, s30
	s_mov_b32 s94, vcc_hi
	s_cbranch_scc1 .Lkx_1

.Lkx_1:
	s_mov_b32 s99, 1

.LBB0_822:
	s_add_i32 s33, s18, 0x18000
	s_mov_b64 s[26:27], 0x80
	v_lshl_add_u64 v[10:11], v[10:11], 0, s[26:27]
	s_mov_b32 m0, s33
	s_add_i32 s34, s18, 0x1a000
	s_waitcnt vmcnt(2)
	s_mov_b32 s99, 0
	s_barrier
	global_load_lds_dwordx4 v[10:11], off
	v_lshl_add_u64 v[4:5], v[4:5], 0, s[26:27]
	s_mov_b32 m0, s34
	s_add_i32 s35, s18, 0x8000
	global_load_lds_dwordx4 v[4:5], off
	v_lshl_add_u64 v[4:5], v[6:7], 0, s[26:27]
	s_mov_b32 m0, s35
	s_add_i32 s68, s18, 0xa000
	global_load_lds_dwordx4 v[4:5], off
	v_lshl_add_u64 v[4:5], v[8:9], 0, s[26:27]
	s_mov_b32 m0, s68
	s_add_i32 s69, s18, 0x1c000
	global_load_lds_dwordx4 v[4:5], off
	v_lshl_add_u64 v[2:3], v[2:3], 0, s[26:27]
	s_mov_b32 m0, s69
	s_add_i32 s72, s18, 0x1e000
	global_load_lds_dwordx4 v[2:3], off
	v_lshl_add_u64 v[0:1], v[0:1], 0, s[26:27]
	s_mov_b32 m0, s72
	s_ashr_i32 s0, s36, 31
	global_load_lds_dwordx4 v[0:1], off
	v_bfe_u32 v147, v12, 4, 2
	s_lshr_b32 s0, s0, 26
	v_and_b32_e32 v146, 15, v12
	s_add_i32 s0, s36, s0
	v_lshlrev_b32_e32 v0, 4, v147
	v_lshlrev_b32_e32 v1, 2, v12
	s_ashr_i32 s73, s0, 6
	v_lshl_or_b32 v0, v146, 6, v0
	s_lshl_b32 s0, s6, 13
	v_and_b32_e32 v1, 32, v1
	v_bitop3_b32 v148, v0, s0, v1 bitop3:0xde
	s_lshl_b32 s0, s7, 5
	s_lshl_b32 s78, s6, 6
	s_and_b32 s6, s0, 0x60
	s_lshl_b32 s0, s6, 7
	v_bitop3_b32 v2, v0, s0, v1 bitop3:0xde
	v_add_u32_e32 v0, v15, v13
	v_add_lshl_u32 v0, v0, v14, 1
	v_mov_b32_e32 v1, v131
	s_cmp_gt_i32 s36, 63
	v_lshl_add_u64 v[136:137], s[10:11], 0, v[0:1]
	v_add_u32_e32 v0, v18, v16
	s_cselect_b64 s[0:1], -1, 0
	s_add_i32 s79, s73, -2
	v_readlane_b32 s4, v246, 5
	v_add_lshl_u32 v0, v0, v17, 1
	s_waitcnt vmcnt(6)
	s_cmpk_lt_u32 s3, 0x100
	v_readlane_b32 s5, v246, 6
	v_lshl_add_u64 v[138:139], s[10:11], 0, v[0:1]
	v_cndmask_b32_e64 v0, 0, 1, s[0:1]
	s_cselect_b64 s[36:37], -1, 0
	s_mov_b32 s47, 0
	s_ashr_i32 s81, s4, 31
	s_mov_b32 s82, s4
	v_cmp_ne_u32_e64 s[4:5], 1, v0
	v_mbcnt_lo_u32_b32 v0, -1, 0
	s_ashr_i32 s80, s78, 31
	s_ashr_i32 s83, s2, 31
	v_mov_b64_e32 v[140:141], 0x200
	v_mov_b64_e32 v[142:143], 0x1ff
	v_or_b32_e32 v149, 0x10000, v2
	v_add_u32_e32 v150, 0x10400, v2
	v_add_u32_e32 v151, 0x10800, v2
	v_add_u32_e32 v152, 0x10c00, v2
	v_or_b32_e32 v153, 0x14000, v2
	v_add_u32_e32 v154, 0x14400, v2
	v_add_u32_e32 v155, 0x14800, v2
	v_add_u32_e32 v156, 0x14c00, v2
	s_add_i32 s90, s18, 0xc000
	s_add_i32 s91, s18, 0xe000
	v_or_b32_e32 v157, 0x18000, v2
	v_add_u32_e32 v158, 0x18400, v2
	v_add_u32_e32 v159, 0x18800, v2
	v_add_u32_e32 v160, 0x18c00, v2
	v_or_b32_e32 v161, 0x1c000, v2
	v_add_u32_e32 v163, 0x1c400, v2
	v_add_u32_e32 v164, 0x1c800, v2
	v_add_u32_e32 v165, 0x1cc00, v2
	v_mbcnt_hi_u32_b32 v166, -1, v0
	s_lshl_b32 s46, s6, 1
	s_mov_b32 s92, s47
	s_barrier
	s_branch .LBB0_825

.LBB0_835:
	s_and_b64 vcc, exec, s[4:5]
	s_waitcnt lgkmcnt(0)
	s_cbranch_vccnz .Lkz_2
	s_branch .Lkp_2
.Lkz_2:
	v_mov_b32_e32 v127, 0
	v_mov_b32_e32 v126, v127
	v_mov_b32_e32 v125, v127
	v_mov_b32_e32 v124, v127
	v_mov_b32_e32 v123, v127
	v_mov_b32_e32 v122, v127
	v_mov_b32_e32 v121, v127
	v_mov_b32_e32 v120, v127
	v_mov_b32_e32 v111, v127
	v_mov_b32_e32 v110, v127
	v_mov_b32_e32 v109, v127
	v_mov_b32_e32 v108, v127
	v_mov_b32_e32 v107, v127
	v_mov_b32_e32 v106, v127
	v_mov_b32_e32 v105, v127
	v_mov_b32_e32 v104, v127
	v_mov_b32_e32 v95, v127
	v_mov_b32_e32 v94, v127
	v_mov_b32_e32 v93, v127
	v_mov_b32_e32 v92, v127
	v_mov_b32_e32 v91, v127
	v_mov_b32_e32 v90, v127
	v_mov_b32_e32 v89, v127
	v_mov_b32_e32 v88, v127
	v_mov_b32_e32 v79, v127
	v_mov_b32_e32 v78, v127
	v_mov_b32_e32 v77, v127
	v_mov_b32_e32 v76, v127
	v_mov_b32_e32 v75, v127
	v_mov_b32_e32 v74, v127
	v_mov_b32_e32 v73, v127
	v_mov_b32_e32 v72, v127
	v_mov_b32_e32 v119, v127
	v_mov_b32_e32 v118, v127
	v_mov_b32_e32 v117, v127
	v_mov_b32_e32 v116, v127
	v_mov_b32_e32 v115, v127
	v_mov_b32_e32 v114, v127
	v_mov_b32_e32 v113, v127
	v_mov_b32_e32 v112, v127
	v_mov_b32_e32 v103, v127
	v_mov_b32_e32 v102, v127
	v_mov_b32_e32 v101, v127
	v_mov_b32_e32 v100, v127
	v_mov_b32_e32 v99, v127
	v_mov_b32_e32 v98, v127
	v_mov_b32_e32 v97, v127
	v_mov_b32_e32 v96, v127
	v_mov_b32_e32 v87, v127
	v_mov_b32_e32 v86, v127
	v_mov_b32_e32 v85, v127
	v_mov_b32_e32 v84, v127
	v_mov_b32_e32 v83, v127
	v_mov_b32_e32 v82, v127
	v_mov_b32_e32 v81, v127
	v_mov_b32_e32 v80, v127
	v_mov_b32_e32 v71, v127
	v_mov_b32_e32 v70, v127
	v_mov_b32_e32 v69, v127
	v_mov_b32_e32 v68, v127
	v_mov_b32_e32 v67, v127
	v_mov_b32_e32 v66, v127
	v_mov_b32_e32 v65, v127
	v_mov_b32_e32 v64, v127
	v_mov_b32_e32 v63, v127
	v_mov_b32_e32 v62, v127
	v_mov_b32_e32 v61, v127
	v_mov_b32_e32 v60, v127
	v_mov_b32_e32 v59, v127
	v_mov_b32_e32 v58, v127
	v_mov_b32_e32 v57, v127
	v_mov_b32_e32 v56, v127
	v_mov_b32_e32 v47, v127
	v_mov_b32_e32 v46, v127
	v_mov_b32_e32 v45, v127
	v_mov_b32_e32 v44, v127
	v_mov_b32_e32 v43, v127
	v_mov_b32_e32 v42, v127
	v_mov_b32_e32 v41, v127
	v_mov_b32_e32 v40, v127
	v_mov_b32_e32 v31, v127
	v_mov_b32_e32 v30, v127
	v_mov_b32_e32 v29, v127
	v_mov_b32_e32 v28, v127
	v_mov_b32_e32 v27, v127
	v_mov_b32_e32 v26, v127
	v_mov_b32_e32 v25, v127
	v_mov_b32_e32 v24, v127
	v_mov_b32_e32 v15, v127
	v_mov_b32_e32 v14, v127
	v_mov_b32_e32 v13, v127
	v_mov_b32_e32 v12, v127
	v_mov_b32_e32 v11, v127
	v_mov_b32_e32 v10, v127
	v_mov_b32_e32 v9, v127
	v_mov_b32_e32 v8, v127
	v_mov_b32_e32 v55, v127
	v_mov_b32_e32 v54, v127
	v_mov_b32_e32 v53, v127
	v_mov_b32_e32 v52, v127
	v_mov_b32_e32 v51, v127
	v_mov_b32_e32 v50, v127
	v_mov_b32_e32 v49, v127
	v_mov_b32_e32 v48, v127
	v_mov_b32_e32 v39, v127
	v_mov_b32_e32 v38, v127
	v_mov_b32_e32 v37, v127
	v_mov_b32_e32 v36, v127
	v_mov_b32_e32 v35, v127
	v_mov_b32_e32 v34, v127
	v_mov_b32_e32 v33, v127
	v_mov_b32_e32 v32, v127
	v_mov_b32_e32 v23, v127
	v_mov_b32_e32 v22, v127
	v_mov_b32_e32 v21, v127
	v_mov_b32_e32 v20, v127
	v_mov_b32_e32 v19, v127
	v_mov_b32_e32 v18, v127
	v_mov_b32_e32 v17, v127
	v_mov_b32_e32 v16, v127
	v_mov_b32_e32 v7, v127
	v_mov_b32_e32 v6, v127
	v_mov_b32_e32 v5, v127
	v_mov_b32_e32 v4, v127
	v_mov_b32_e32 v3, v127
	v_mov_b32_e32 v2, v127
	v_mov_b32_e32 v1, v127
	v_mov_b32_e32 v0, v127
	s_branch .LBB0_838
.Lkp_2:
	s_add_u32 s74, s74, 0x80
	s_addc_u32 s75, s75, 0
	s_add_u32 s3, s76, 0x100
	s_addc_u32 s9, s77, 0
	s_mov_b32 s76, 0
	ds_read_b128 v[168:171], v149
	ds_read_b128 v[172:175], v150
	ds_read_b128 v[176:179], v151
	ds_read_b128 v[180:183], v152
	ds_read_b128 v[184:187], v153
	ds_read_b128 v[188:191], v154
	ds_read_b128 v[192:195], v155
	ds_read_b128 v[196:199], v156
	s_add_i32 s96, s76, 2
	s_add_u32 s52, s74, 0x80
	s_addc_u32 s53, s75, 0
	s_cmp_eq_u32 s79, s76
	s_cselect_b32 s76, s0, s52
	s_cselect_b32 s77, s1, s53
	s_cselect_b32 s53, s71, s9
	s_cselect_b32 s52, s70, s3
	s_mov_b32 m0, s90
	v_lshl_add_u64 v[144:145], s[74:75], 0, v[136:137]
	ds_read_b128 v[200:203], v148
	ds_read_b128 v[204:207], v148 offset:1024
	ds_read_b128 v[208:211], v148 offset:2048
	ds_read_b128 v[212:215], v148 offset:3072
	ds_read_b128 v[216:219], v148 offset:4096
	ds_read_b128 v[220:223], v148 offset:5120
	ds_read_b128 v[224:227], v148 offset:6144
	ds_read_b128 v[228:231], v148 offset:7168
	global_load_lds_dwordx4 v[144:145], off
	v_lshl_add_u64 v[144:145], s[74:75], 0, v[138:139]
	s_mov_b32 m0, s91
	s_nop 0
	global_load_lds_dwordx4 v[144:145], off
	s_cmp_lg_u32 s99, 0
	s_cbranch_scc1 .Lsw_2_0
	s_waitcnt vmcnt(8)
.Lsw_2_0:
	s_waitcnt vmcnt(24)
	s_waitcnt lgkmcnt(0)
	s_barrier
	s_setprio 1
	s_waitcnt lgkmcnt(0)
	v_mfma_f32_16x16x32_bf16 v[124:127], v[168:171], v[200:203], 0
	v_mfma_f32_16x16x32_bf16 v[120:123], v[176:179], v[200:203], 0
	v_mfma_f32_16x16x32_bf16 v[108:111], v[168:171], v[208:211], 0
	v_mfma_f32_16x16x32_bf16 v[104:107], v[176:179], v[208:211], 0
	v_mfma_f32_16x16x32_bf16 v[92:95], v[168:171], v[216:219], 0
	v_mfma_f32_16x16x32_bf16 v[88:91], v[176:179], v[216:219], 0
	v_mfma_f32_16x16x32_bf16 v[76:79], v[168:171], v[224:227], 0
	v_mfma_f32_16x16x32_bf16 v[72:75], v[176:179], v[224:227], 0
	v_mfma_f32_16x16x32_bf16 v[124:127], v[172:175], v[204:207], v[124:127]
	v_mfma_f32_16x16x32_bf16 v[120:123], v[180:183], v[204:207], v[120:123]
	v_mfma_f32_16x16x32_bf16 v[108:111], v[172:175], v[212:215], v[108:111]
	v_mfma_f32_16x16x32_bf16 v[104:107], v[180:183], v[212:215], v[104:107]
	v_mfma_f32_16x16x32_bf16 v[92:95], v[172:175], v[220:223], v[92:95]
	v_mfma_f32_16x16x32_bf16 v[88:91], v[180:183], v[220:223], v[88:91]
	v_mfma_f32_16x16x32_bf16 v[76:79], v[172:175], v[228:231], v[76:79]
	v_mfma_f32_16x16x32_bf16 v[72:75], v[180:183], v[228:231], v[72:75]
	s_setprio 0
	s_setprio 1
	v_mfma_f32_16x16x32_bf16 v[116:119], v[184:187], v[200:203], 0
	v_mfma_f32_16x16x32_bf16 v[112:115], v[192:195], v[200:203], 0
	v_mfma_f32_16x16x32_bf16 v[100:103], v[184:187], v[208:211], 0
	v_mfma_f32_16x16x32_bf16 v[96:99], v[192:195], v[208:211], 0
	v_mfma_f32_16x16x32_bf16 v[84:87], v[184:187], v[216:219], 0
	v_mfma_f32_16x16x32_bf16 v[80:83], v[192:195], v[216:219], 0
	v_mfma_f32_16x16x32_bf16 v[68:71], v[184:187], v[224:227], 0
	v_mfma_f32_16x16x32_bf16 v[64:67], v[192:195], v[224:227], 0
	v_mfma_f32_16x16x32_bf16 v[116:119], v[188:191], v[204:207], v[116:119]
	v_mfma_f32_16x16x32_bf16 v[112:115], v[196:199], v[204:207], v[112:115]
	v_mfma_f32_16x16x32_bf16 v[100:103], v[188:191], v[212:215], v[100:103]
	v_mfma_f32_16x16x32_bf16 v[96:99], v[196:199], v[212:215], v[96:99]
	v_mfma_f32_16x16x32_bf16 v[84:87], v[188:191], v[220:223], v[84:87]
	v_mfma_f32_16x16x32_bf16 v[80:83], v[196:199], v[220:223], v[80:83]
	v_mfma_f32_16x16x32_bf16 v[68:71], v[188:191], v[228:231], v[68:71]
	v_mfma_f32_16x16x32_bf16 v[64:67], v[196:199], v[228:231], v[64:67]
	s_setprio 0
	s_barrier
	s_mov_b32 m0, s19
	v_lshl_add_u64 v[144:145], s[52:53], 0, v[130:131]
	v_lshl_add_u64 v[232:233], s[52:53], 0, v[134:135]
	s_add_u32 s52, s52, s12
	ds_read_b128 v[200:203], v148 offset:16384
	ds_read_b128 v[204:207], v148 offset:17408
	ds_read_b128 v[208:211], v148 offset:18432
	ds_read_b128 v[212:215], v148 offset:19456
	ds_read_b128 v[216:219], v148 offset:20480
	ds_read_b128 v[220:223], v148 offset:21504
	ds_read_b128 v[224:227], v148 offset:22528
	ds_read_b128 v[228:231], v148 offset:23552
	global_load_lds_dwordx4 v[144:145], off
	s_mov_b32 m0, s20
	s_addc_u32 s53, s53, s13
	global_load_lds_dwordx4 v[232:233], off
	v_lshl_add_u64 v[234:235], s[52:53], 0, v[130:131]
	s_mov_b32 m0, s21
	v_lshl_add_u64 v[236:237], s[52:53], 0, v[134:135]
	global_load_lds_dwordx4 v[234:235], off
	s_mov_b32 m0, s28
	v_lshl_add_u64 v[238:239], s[76:77], 0, v[128:129]
	global_load_lds_dwordx4 v[236:237], off
	s_mov_b32 m0, s18
	v_lshl_add_u64 v[240:241], s[76:77], 0, v[132:133]
	global_load_lds_dwordx4 v[238:239], off
	s_mov_b32 m0, s29
	s_nop 0
	global_load_lds_dwordx4 v[240:241], off
	s_cmp_lg_u32 s99, 0
	s_cbranch_scc1 .Lsw_2_1
	s_waitcnt vmcnt(8)
.Lsw_2_1:
	s_waitcnt vmcnt(24)
	s_waitcnt lgkmcnt(0)
	s_barrier
	s_setprio 1
	s_waitcnt lgkmcnt(0)
	v_mfma_f32_16x16x32_bf16 v[60:63], v[168:171], v[200:203], 0
	v_mfma_f32_16x16x32_bf16 v[56:59], v[176:179], v[200:203], 0
	v_mfma_f32_16x16x32_bf16 v[44:47], v[168:171], v[208:211], 0
	v_mfma_f32_16x16x32_bf16 v[40:43], v[176:179], v[208:211], 0
	v_mfma_f32_16x16x32_bf16 v[28:31], v[168:171], v[216:219], 0
	v_mfma_f32_16x16x32_bf16 v[24:27], v[176:179], v[216:219], 0
	v_mfma_f32_16x16x32_bf16 v[12:15], v[168:171], v[224:227], 0
	v_mfma_f32_16x16x32_bf16 v[8:11], v[176:179], v[224:227], 0
	v_mfma_f32_16x16x32_bf16 v[60:63], v[172:175], v[204:207], v[60:63]
	v_mfma_f32_16x16x32_bf16 v[56:59], v[180:183], v[204:207], v[56:59]
	v_mfma_f32_16x16x32_bf16 v[44:47], v[172:175], v[212:215], v[44:47]
	v_mfma_f32_16x16x32_bf16 v[40:43], v[180:183], v[212:215], v[40:43]
	v_mfma_f32_16x16x32_bf16 v[28:31], v[172:175], v[220:223], v[28:31]
	v_mfma_f32_16x16x32_bf16 v[24:27], v[180:183], v[220:223], v[24:27]
	v_mfma_f32_16x16x32_bf16 v[12:15], v[172:175], v[228:231], v[12:15]
	v_mfma_f32_16x16x32_bf16 v[8:11], v[180:183], v[228:231], v[8:11]
	s_setprio 0
	s_setprio 1
	v_mfma_f32_16x16x32_bf16 v[52:55], v[184:187], v[200:203], 0
	v_mfma_f32_16x16x32_bf16 v[48:51], v[192:195], v[200:203], 0
	v_mfma_f32_16x16x32_bf16 v[36:39], v[184:187], v[208:211], 0
	v_mfma_f32_16x16x32_bf16 v[32:35], v[192:195], v[208:211], 0
	v_mfma_f32_16x16x32_bf16 v[20:23], v[184:187], v[216:219], 0
	v_mfma_f32_16x16x32_bf16 v[16:19], v[192:195], v[216:219], 0
	v_mfma_f32_16x16x32_bf16 v[4:7], v[184:187], v[224:227], 0
	v_mfma_f32_16x16x32_bf16 v[0:3], v[192:195], v[224:227], 0
	v_mfma_f32_16x16x32_bf16 v[52:55], v[188:191], v[204:207], v[52:55]
	v_mfma_f32_16x16x32_bf16 v[48:51], v[196:199], v[204:207], v[48:51]
	v_mfma_f32_16x16x32_bf16 v[36:39], v[188:191], v[212:215], v[36:39]
	v_mfma_f32_16x16x32_bf16 v[32:35], v[196:199], v[212:215], v[32:35]
	v_mfma_f32_16x16x32_bf16 v[20:23], v[188:191], v[220:223], v[20:23]
	v_mfma_f32_16x16x32_bf16 v[16:19], v[196:199], v[220:223], v[16:19]
	v_mfma_f32_16x16x32_bf16 v[4:7], v[188:191], v[228:231], v[4:7]
	v_mfma_f32_16x16x32_bf16 v[0:3], v[196:199], v[228:231], v[0:3]
	s_setprio 0
	s_barrier
	ds_read_b128 v[168:171], v157
	ds_read_b128 v[172:175], v158
	ds_read_b128 v[176:179], v159
	ds_read_b128 v[180:183], v160
	ds_read_b128 v[184:187], v161
	ds_read_b128 v[188:191], v163
	ds_read_b128 v[192:195], v164
	ds_read_b128 v[196:199], v165
	s_add_u32 s52, s76, s10
	s_addc_u32 s53, s77, s11
	s_mov_b32 m0, s30
	v_lshl_add_u64 v[242:243], s[52:53], 0, v[128:129]
	ds_read_b128 v[200:203], v148 offset:32768
	ds_read_b128 v[204:207], v148 offset:33792
	ds_read_b128 v[208:211], v148 offset:34816
	ds_read_b128 v[212:215], v148 offset:35840
	ds_read_b128 v[216:219], v148 offset:36864
	ds_read_b128 v[220:223], v148 offset:37888
	ds_read_b128 v[224:227], v148 offset:38912
	ds_read_b128 v[228:231], v148 offset:39936
	global_load_lds_dwordx4 v[242:243], off
	v_lshl_add_u64 v[242:243], s[52:53], 0, v[132:133]
	s_mov_b32 m0, s31
	s_nop 0
	global_load_lds_dwordx4 v[242:243], off
	s_waitcnt vmcnt(8)
	s_waitcnt lgkmcnt(0)
	s_barrier
	s_setprio 1
	s_waitcnt lgkmcnt(0)
	v_mfma_f32_16x16x32_bf16 v[124:127], v[168:171], v[200:203], v[124:127]
	v_mfma_f32_16x16x32_bf16 v[120:123], v[176:179], v[200:203], v[120:123]
	v_mfma_f32_16x16x32_bf16 v[108:111], v[168:171], v[208:211], v[108:111]
	v_mfma_f32_16x16x32_bf16 v[104:107], v[176:179], v[208:211], v[104:107]
	v_mfma_f32_16x16x32_bf16 v[92:95], v[168:171], v[216:219], v[92:95]
	v_mfma_f32_16x16x32_bf16 v[88:91], v[176:179], v[216:219], v[88:91]
	v_mfma_f32_16x16x32_bf16 v[76:79], v[168:171], v[224:227], v[76:79]
	v_mfma_f32_16x16x32_bf16 v[72:75], v[176:179], v[224:227], v[72:75]
	v_mfma_f32_16x16x32_bf16 v[124:127], v[172:175], v[204:207], v[124:127]
	v_mfma_f32_16x16x32_bf16 v[120:123], v[180:183], v[204:207], v[120:123]
	v_mfma_f32_16x16x32_bf16 v[108:111], v[172:175], v[212:215], v[108:111]
	v_mfma_f32_16x16x32_bf16 v[104:107], v[180:183], v[212:215], v[104:107]
	v_mfma_f32_16x16x32_bf16 v[92:95], v[172:175], v[220:223], v[92:95]
	v_mfma_f32_16x16x32_bf16 v[88:91], v[180:183], v[220:223], v[88:91]
	v_mfma_f32_16x16x32_bf16 v[76:79], v[172:175], v[228:231], v[76:79]
	v_mfma_f32_16x16x32_bf16 v[72:75], v[180:183], v[228:231], v[72:75]
	s_setprio 0
	s_setprio 1
	v_mfma_f32_16x16x32_bf16 v[116:119], v[184:187], v[200:203], v[116:119]
	v_mfma_f32_16x16x32_bf16 v[112:115], v[192:195], v[200:203], v[112:115]
	v_mfma_f32_16x16x32_bf16 v[100:103], v[184:187], v[208:211], v[100:103]
	v_mfma_f32_16x16x32_bf16 v[96:99], v[192:195], v[208:211], v[96:99]
	v_mfma_f32_16x16x32_bf16 v[84:87], v[184:187], v[216:219], v[84:87]
	v_mfma_f32_16x16x32_bf16 v[80:83], v[192:195], v[216:219], v[80:83]
	v_mfma_f32_16x16x32_bf16 v[68:71], v[184:187], v[224:227], v[68:71]
	v_mfma_f32_16x16x32_bf16 v[64:67], v[192:195], v[224:227], v[64:67]
	v_mfma_f32_16x16x32_bf16 v[116:119], v[188:191], v[204:207], v[116:119]
	v_mfma_f32_16x16x32_bf16 v[112:115], v[196:199], v[204:207], v[112:115]
	v_mfma_f32_16x16x32_bf16 v[100:103], v[188:191], v[212:215], v[100:103]
	v_mfma_f32_16x16x32_bf16 v[96:99], v[196:199], v[212:215], v[96:99]
	v_mfma_f32_16x16x32_bf16 v[84:87], v[188:191], v[220:223], v[84:87]
	v_mfma_f32_16x16x32_bf16 v[80:83], v[196:199], v[220:223], v[80:83]
	v_mfma_f32_16x16x32_bf16 v[68:71], v[188:191], v[228:231], v[68:71]
	v_mfma_f32_16x16x32_bf16 v[64:67], v[196:199], v[228:231], v[64:67]
	s_setprio 0
	s_barrier
	s_mov_b32 m0, s33
	v_lshl_add_u64 v[144:145], v[144:145], 0, s[26:27]
	ds_read_b128 v[200:203], v148 offset:49152
	ds_read_b128 v[204:207], v148 offset:50176
	ds_read_b128 v[208:211], v148 offset:51200
	ds_read_b128 v[212:215], v148 offset:52224
	ds_read_b128 v[216:219], v148 offset:53248
	ds_read_b128 v[220:223], v148 offset:54272
	ds_read_b128 v[224:227], v148 offset:55296
	ds_read_b128 v[228:231], v148 offset:56320
	global_load_lds_dwordx4 v[144:145], off
	v_lshl_add_u64 v[144:145], v[232:233], 0, s[26:27]
	s_mov_b32 m0, s34
	s_nop 0
	global_load_lds_dwordx4 v[144:145], off
	v_lshl_add_u64 v[144:145], v[234:235], 0, s[26:27]
	s_mov_b32 m0, s69
	s_nop 0
	global_load_lds_dwordx4 v[144:145], off
	v_lshl_add_u64 v[144:145], v[236:237], 0, s[26:27]
	s_mov_b32 m0, s72
	s_nop 0
	global_load_lds_dwordx4 v[144:145], off
	v_lshl_add_u64 v[144:145], v[238:239], 0, s[26:27]
	s_mov_b32 m0, s35
	s_nop 0
	global_load_lds_dwordx4 v[144:145], off
	v_lshl_add_u64 v[144:145], v[240:241], 0, s[26:27]
	s_mov_b32 m0, s68
	s_nop 0
	global_load_lds_dwordx4 v[144:145], off
	s_waitcnt vmcnt(8)
	s_waitcnt lgkmcnt(0)
	s_barrier
	s_setprio 1
	s_waitcnt lgkmcnt(0)
	v_mfma_f32_16x16x32_bf16 v[60:63], v[168:171], v[200:203], v[60:63]
	v_mfma_f32_16x16x32_bf16 v[56:59], v[176:179], v[200:203], v[56:59]
	v_mfma_f32_16x16x32_bf16 v[44:47], v[168:171], v[208:211], v[44:47]
	v_mfma_f32_16x16x32_bf16 v[40:43], v[176:179], v[208:211], v[40:43]
	v_mfma_f32_16x16x32_bf16 v[28:31], v[168:171], v[216:219], v[28:31]
	v_mfma_f32_16x16x32_bf16 v[24:27], v[176:179], v[216:219], v[24:27]
	v_mfma_f32_16x16x32_bf16 v[12:15], v[168:171], v[224:227], v[12:15]
	v_mfma_f32_16x16x32_bf16 v[8:11], v[176:179], v[224:227], v[8:11]
	v_mfma_f32_16x16x32_bf16 v[60:63], v[172:175], v[204:207], v[60:63]
	v_mfma_f32_16x16x32_bf16 v[56:59], v[180:183], v[204:207], v[56:59]
	v_mfma_f32_16x16x32_bf16 v[44:47], v[172:175], v[212:215], v[44:47]
	v_mfma_f32_16x16x32_bf16 v[40:43], v[180:183], v[212:215], v[40:43]
	v_mfma_f32_16x16x32_bf16 v[28:31], v[172:175], v[220:223], v[28:31]
	v_mfma_f32_16x16x32_bf16 v[24:27], v[180:183], v[220:223], v[24:27]
	v_mfma_f32_16x16x32_bf16 v[12:15], v[172:175], v[228:231], v[12:15]
	v_mfma_f32_16x16x32_bf16 v[8:11], v[180:183], v[228:231], v[8:11]
	s_setprio 0
	s_setprio 1
	v_mfma_f32_16x16x32_bf16 v[52:55], v[184:187], v[200:203], v[52:55]
	v_mfma_f32_16x16x32_bf16 v[48:51], v[192:195], v[200:203], v[48:51]
	v_mfma_f32_16x16x32_bf16 v[36:39], v[184:187], v[208:211], v[36:39]
	v_mfma_f32_16x16x32_bf16 v[32:35], v[192:195], v[208:211], v[32:35]
	v_mfma_f32_16x16x32_bf16 v[20:23], v[184:187], v[216:219], v[20:23]
	v_mfma_f32_16x16x32_bf16 v[16:19], v[192:195], v[216:219], v[16:19]
	v_mfma_f32_16x16x32_bf16 v[4:7], v[184:187], v[224:227], v[4:7]
	v_mfma_f32_16x16x32_bf16 v[0:3], v[192:195], v[224:227], v[0:3]
	v_mfma_f32_16x16x32_bf16 v[52:55], v[188:191], v[204:207], v[52:55]
	v_mfma_f32_16x16x32_bf16 v[48:51], v[196:199], v[204:207], v[48:51]
	v_mfma_f32_16x16x32_bf16 v[36:39], v[188:191], v[212:215], v[36:39]
	v_mfma_f32_16x16x32_bf16 v[32:35], v[196:199], v[212:215], v[32:35]
	v_mfma_f32_16x16x32_bf16 v[20:23], v[188:191], v[220:223], v[20:23]
	v_mfma_f32_16x16x32_bf16 v[16:19], v[196:199], v[220:223], v[16:19]
	v_mfma_f32_16x16x32_bf16 v[4:7], v[188:191], v[228:231], v[4:7]
	v_mfma_f32_16x16x32_bf16 v[0:3], v[196:199], v[228:231], v[0:3]
	s_setprio 0
	s_barrier
	s_add_u32 s74, s74, 0x100
	s_addc_u32 s75, s75, 0
	s_add_u32 s3, s3, 0x100
	s_addc_u32 s9, s9, 0
	s_cmp_ge_i32 s96, s73
	s_mov_b32 s76, s96
	s_cbranch_scc1 .Lkx_2

.LBB0_863:
	s_add_i32 s34, s7, 0x18000
	s_mov_b64 s[16:17], 0x80
	v_lshl_add_u64 v[10:11], v[10:11], 0, s[16:17]
	s_mov_b32 m0, s34
	s_add_i32 s35, s7, 0x1a000
	s_waitcnt vmcnt(2)
	s_mov_b32 s99, 0
	s_barrier
	global_load_lds_dwordx4 v[10:11], off
	v_lshl_add_u64 v[6:7], v[6:7], 0, s[16:17]
	s_mov_b32 m0, s35
	s_add_i32 s36, s7, 0x8000
	global_load_lds_dwordx4 v[6:7], off
	v_lshl_add_u64 v[6:7], v[8:9], 0, s[16:17]
	s_mov_b32 m0, s36
	s_add_i32 s37, s7, 0xa000
	global_load_lds_dwordx4 v[6:7], off
	v_lshl_add_u64 v[4:5], v[4:5], 0, s[16:17]
	s_mov_b32 m0, s37
	s_add_i32 s46, s7, 0x1c000
	global_load_lds_dwordx4 v[4:5], off
	v_lshl_add_u64 v[2:3], v[2:3], 0, s[16:17]
	s_mov_b32 m0, s46
	s_add_i32 s47, s7, 0x1e000
	global_load_lds_dwordx4 v[2:3], off
	v_lshl_add_u64 v[0:1], v[0:1], 0, s[16:17]
	s_mov_b32 m0, s47
	s_lshl_b32 s3, s3, 5
	global_load_lds_dwordx4 v[0:1], off
	s_waitcnt vmcnt(6)
	s_lshl_b32 s6, s70, 6
	s_and_b32 s3, s3, 0x60
	s_mov_b32 s5, 0
	v_and_b32_e32 v130, 15, v12
	v_bfe_u32 v142, v12, 4, 2
	s_cmp_lt_i32 s27, 64
	v_mov_b32_e32 v126, 0
	v_mov_b32_e32 v125, 0
	v_mov_b32_e32 v124, 0
	v_mov_b32_e32 v123, 0
	v_mov_b32_e32 v122, 0
	v_mov_b32_e32 v121, 0
	v_mov_b32_e32 v120, 0
	v_mov_b32_e32 v111, 0
	v_mov_b32_e32 v110, 0
	v_mov_b32_e32 v109, 0
	v_mov_b32_e32 v108, 0
	v_mov_b32_e32 v107, 0
	v_mov_b32_e32 v106, 0
	v_mov_b32_e32 v105, 0
	v_mov_b32_e32 v104, 0
	v_mov_b32_e32 v95, 0
	v_mov_b32_e32 v94, 0
	v_mov_b32_e32 v93, 0
	v_mov_b32_e32 v92, 0
	v_mov_b32_e32 v91, 0
	v_mov_b32_e32 v90, 0
	v_mov_b32_e32 v89, 0
	v_mov_b32_e32 v88, 0
	v_mov_b32_e32 v79, 0
	v_mov_b32_e32 v78, 0
	v_mov_b32_e32 v77, 0
	v_mov_b32_e32 v76, 0
	v_mov_b32_e32 v75, 0
	v_mov_b32_e32 v74, 0
	v_mov_b32_e32 v73, 0
	v_mov_b32_e32 v72, 0
	v_mov_b32_e32 v119, 0
	v_mov_b32_e32 v118, 0
	v_mov_b32_e32 v117, 0
	v_mov_b32_e32 v116, 0
	v_mov_b32_e32 v115, 0
	v_mov_b32_e32 v114, 0
	v_mov_b32_e32 v113, 0
	v_mov_b32_e32 v112, 0
	v_mov_b32_e32 v103, 0
	v_mov_b32_e32 v102, 0
	v_mov_b32_e32 v101, 0
	v_mov_b32_e32 v100, 0
	v_mov_b32_e32 v99, 0
	v_mov_b32_e32 v98, 0
	v_mov_b32_e32 v97, 0
	v_mov_b32_e32 v96, 0
	v_mov_b32_e32 v87, 0
	v_mov_b32_e32 v86, 0
	v_mov_b32_e32 v85, 0
	v_mov_b32_e32 v84, 0
	v_mov_b32_e32 v83, 0
	v_mov_b32_e32 v82, 0
	v_mov_b32_e32 v81, 0
	v_mov_b32_e32 v80, 0
	v_mov_b32_e32 v71, 0
	v_mov_b32_e32 v70, 0
	v_mov_b32_e32 v69, 0
	v_mov_b32_e32 v68, 0
	v_mov_b32_e32 v67, 0
	v_mov_b32_e32 v66, 0
	v_mov_b32_e32 v65, 0
	v_mov_b32_e32 v64, 0
	v_mov_b32_e32 v63, 0
	v_mov_b32_e32 v62, 0
	v_mov_b32_e32 v61, 0
	v_mov_b32_e32 v60, 0
	v_mov_b32_e32 v59, 0
	v_mov_b32_e32 v58, 0
	v_mov_b32_e32 v57, 0
	v_mov_b32_e32 v56, 0
	v_mov_b32_e32 v47, 0
	v_mov_b32_e32 v46, 0
	v_mov_b32_e32 v45, 0
	v_mov_b32_e32 v44, 0
	v_mov_b32_e32 v43, 0
	v_mov_b32_e32 v42, 0
	v_mov_b32_e32 v41, 0
	v_mov_b32_e32 v40, 0
	v_mov_b32_e32 v31, 0
	v_mov_b32_e32 v30, 0
	v_mov_b32_e32 v29, 0
	v_mov_b32_e32 v28, 0
	v_mov_b32_e32 v27, 0
	v_mov_b32_e32 v26, 0
	v_mov_b32_e32 v25, 0
	v_mov_b32_e32 v24, 0
	v_mov_b32_e32 v15, 0
	v_mov_b32_e32 v14, 0
	v_mov_b32_e32 v13, 0
	v_mov_b32_e32 v12, 0
	v_mov_b32_e32 v11, 0
	v_mov_b32_e32 v10, 0
	v_mov_b32_e32 v9, 0
	v_mov_b32_e32 v8, 0
	v_mov_b32_e32 v55, 0
	v_mov_b32_e32 v54, 0
	v_mov_b32_e32 v53, 0
	v_mov_b32_e32 v52, 0
	v_mov_b32_e32 v51, 0
	v_mov_b32_e32 v50, 0
	v_mov_b32_e32 v49, 0
	v_mov_b32_e32 v48, 0
	v_mov_b32_e32 v39, 0
	v_mov_b32_e32 v38, 0
	v_mov_b32_e32 v37, 0
	v_mov_b32_e32 v36, 0
	v_mov_b32_e32 v35, 0
	v_mov_b32_e32 v34, 0
	v_mov_b32_e32 v33, 0
	v_mov_b32_e32 v32, 0
	v_mov_b32_e32 v23, 0
	v_mov_b32_e32 v22, 0
	v_mov_b32_e32 v21, 0
	v_mov_b32_e32 v20, 0
	v_mov_b32_e32 v19, 0
	v_mov_b32_e32 v18, 0
	v_mov_b32_e32 v17, 0
	v_mov_b32_e32 v16, 0
	v_mov_b32_e32 v7, 0
	v_mov_b32_e32 v6, 0
	v_mov_b32_e32 v5, 0
	v_mov_b32_e32 v4, 0
	v_mov_b32_e32 v3, 0
	v_mov_b32_e32 v2, 0
	v_mov_b32_e32 v1, 0
	v_mov_b32_e32 v0, 0
	s_barrier
	s_cbranch_scc1 .LBB0_867
	s_ashr_i32 s52, s27, 31
	s_lshr_b32 s52, s52, 26
	s_add_i32 s27, s27, s52
	v_or_b32_e32 v0, s6, v130
	s_ashr_i32 s68, s27, 6
	v_lshlrev_b32_e32 v1, 4, v142
	v_lshlrev_b32_e32 v2, 6, v0
	s_movk_i32 s27, 0x3c0
	v_lshlrev_b32_e32 v0, 2, v0
	v_and_or_b32 v2, v2, s27, v1
	s_lshl_b32 s27, s70, 13
	v_and_b32_e32 v0, 32, v0
	v_bitop3_b32 v131, v2, s27, v0 bitop3:0xde
	v_lshl_or_b32 v0, v130, 6, v1
	v_lshlrev_b32_e32 v1, 2, v130
	s_lshl_b32 s27, s3, 7
	v_and_b32_e32 v1, 32, v1
	v_bitop3_b32 v2, v0, s27, v1 bitop3:0xde
	s_mov_b32 s27, s5
	s_add_i32 s69, s68, -2
	s_lshl_b64 s[26:27], s[26:27], 9
	s_add_u32 s26, s26, 0x10100
	s_addc_u32 s27, s27, 0
	s_mul_i32 s25, s26, s25
	s_mul_hi_u32 s52, s26, s24
	s_add_i32 s25, s52, s25
	s_mul_i32 s27, s27, s24
	s_add_i32 s25, s25, s27
	s_mul_i32 s26, s26, s24
	v_add_u32_e32 v0, v143, v138
	s_add_u32 s24, s64, s26
	v_add_lshl_u32 v0, v0, v139, 1
	v_mov_b32_e32 v1, 0
	s_addc_u32 s25, s65, s25
	v_lshl_add_u64 v[138:139], s[24:25], 0, v[0:1]
	v_add_u32_e32 v0, v141, v127
	v_add_lshl_u32 v0, v0, v140, 1
	v_lshl_add_u64 v[140:141], s[24:25], 0, v[0:1]
	v_or_b32_e32 v143, 0x10000, v2
	v_add_u32_e32 v144, 0x10400, v2
	v_add_u32_e32 v145, 0x10800, v2
	v_add_u32_e32 v146, 0x10c00, v2
	v_or_b32_e32 v147, 0x14000, v2
	v_add_u32_e32 v148, 0x14400, v2
	v_add_u32_e32 v149, 0x14800, v2
	v_add_u32_e32 v150, 0x14c00, v2
	s_add_i32 s70, s7, 0xc000
	s_add_i32 s71, s7, 0xe000
	v_or_b32_e32 v151, 0x18000, v2
	v_add_u32_e32 v152, 0x18400, v2
	v_add_u32_e32 v153, 0x18800, v2
	v_add_u32_e32 v154, 0x18c00, v2
	v_or_b32_e32 v155, 0x1c000, v2
	v_add_u32_e32 v156, 0x1c400, v2
	v_add_u32_e32 v157, 0x1c800, v2
	v_add_u32_e32 v158, 0x1cc00, v2
	s_mov_b64 s[24:25], 0x80
	s_mov_b32 s26, s5
	v_mov_b32_e32 v0, v1
	v_mov_b32_e32 v2, v1
	v_mov_b32_e32 v3, v1
	v_mov_b32_e32 v4, v1
	v_mov_b32_e32 v5, v1
	v_mov_b32_e32 v6, v1
	v_mov_b32_e32 v7, v1
	v_mov_b32_e32 v16, v1
	v_mov_b32_e32 v17, v1
	v_mov_b32_e32 v18, v1
	v_mov_b32_e32 v19, v1
	v_mov_b32_e32 v20, v1
	v_mov_b32_e32 v21, v1
	v_mov_b32_e32 v22, v1
	v_mov_b32_e32 v23, v1
	v_mov_b32_e32 v32, v1
	v_mov_b32_e32 v33, v1
	v_mov_b32_e32 v34, v1
	v_mov_b32_e32 v35, v1
	v_mov_b32_e32 v36, v1
	v_mov_b32_e32 v37, v1
	v_mov_b32_e32 v38, v1
	v_mov_b32_e32 v39, v1
	v_mov_b32_e32 v48, v1
	v_mov_b32_e32 v49, v1
	v_mov_b32_e32 v50, v1
	v_mov_b32_e32 v51, v1
	v_mov_b32_e32 v52, v1
	v_mov_b32_e32 v53, v1
	v_mov_b32_e32 v54, v1
	v_mov_b32_e32 v55, v1
	v_mov_b32_e32 v8, v1
	v_mov_b32_e32 v9, v1
	v_mov_b32_e32 v10, v1
	v_mov_b32_e32 v11, v1
	v_mov_b32_e32 v12, v1
	v_mov_b32_e32 v13, v1
	v_mov_b32_e32 v14, v1
	v_mov_b32_e32 v15, v1
	v_mov_b32_e32 v24, v1
	v_mov_b32_e32 v25, v1
	v_mov_b32_e32 v26, v1
	v_mov_b32_e32 v27, v1
	v_mov_b32_e32 v28, v1
	v_mov_b32_e32 v29, v1
	v_mov_b32_e32 v30, v1
	v_mov_b32_e32 v31, v1
	v_mov_b32_e32 v40, v1
	v_mov_b32_e32 v41, v1
	v_mov_b32_e32 v42, v1
	v_mov_b32_e32 v43, v1
	v_mov_b32_e32 v44, v1
	v_mov_b32_e32 v45, v1
	v_mov_b32_e32 v46, v1
	v_mov_b32_e32 v47, v1
	v_mov_b32_e32 v56, v1
	v_mov_b32_e32 v57, v1
	v_mov_b32_e32 v58, v1
	v_mov_b32_e32 v59, v1
	v_mov_b32_e32 v60, v1
	v_mov_b32_e32 v61, v1
	v_mov_b32_e32 v62, v1
	v_mov_b32_e32 v63, v1
	v_mov_b32_e32 v64, v1
	v_mov_b32_e32 v65, v1
	v_mov_b32_e32 v66, v1
	v_mov_b32_e32 v67, v1
	v_mov_b32_e32 v68, v1
	v_mov_b32_e32 v69, v1
	v_mov_b32_e32 v70, v1
	v_mov_b32_e32 v71, v1
	v_mov_b32_e32 v80, v1
	v_mov_b32_e32 v81, v1
	v_mov_b32_e32 v82, v1
	v_mov_b32_e32 v83, v1
	v_mov_b32_e32 v84, v1
	v_mov_b32_e32 v85, v1
	v_mov_b32_e32 v86, v1
	v_mov_b32_e32 v87, v1
	v_mov_b32_e32 v96, v1
	v_mov_b32_e32 v97, v1
	v_mov_b32_e32 v98, v1
	v_mov_b32_e32 v99, v1
	v_mov_b32_e32 v100, v1
	v_mov_b32_e32 v101, v1
	v_mov_b32_e32 v102, v1
	v_mov_b32_e32 v103, v1
	v_mov_b32_e32 v112, v1
	v_mov_b32_e32 v113, v1
	v_mov_b32_e32 v114, v1
	v_mov_b32_e32 v115, v1
	v_mov_b32_e32 v116, v1
	v_mov_b32_e32 v117, v1
	v_mov_b32_e32 v118, v1
	v_mov_b32_e32 v119, v1
	v_mov_b32_e32 v72, v1
	v_mov_b32_e32 v73, v1
	v_mov_b32_e32 v74, v1
	v_mov_b32_e32 v75, v1
	v_mov_b32_e32 v76, v1
	v_mov_b32_e32 v77, v1
	v_mov_b32_e32 v78, v1
	v_mov_b32_e32 v79, v1
	v_mov_b32_e32 v88, v1
	v_mov_b32_e32 v89, v1
	v_mov_b32_e32 v90, v1
	v_mov_b32_e32 v91, v1
	v_mov_b32_e32 v92, v1
	v_mov_b32_e32 v93, v1
	v_mov_b32_e32 v94, v1
	v_mov_b32_e32 v95, v1
	v_mov_b32_e32 v104, v1
	v_mov_b32_e32 v105, v1
	v_mov_b32_e32 v106, v1
	v_mov_b32_e32 v107, v1
	v_mov_b32_e32 v108, v1
	v_mov_b32_e32 v109, v1
	v_mov_b32_e32 v110, v1
	v_mov_b32_e32 v111, v1
	v_mov_b32_e32 v120, v1
	v_mov_b32_e32 v121, v1
	v_mov_b32_e32 v122, v1
	v_mov_b32_e32 v123, v1
	v_mov_b32_e32 v124, v1
	v_mov_b32_e32 v125, v1
	v_mov_b32_e32 v126, v1
	v_mov_b32_e32 v127, v1

.LBB0_873:
	s_lshl_b32 s16, s16, 5
	s_and_b32 s20, s16, 0x60
	s_add_i32 s35, s7, 0x18000
	s_mov_b64 s[16:17], 0xb80
	v_lshl_add_u64 v[0:1], v[0:1], 0, s[16:17]
	s_mov_b32 m0, s35
	s_add_i32 s36, s7, 0x1a000
	s_waitcnt vmcnt(2)
	s_mov_b32 s99, 0
	s_barrier
	global_load_lds_dwordx4 v[0:1], off
	v_lshl_add_u64 v[0:1], v[6:7], 0, s[16:17]
	s_mov_b32 m0, s36
	s_add_i32 s37, s7, 0x8000
	global_load_lds_dwordx4 v[0:1], off
	v_lshl_add_u64 v[0:1], v[8:9], 0, s[16:17]
	s_mov_b32 m0, s37
	s_add_i32 s46, s7, 0xa000
	global_load_lds_dwordx4 v[0:1], off
	v_lshl_add_u64 v[0:1], v[10:11], 0, s[16:17]
	s_mov_b32 m0, s46
	s_add_i32 s47, s7, 0x1c000
	global_load_lds_dwordx4 v[0:1], off
	v_lshl_add_u64 v[0:1], v[2:3], 0, s[16:17]
	s_mov_b32 m0, s47
	s_add_i32 s48, s7, 0x1e000
	global_load_lds_dwordx4 v[0:1], off
	v_lshl_add_u64 v[0:1], v[4:5], 0, s[16:17]
	s_mov_b32 m0, s48
	s_lshl_b32 s6, s25, 6
	global_load_lds_dwordx4 v[0:1], off
	s_waitcnt vmcnt(6)
	s_mov_b32 s5, 0
	v_and_b32_e32 v130, 15, v12
	v_bfe_u32 v142, v12, 4, 2
	s_cmp_lt_i32 s19, 64
	v_mov_b32_e32 v126, 0
	v_mov_b32_e32 v125, 0
	v_mov_b32_e32 v124, 0
	v_mov_b32_e32 v123, 0
	v_mov_b32_e32 v122, 0
	v_mov_b32_e32 v121, 0
	v_mov_b32_e32 v120, 0
	v_mov_b32_e32 v111, 0
	v_mov_b32_e32 v110, 0
	v_mov_b32_e32 v109, 0
	v_mov_b32_e32 v108, 0
	v_mov_b32_e32 v107, 0
	v_mov_b32_e32 v106, 0
	v_mov_b32_e32 v105, 0
	v_mov_b32_e32 v104, 0
	v_mov_b32_e32 v95, 0
	v_mov_b32_e32 v94, 0
	v_mov_b32_e32 v93, 0
	v_mov_b32_e32 v92, 0
	v_mov_b32_e32 v91, 0
	v_mov_b32_e32 v90, 0
	v_mov_b32_e32 v89, 0
	v_mov_b32_e32 v88, 0
	v_mov_b32_e32 v79, 0
	v_mov_b32_e32 v78, 0
	v_mov_b32_e32 v77, 0
	v_mov_b32_e32 v76, 0
	v_mov_b32_e32 v75, 0
	v_mov_b32_e32 v74, 0
	v_mov_b32_e32 v73, 0
	v_mov_b32_e32 v72, 0
	v_mov_b32_e32 v119, 0
	v_mov_b32_e32 v118, 0
	v_mov_b32_e32 v117, 0
	v_mov_b32_e32 v116, 0
	v_mov_b32_e32 v115, 0
	v_mov_b32_e32 v114, 0
	v_mov_b32_e32 v113, 0
	v_mov_b32_e32 v112, 0
	v_mov_b32_e32 v103, 0
	v_mov_b32_e32 v102, 0
	v_mov_b32_e32 v101, 0
	v_mov_b32_e32 v100, 0
	v_mov_b32_e32 v99, 0
	v_mov_b32_e32 v98, 0
	v_mov_b32_e32 v97, 0
	v_mov_b32_e32 v96, 0
	v_mov_b32_e32 v87, 0
	v_mov_b32_e32 v86, 0
	v_mov_b32_e32 v85, 0
	v_mov_b32_e32 v84, 0
	v_mov_b32_e32 v83, 0
	v_mov_b32_e32 v82, 0
	v_mov_b32_e32 v81, 0
	v_mov_b32_e32 v80, 0
	v_mov_b32_e32 v71, 0
	v_mov_b32_e32 v70, 0
	v_mov_b32_e32 v69, 0
	v_mov_b32_e32 v68, 0
	v_mov_b32_e32 v67, 0
	v_mov_b32_e32 v66, 0
	v_mov_b32_e32 v65, 0
	v_mov_b32_e32 v64, 0
	v_mov_b32_e32 v63, 0
	v_mov_b32_e32 v62, 0
	v_mov_b32_e32 v61, 0
	v_mov_b32_e32 v60, 0
	v_mov_b32_e32 v59, 0
	v_mov_b32_e32 v58, 0
	v_mov_b32_e32 v57, 0
	v_mov_b32_e32 v56, 0
	v_mov_b32_e32 v47, 0
	v_mov_b32_e32 v46, 0
	v_mov_b32_e32 v45, 0
	v_mov_b32_e32 v44, 0
	v_mov_b32_e32 v43, 0
	v_mov_b32_e32 v42, 0
	v_mov_b32_e32 v41, 0
	v_mov_b32_e32 v40, 0
	v_mov_b32_e32 v31, 0
	v_mov_b32_e32 v30, 0
	v_mov_b32_e32 v29, 0
	v_mov_b32_e32 v28, 0
	v_mov_b32_e32 v27, 0
	v_mov_b32_e32 v26, 0
	v_mov_b32_e32 v25, 0
	v_mov_b32_e32 v24, 0
	v_mov_b32_e32 v15, 0
	v_mov_b32_e32 v14, 0
	v_mov_b32_e32 v13, 0
	v_mov_b32_e32 v12, 0
	v_mov_b32_e32 v11, 0
	v_mov_b32_e32 v10, 0
	v_mov_b32_e32 v9, 0
	v_mov_b32_e32 v8, 0
	v_mov_b32_e32 v55, 0
	v_mov_b32_e32 v54, 0
	v_mov_b32_e32 v53, 0
	v_mov_b32_e32 v52, 0
	v_mov_b32_e32 v51, 0
	v_mov_b32_e32 v50, 0
	v_mov_b32_e32 v49, 0
	v_mov_b32_e32 v48, 0
	v_mov_b32_e32 v39, 0
	v_mov_b32_e32 v38, 0
	v_mov_b32_e32 v37, 0
	v_mov_b32_e32 v36, 0
	v_mov_b32_e32 v35, 0
	v_mov_b32_e32 v34, 0
	v_mov_b32_e32 v33, 0
	v_mov_b32_e32 v32, 0
	v_mov_b32_e32 v23, 0
	v_mov_b32_e32 v22, 0
	v_mov_b32_e32 v21, 0
	v_mov_b32_e32 v20, 0
	v_mov_b32_e32 v19, 0
	v_mov_b32_e32 v18, 0
	v_mov_b32_e32 v17, 0
	v_mov_b32_e32 v16, 0
	v_mov_b32_e32 v7, 0
	v_mov_b32_e32 v6, 0
	v_mov_b32_e32 v5, 0
	v_mov_b32_e32 v4, 0
	v_mov_b32_e32 v3, 0
	v_mov_b32_e32 v2, 0
	v_mov_b32_e32 v1, 0
	v_mov_b32_e32 v0, 0
	s_barrier
	s_cbranch_scc1 .LBB0_877
	s_ashr_i32 s26, s19, 31
	s_lshr_b32 s26, s26, 26
	v_or_b32_e32 v0, s6, v130
	s_add_i32 s19, s19, s26
	v_lshlrev_b32_e32 v1, 4, v142
	v_lshlrev_b32_e32 v2, 6, v0
	s_movk_i32 s26, 0x3c0
	v_lshlrev_b32_e32 v0, 2, v0
	v_and_or_b32 v2, v2, s26, v1
	s_lshl_b32 s25, s25, 13
	v_and_b32_e32 v0, 32, v0
	v_bitop3_b32 v131, v2, s25, v0 bitop3:0xde
	v_lshl_or_b32 v0, v130, 6, v1
	v_lshlrev_b32_e32 v1, 2, v130
	s_lshl_b32 s25, s20, 7
	v_and_b32_e32 v1, 32, v1
	s_ashr_i32 s19, s19, 6
	v_bitop3_b32 v2, v0, s25, v1 bitop3:0xde
	s_mov_b32 s25, s5
	s_add_i32 s49, s19, -2
	s_lshl_b64 s[24:25], s[24:25], 9
	s_add_u32 s24, s24, 0x10100
	s_addc_u32 s25, s25, 0
	s_mul_i32 s1, s24, s1
	s_mul_hi_u32 s26, s24, s0
	s_add_i32 s1, s26, s1
	s_mul_i32 s25, s25, s0
	s_add_i32 s1, s1, s25
	s_mul_i32 s24, s24, s0
	v_add_u32_e32 v0, v139, v127
	s_add_u32 s0, s64, s24
	v_add_lshl_u32 v0, v0, v138, 1
	v_mov_b32_e32 v1, 0
	s_addc_u32 s1, s65, s1
	v_lshl_add_u64 v[138:139], s[0:1], 0, v[0:1]
	v_add_u32_e32 v0, v143, v140
	v_add_lshl_u32 v0, v0, v141, 1
	v_lshl_add_u64 v[140:141], s[0:1], 0, v[0:1]
	v_or_b32_e32 v143, 0x10000, v2
	v_add_u32_e32 v144, 0x10400, v2
	v_add_u32_e32 v145, 0x10800, v2
	v_add_u32_e32 v146, 0x10c00, v2
	v_or_b32_e32 v147, 0x14000, v2
	v_add_u32_e32 v148, 0x14400, v2
	v_add_u32_e32 v149, 0x14800, v2
	v_add_u32_e32 v150, 0x14c00, v2
	s_add_i32 s68, s7, 0xc000
	s_add_i32 s69, s7, 0xe000
	s_mov_b64 s[0:1], 0xb00
	v_or_b32_e32 v151, 0x18000, v2
	v_add_u32_e32 v152, 0x18400, v2
	v_add_u32_e32 v153, 0x18800, v2
	v_add_u32_e32 v154, 0x18c00, v2
	v_or_b32_e32 v155, 0x1c000, v2
	v_add_u32_e32 v156, 0x1c400, v2
	v_add_u32_e32 v157, 0x1c800, v2
	v_add_u32_e32 v158, 0x1cc00, v2
	s_mov_b64 s[24:25], 0xb80
	s_mov_b32 s26, s5
	v_mov_b32_e32 v0, v1
	v_mov_b32_e32 v2, v1
	v_mov_b32_e32 v3, v1
	v_mov_b32_e32 v4, v1
	v_mov_b32_e32 v5, v1
	v_mov_b32_e32 v6, v1
	v_mov_b32_e32 v7, v1
	v_mov_b32_e32 v16, v1
	v_mov_b32_e32 v17, v1
	v_mov_b32_e32 v18, v1
	v_mov_b32_e32 v19, v1
	v_mov_b32_e32 v20, v1
	v_mov_b32_e32 v21, v1
	v_mov_b32_e32 v22, v1
	v_mov_b32_e32 v23, v1
	v_mov_b32_e32 v32, v1
	v_mov_b32_e32 v33, v1
	v_mov_b32_e32 v34, v1
	v_mov_b32_e32 v35, v1
	v_mov_b32_e32 v36, v1
	v_mov_b32_e32 v37, v1
	v_mov_b32_e32 v38, v1
	v_mov_b32_e32 v39, v1
	v_mov_b32_e32 v48, v1
	v_mov_b32_e32 v49, v1
	v_mov_b32_e32 v50, v1
	v_mov_b32_e32 v51, v1
	v_mov_b32_e32 v52, v1
	v_mov_b32_e32 v53, v1
	v_mov_b32_e32 v54, v1
	v_mov_b32_e32 v55, v1
	v_mov_b32_e32 v8, v1
	v_mov_b32_e32 v9, v1
	v_mov_b32_e32 v10, v1
	v_mov_b32_e32 v11, v1
	v_mov_b32_e32 v12, v1
	v_mov_b32_e32 v13, v1
	v_mov_b32_e32 v14, v1
	v_mov_b32_e32 v15, v1
	v_mov_b32_e32 v24, v1
	v_mov_b32_e32 v25, v1
	v_mov_b32_e32 v26, v1
	v_mov_b32_e32 v27, v1
	v_mov_b32_e32 v28, v1
	v_mov_b32_e32 v29, v1
	v_mov_b32_e32 v30, v1
	v_mov_b32_e32 v31, v1
	v_mov_b32_e32 v40, v1
	v_mov_b32_e32 v41, v1
	v_mov_b32_e32 v42, v1
	v_mov_b32_e32 v43, v1
	v_mov_b32_e32 v44, v1
	v_mov_b32_e32 v45, v1
	v_mov_b32_e32 v46, v1
	v_mov_b32_e32 v47, v1
	v_mov_b32_e32 v56, v1
	v_mov_b32_e32 v57, v1
	v_mov_b32_e32 v58, v1
	v_mov_b32_e32 v59, v1
	v_mov_b32_e32 v60, v1
	v_mov_b32_e32 v61, v1
	v_mov_b32_e32 v62, v1
	v_mov_b32_e32 v63, v1
	v_mov_b32_e32 v64, v1
	v_mov_b32_e32 v65, v1
	v_mov_b32_e32 v66, v1
	v_mov_b32_e32 v67, v1
	v_mov_b32_e32 v68, v1
	v_mov_b32_e32 v69, v1
	v_mov_b32_e32 v70, v1
	v_mov_b32_e32 v71, v1
	v_mov_b32_e32 v80, v1
	v_mov_b32_e32 v81, v1
	v_mov_b32_e32 v82, v1
	v_mov_b32_e32 v83, v1
	v_mov_b32_e32 v84, v1
	v_mov_b32_e32 v85, v1
	v_mov_b32_e32 v86, v1
	v_mov_b32_e32 v87, v1
	v_mov_b32_e32 v96, v1
	v_mov_b32_e32 v97, v1
	v_mov_b32_e32 v98, v1
	v_mov_b32_e32 v99, v1
	v_mov_b32_e32 v100, v1
	v_mov_b32_e32 v101, v1
	v_mov_b32_e32 v102, v1
	v_mov_b32_e32 v103, v1
	v_mov_b32_e32 v112, v1
	v_mov_b32_e32 v113, v1
	v_mov_b32_e32 v114, v1
	v_mov_b32_e32 v115, v1
	v_mov_b32_e32 v116, v1
	v_mov_b32_e32 v117, v1
	v_mov_b32_e32 v118, v1
	v_mov_b32_e32 v119, v1
	v_mov_b32_e32 v72, v1
	v_mov_b32_e32 v73, v1
	v_mov_b32_e32 v74, v1
	v_mov_b32_e32 v75, v1
	v_mov_b32_e32 v76, v1
	v_mov_b32_e32 v77, v1
	v_mov_b32_e32 v78, v1
	v_mov_b32_e32 v79, v1
	v_mov_b32_e32 v88, v1
	v_mov_b32_e32 v89, v1
	v_mov_b32_e32 v90, v1
	v_mov_b32_e32 v91, v1
	v_mov_b32_e32 v92, v1
	v_mov_b32_e32 v93, v1
	v_mov_b32_e32 v94, v1
	v_mov_b32_e32 v95, v1
	v_mov_b32_e32 v104, v1
	v_mov_b32_e32 v105, v1
	v_mov_b32_e32 v106, v1
	v_mov_b32_e32 v107, v1
	v_mov_b32_e32 v108, v1
	v_mov_b32_e32 v109, v1
	v_mov_b32_e32 v110, v1
	v_mov_b32_e32 v111, v1
	v_mov_b32_e32 v120, v1
	v_mov_b32_e32 v121, v1
	v_mov_b32_e32 v122, v1
	v_mov_b32_e32 v123, v1
	v_mov_b32_e32 v124, v1
	v_mov_b32_e32 v125, v1
	v_mov_b32_e32 v126, v1
	v_mov_b32_e32 v127, v1

.LBB0_1083:
	s_add_i32 s97, s3, 0x18000
	s_mov_b64 s[46:47], 0x80
	v_lshl_add_u64 v[8:9], v[8:9], 0, s[46:47]
	s_mov_b32 m0, s97
	s_add_i32 s96, s3, 0x1a000
	s_waitcnt vmcnt(2)
	s_mov_b32 s99, 0
	s_barrier
	global_load_lds_dwordx4 v[8:9], off
	v_lshl_add_u64 v[4:5], v[4:5], 0, s[46:47]
	s_mov_b32 m0, s96
	s_add_i32 s20, s3, 0x8000
	global_load_lds_dwordx4 v[4:5], off
	v_lshl_add_u64 v[4:5], v[6:7], 0, s[46:47]
	s_mov_b32 m0, s20
	s_add_i32 s21, s3, 0xa000
	global_load_lds_dwordx4 v[4:5], off
	v_lshl_add_u64 v[4:5], v[10:11], 0, s[46:47]
	s_mov_b32 m0, s21
	s_add_i32 s90, s3, 0x1c000
	global_load_lds_dwordx4 v[4:5], off
	v_lshl_add_u64 v[2:3], v[2:3], 0, s[46:47]
	s_mov_b32 m0, s90
	s_add_i32 s28, s3, 0x1e000
	global_load_lds_dwordx4 v[2:3], off
	v_lshl_add_u64 v[0:1], v[0:1], 0, s[46:47]
	s_mov_b32 m0, s28
	s_ashr_i32 s4, s11, 31
	global_load_lds_dwordx4 v[0:1], off
	v_bfe_u32 v159, v12, 4, 2
	s_lshr_b32 s4, s4, 26
	v_and_b32_e32 v158, 15, v12
	s_add_i32 s4, s11, s4
	v_lshlrev_b32_e32 v0, 4, v159
	v_lshlrev_b32_e32 v1, 2, v12
	s_ashr_i32 s29, s4, 6
	v_lshl_or_b32 v0, v158, 6, v0
	s_lshl_b32 s4, s18, 13
	v_and_b32_e32 v1, 32, v1
	v_bitop3_b32 v160, v0, s4, v1 bitop3:0xde
	s_lshl_b32 s4, s19, 5
	s_and_b32 s34, s4, 0x60
	s_lshl_b32 s48, s18, 6
	s_lshl_b32 s4, s34, 7
	s_cmp_gt_i32 s11, 63
	s_cselect_b64 s[58:59], -1, 0
	s_add_i32 s35, s29, -2
	v_bitop3_b32 v2, v0, s4, v1 bitop3:0xde
	s_cmpk_lt_u32 s10, 0x100
	v_readlane_b32 s4, v246, 5
	s_cselect_b64 s[68:69], -1, 0
	s_ashr_i32 s49, s48, 31
	s_ashr_i32 s33, s4, 31
	s_ashr_i32 s37, s2, 31
	v_add_u32_e32 v0, v15, v13
	s_add_u32 s72, s64, 0xac40000
	v_add_lshl_u32 v0, v0, v14, 1
	v_mov_b32_e32 v1, v139
	s_waitcnt vmcnt(6)
	v_readlane_b32 s5, v246, 6
	s_addc_u32 s73, s65, 0
	v_lshl_add_u64 v[144:145], s[0:1], 0, v[0:1]
	v_add_u32_e32 v0, v18, v16
	v_writelane_b32 v246, s56, 14
	s_add_u32 s74, s64, 0xaa00000
	v_add_lshl_u32 v0, v0, v17, 1
	v_writelane_b32 v246, s57, 15
	s_mov_b32 s71, 0
	s_mov_b32 s36, s4
	s_addc_u32 s75, s65, 0
	v_lshl_add_u64 v[146:147], s[0:1], 0, v[0:1]
	v_mov_b64_e32 v[148:149], 0x97f
	v_or_b32_e32 v161, 0x10000, v2
	v_add_u32_e32 v164, 0x10400, v2
	v_add_u32_e32 v165, 0x10800, v2
	v_add_u32_e32 v166, 0x10c00, v2
	v_or_b32_e32 v167, 0x14000, v2
	v_add_u32_e32 v168, 0x14400, v2
	v_add_u32_e32 v169, 0x14800, v2
	v_add_u32_e32 v170, 0x14c00, v2
	s_add_i32 s18, s3, 0xc000
	s_add_i32 s19, s3, 0xe000
	v_or_b32_e32 v171, 0x18000, v2
	v_add_u32_e32 v172, 0x18400, v2
	v_add_u32_e32 v173, 0x18800, v2
	v_add_u32_e32 v174, 0x18c00, v2
	v_or_b32_e32 v175, 0x1c000, v2
	v_add_u32_e32 v176, 0x1c400, v2
	v_add_u32_e32 v177, 0x1c800, v2
	v_add_u32_e32 v178, 0x1cc00, v2
	v_mbcnt_hi_u32_b32 v179, -1, v163
	v_mov_b32_e32 v180, 0x3e38aa3b
	s_mov_b32 s81, 0
	v_writelane_b32 v246, s58, 16
	s_barrier
	s_nop 0
	v_writelane_b32 v246, s59, 17
	s_branch .LBB0_1086

.LBB0_1094:
	s_add_u32 s6, s6, 0x80
	s_addc_u32 s7, s7, 0
	s_add_u32 s10, s8, 0x100
	s_addc_u32 s11, s9, 0
	s_waitcnt lgkmcnt(0)
	ds_read_b128 v[128:131], v161
	ds_read_b128 v[132:135], v164
	ds_read_b128 v[150:153], v165
	ds_read_b128 v[154:157], v166
	ds_read_b128 v[182:185], v167
	ds_read_b128 v[186:189], v168
	ds_read_b128 v[190:193], v169
	ds_read_b128 v[194:197], v170
	s_add_i32 s77, s70, 2
	s_add_u32 s8, s6, 0x80
	s_addc_u32 s9, s7, 0
	s_cmp_eq_u32 s35, s70
	s_cselect_b32 s9, s79, s9
	s_cselect_b32 s8, s78, s8
	s_cselect_b32 s53, s83, s11
	s_cselect_b32 s52, s82, s10
	s_mov_b32 m0, s18
	v_lshl_add_u64 v[230:231], s[6:7], 0, v[144:145]
	ds_read_b128 v[198:201], v160
	ds_read_b128 v[202:205], v160 offset:1024
	ds_read_b128 v[206:209], v160 offset:2048
	ds_read_b128 v[210:213], v160 offset:3072
	ds_read_b128 v[214:217], v160 offset:4096
	ds_read_b128 v[218:221], v160 offset:5120
	ds_read_b128 v[222:225], v160 offset:6144
	ds_read_b128 v[226:229], v160 offset:7168
	global_load_lds_dwordx4 v[230:231], off
	v_lshl_add_u64 v[230:231], s[6:7], 0, v[146:147]
	s_mov_b32 m0, s19
	s_nop 0
	global_load_lds_dwordx4 v[230:231], off
	s_waitcnt vmcnt(8)
	s_waitcnt lgkmcnt(0)
	s_barrier
	s_setprio 1
	s_waitcnt lgkmcnt(0)
	v_mfma_f32_16x16x32_bf16 v[112:115], v[128:131], v[198:201], 0
	v_mfma_f32_16x16x32_bf16 v[124:127], v[150:153], v[198:201], 0
	v_mfma_f32_16x16x32_bf16 v[120:123], v[128:131], v[206:209], 0
	v_mfma_f32_16x16x32_bf16 v[116:119], v[150:153], v[206:209], 0
	v_mfma_f32_16x16x32_bf16 v[108:111], v[128:131], v[214:217], 0
	v_mfma_f32_16x16x32_bf16 v[104:107], v[150:153], v[214:217], 0
	v_mfma_f32_16x16x32_bf16 v[92:95], v[128:131], v[222:225], 0
	v_mfma_f32_16x16x32_bf16 v[88:91], v[150:153], v[222:225], 0
	v_mfma_f32_16x16x32_bf16 v[112:115], v[132:135], v[202:205], v[112:115]
	v_mfma_f32_16x16x32_bf16 v[124:127], v[154:157], v[202:205], v[124:127]
	v_mfma_f32_16x16x32_bf16 v[120:123], v[132:135], v[210:213], v[120:123]
	v_mfma_f32_16x16x32_bf16 v[116:119], v[154:157], v[210:213], v[116:119]
	v_mfma_f32_16x16x32_bf16 v[108:111], v[132:135], v[218:221], v[108:111]
	v_mfma_f32_16x16x32_bf16 v[104:107], v[154:157], v[218:221], v[104:107]
	v_mfma_f32_16x16x32_bf16 v[92:95], v[132:135], v[226:229], v[92:95]
	v_mfma_f32_16x16x32_bf16 v[88:91], v[154:157], v[226:229], v[88:91]
	s_setprio 0
	s_setprio 1
	v_mfma_f32_16x16x32_bf16 v[100:103], v[182:185], v[198:201], 0
	v_mfma_f32_16x16x32_bf16 v[96:99], v[190:193], v[198:201], 0
	v_mfma_f32_16x16x32_bf16 v[84:87], v[182:185], v[206:209], 0
	v_mfma_f32_16x16x32_bf16 v[80:83], v[190:193], v[206:209], 0
	v_mfma_f32_16x16x32_bf16 v[76:79], v[182:185], v[214:217], 0
	v_mfma_f32_16x16x32_bf16 v[72:75], v[190:193], v[214:217], 0
	v_mfma_f32_16x16x32_bf16 v[60:63], v[182:185], v[222:225], 0
	v_mfma_f32_16x16x32_bf16 v[56:59], v[190:193], v[222:225], 0
	v_mfma_f32_16x16x32_bf16 v[100:103], v[186:189], v[202:205], v[100:103]
	v_mfma_f32_16x16x32_bf16 v[96:99], v[194:197], v[202:205], v[96:99]
	v_mfma_f32_16x16x32_bf16 v[84:87], v[186:189], v[210:213], v[84:87]
	v_mfma_f32_16x16x32_bf16 v[80:83], v[194:197], v[210:213], v[80:83]
	v_mfma_f32_16x16x32_bf16 v[76:79], v[186:189], v[218:221], v[76:79]
	v_mfma_f32_16x16x32_bf16 v[72:75], v[194:197], v[218:221], v[72:75]
	v_mfma_f32_16x16x32_bf16 v[60:63], v[186:189], v[226:229], v[60:63]
	v_mfma_f32_16x16x32_bf16 v[56:59], v[194:197], v[226:229], v[56:59]
	s_setprio 0
	s_barrier
	s_mov_b32 m0, s88
	v_lshl_add_u64 v[230:231], s[52:53], 0, v[138:139]
	v_lshl_add_u64 v[232:233], s[52:53], 0, v[142:143]
	s_add_u32 s52, s52, s12
	ds_read_b128 v[198:201], v160 offset:16384
	ds_read_b128 v[202:205], v160 offset:17408
	ds_read_b128 v[206:209], v160 offset:18432
	ds_read_b128 v[210:213], v160 offset:19456
	ds_read_b128 v[214:217], v160 offset:20480
	ds_read_b128 v[218:221], v160 offset:21504
	ds_read_b128 v[222:225], v160 offset:22528
	ds_read_b128 v[226:229], v160 offset:23552
	global_load_lds_dwordx4 v[230:231], off
	s_mov_b32 m0, s89
	s_addc_u32 s53, s53, s13
	global_load_lds_dwordx4 v[232:233], off
	v_lshl_add_u64 v[234:235], s[52:53], 0, v[138:139]
	s_mov_b32 m0, s91
	v_lshl_add_u64 v[236:237], s[52:53], 0, v[142:143]
	global_load_lds_dwordx4 v[234:235], off
	s_mov_b32 m0, s92
	v_lshl_add_u64 v[238:239], s[8:9], 0, v[136:137]
	global_load_lds_dwordx4 v[236:237], off
	s_mov_b32 m0, s3
	v_lshl_add_u64 v[240:241], s[8:9], 0, v[140:141]
	global_load_lds_dwordx4 v[238:239], off
	s_mov_b32 m0, s93
	s_nop 0
	global_load_lds_dwordx4 v[240:241], off
	s_waitcnt vmcnt(8)
	s_waitcnt lgkmcnt(0)
	s_barrier
	s_setprio 1
	s_waitcnt lgkmcnt(0)
	v_mfma_f32_16x16x32_bf16 v[68:71], v[128:131], v[198:201], 0
	v_mfma_f32_16x16x32_bf16 v[64:67], v[150:153], v[198:201], 0
	v_mfma_f32_16x16x32_bf16 v[52:55], v[128:131], v[206:209], 0
	v_mfma_f32_16x16x32_bf16 v[48:51], v[150:153], v[206:209], 0
	v_mfma_f32_16x16x32_bf16 v[44:47], v[128:131], v[214:217], 0
	v_mfma_f32_16x16x32_bf16 v[32:35], v[150:153], v[214:217], 0
	v_mfma_f32_16x16x32_bf16 v[24:27], v[128:131], v[222:225], 0
	v_mfma_f32_16x16x32_bf16 v[16:19], v[150:153], v[222:225], 0
	v_mfma_f32_16x16x32_bf16 v[68:71], v[132:135], v[202:205], v[68:71]
	v_mfma_f32_16x16x32_bf16 v[64:67], v[154:157], v[202:205], v[64:67]
	v_mfma_f32_16x16x32_bf16 v[52:55], v[132:135], v[210:213], v[52:55]
	v_mfma_f32_16x16x32_bf16 v[48:51], v[154:157], v[210:213], v[48:51]
	v_mfma_f32_16x16x32_bf16 v[44:47], v[132:135], v[218:221], v[44:47]
	v_mfma_f32_16x16x32_bf16 v[32:35], v[154:157], v[218:221], v[32:35]
	v_mfma_f32_16x16x32_bf16 v[24:27], v[132:135], v[226:229], v[24:27]
	v_mfma_f32_16x16x32_bf16 v[16:19], v[154:157], v[226:229], v[16:19]
	s_setprio 0
	s_setprio 1
	v_mfma_f32_16x16x32_bf16 v[40:43], v[182:185], v[198:201], 0
	v_mfma_f32_16x16x32_bf16 v[36:39], v[190:193], v[198:201], 0
	v_mfma_f32_16x16x32_bf16 v[28:31], v[182:185], v[206:209], 0
	v_mfma_f32_16x16x32_bf16 v[20:23], v[190:193], v[206:209], 0
	v_mfma_f32_16x16x32_bf16 v[12:15], v[182:185], v[214:217], 0
	v_mfma_f32_16x16x32_bf16 v[8:11], v[190:193], v[214:217], 0
	v_mfma_f32_16x16x32_bf16 v[4:7], v[182:185], v[222:225], 0
	v_mfma_f32_16x16x32_bf16 v[0:3], v[190:193], v[222:225], 0
	v_mfma_f32_16x16x32_bf16 v[40:43], v[186:189], v[202:205], v[40:43]
	v_mfma_f32_16x16x32_bf16 v[36:39], v[194:197], v[202:205], v[36:39]
	v_mfma_f32_16x16x32_bf16 v[28:31], v[186:189], v[210:213], v[28:31]
	v_mfma_f32_16x16x32_bf16 v[20:23], v[194:197], v[210:213], v[20:23]
	v_mfma_f32_16x16x32_bf16 v[12:15], v[186:189], v[218:221], v[12:15]
	v_mfma_f32_16x16x32_bf16 v[8:11], v[194:197], v[218:221], v[8:11]
	v_mfma_f32_16x16x32_bf16 v[4:7], v[186:189], v[226:229], v[4:7]
	v_mfma_f32_16x16x32_bf16 v[0:3], v[194:197], v[226:229], v[0:3]
	s_setprio 0
	s_barrier
	ds_read_b128 v[128:131], v171
	ds_read_b128 v[132:135], v172
	ds_read_b128 v[150:153], v173
	ds_read_b128 v[154:157], v174
	ds_read_b128 v[182:185], v175
	ds_read_b128 v[186:189], v176
	ds_read_b128 v[190:193], v177
	ds_read_b128 v[194:197], v178
	s_add_u32 s8, s8, s0
	s_addc_u32 s9, s9, s1
	s_mov_b32 m0, s94
	v_lshl_add_u64 v[242:243], s[8:9], 0, v[136:137]
	ds_read_b128 v[198:201], v160 offset:32768
	ds_read_b128 v[202:205], v160 offset:33792
	ds_read_b128 v[206:209], v160 offset:34816
	ds_read_b128 v[210:213], v160 offset:35840
	ds_read_b128 v[214:217], v160 offset:36864
	ds_read_b128 v[218:221], v160 offset:37888
	ds_read_b128 v[222:225], v160 offset:38912
	ds_read_b128 v[226:229], v160 offset:39936
	global_load_lds_dwordx4 v[242:243], off
	v_lshl_add_u64 v[242:243], s[8:9], 0, v[140:141]
	s_mov_b32 m0, s95
	s_nop 0
	global_load_lds_dwordx4 v[242:243], off
	s_waitcnt vmcnt(8)
	s_waitcnt lgkmcnt(0)
	s_barrier
	s_setprio 1
	s_waitcnt lgkmcnt(0)
	v_mfma_f32_16x16x32_bf16 v[112:115], v[128:131], v[198:201], v[112:115]
	v_mfma_f32_16x16x32_bf16 v[124:127], v[150:153], v[198:201], v[124:127]
	v_mfma_f32_16x16x32_bf16 v[120:123], v[128:131], v[206:209], v[120:123]
	v_mfma_f32_16x16x32_bf16 v[116:119], v[150:153], v[206:209], v[116:119]
	v_mfma_f32_16x16x32_bf16 v[108:111], v[128:131], v[214:217], v[108:111]
	v_mfma_f32_16x16x32_bf16 v[104:107], v[150:153], v[214:217], v[104:107]
	v_mfma_f32_16x16x32_bf16 v[92:95], v[128:131], v[222:225], v[92:95]
	v_mfma_f32_16x16x32_bf16 v[88:91], v[150:153], v[222:225], v[88:91]
	v_mfma_f32_16x16x32_bf16 v[112:115], v[132:135], v[202:205], v[112:115]
	v_mfma_f32_16x16x32_bf16 v[124:127], v[154:157], v[202:205], v[124:127]
	v_mfma_f32_16x16x32_bf16 v[120:123], v[132:135], v[210:213], v[120:123]
	v_mfma_f32_16x16x32_bf16 v[116:119], v[154:157], v[210:213], v[116:119]
	v_mfma_f32_16x16x32_bf16 v[108:111], v[132:135], v[218:221], v[108:111]
	v_mfma_f32_16x16x32_bf16 v[104:107], v[154:157], v[218:221], v[104:107]
	v_mfma_f32_16x16x32_bf16 v[92:95], v[132:135], v[226:229], v[92:95]
	v_mfma_f32_16x16x32_bf16 v[88:91], v[154:157], v[226:229], v[88:91]
	s_setprio 0
	s_setprio 1
	v_mfma_f32_16x16x32_bf16 v[100:103], v[182:185], v[198:201], v[100:103]
	v_mfma_f32_16x16x32_bf16 v[96:99], v[190:193], v[198:201], v[96:99]
	v_mfma_f32_16x16x32_bf16 v[84:87], v[182:185], v[206:209], v[84:87]
	v_mfma_f32_16x16x32_bf16 v[80:83], v[190:193], v[206:209], v[80:83]
	v_mfma_f32_16x16x32_bf16 v[76:79], v[182:185], v[214:217], v[76:79]
	v_mfma_f32_16x16x32_bf16 v[72:75], v[190:193], v[214:217], v[72:75]
	v_mfma_f32_16x16x32_bf16 v[60:63], v[182:185], v[222:225], v[60:63]
	v_mfma_f32_16x16x32_bf16 v[56:59], v[190:193], v[222:225], v[56:59]
	v_mfma_f32_16x16x32_bf16 v[100:103], v[186:189], v[202:205], v[100:103]
	v_mfma_f32_16x16x32_bf16 v[96:99], v[194:197], v[202:205], v[96:99]
	v_mfma_f32_16x16x32_bf16 v[84:87], v[186:189], v[210:213], v[84:87]
	v_mfma_f32_16x16x32_bf16 v[80:83], v[194:197], v[210:213], v[80:83]
	v_mfma_f32_16x16x32_bf16 v[76:79], v[186:189], v[218:221], v[76:79]
	v_mfma_f32_16x16x32_bf16 v[72:75], v[194:197], v[218:221], v[72:75]
	v_mfma_f32_16x16x32_bf16 v[60:63], v[186:189], v[226:229], v[60:63]
	v_mfma_f32_16x16x32_bf16 v[56:59], v[194:197], v[226:229], v[56:59]
	s_setprio 0
	s_barrier
	s_mov_b32 m0, s97
	v_lshl_add_u64 v[230:231], v[230:231], 0, s[46:47]
	ds_read_b128 v[198:201], v160 offset:49152
	ds_read_b128 v[202:205], v160 offset:50176
	ds_read_b128 v[206:209], v160 offset:51200
	ds_read_b128 v[210:213], v160 offset:52224
	ds_read_b128 v[214:217], v160 offset:53248
	ds_read_b128 v[218:221], v160 offset:54272
	ds_read_b128 v[222:225], v160 offset:55296
	ds_read_b128 v[226:229], v160 offset:56320
	global_load_lds_dwordx4 v[230:231], off
	v_lshl_add_u64 v[230:231], v[232:233], 0, s[46:47]
	s_mov_b32 m0, s96
	s_nop 0
	global_load_lds_dwordx4 v[230:231], off
	v_lshl_add_u64 v[230:231], v[234:235], 0, s[46:47]
	s_mov_b32 m0, s90
	s_nop 0
	global_load_lds_dwordx4 v[230:231], off
	v_lshl_add_u64 v[230:231], v[236:237], 0, s[46:47]
	s_mov_b32 m0, s28
	s_nop 0
	global_load_lds_dwordx4 v[230:231], off
	v_lshl_add_u64 v[230:231], v[238:239], 0, s[46:47]
	s_mov_b32 m0, s20
	s_nop 0
	global_load_lds_dwordx4 v[230:231], off
	v_lshl_add_u64 v[230:231], v[240:241], 0, s[46:47]
	s_mov_b32 m0, s21
	s_nop 0
	global_load_lds_dwordx4 v[230:231], off
	s_waitcnt vmcnt(8)
	s_waitcnt lgkmcnt(0)
	s_barrier
	s_setprio 1
	s_waitcnt lgkmcnt(0)
	v_mfma_f32_16x16x32_bf16 v[68:71], v[128:131], v[198:201], v[68:71]
	v_mfma_f32_16x16x32_bf16 v[64:67], v[150:153], v[198:201], v[64:67]
	v_mfma_f32_16x16x32_bf16 v[52:55], v[128:131], v[206:209], v[52:55]
	v_mfma_f32_16x16x32_bf16 v[48:51], v[150:153], v[206:209], v[48:51]
	v_mfma_f32_16x16x32_bf16 v[44:47], v[128:131], v[214:217], v[44:47]
	v_mfma_f32_16x16x32_bf16 v[32:35], v[150:153], v[214:217], v[32:35]
	v_mfma_f32_16x16x32_bf16 v[24:27], v[128:131], v[222:225], v[24:27]
	v_mfma_f32_16x16x32_bf16 v[16:19], v[150:153], v[222:225], v[16:19]
	v_mfma_f32_16x16x32_bf16 v[68:71], v[132:135], v[202:205], v[68:71]
	v_mfma_f32_16x16x32_bf16 v[64:67], v[154:157], v[202:205], v[64:67]
	v_mfma_f32_16x16x32_bf16 v[52:55], v[132:135], v[210:213], v[52:55]
	v_mfma_f32_16x16x32_bf16 v[48:51], v[154:157], v[210:213], v[48:51]
	v_mfma_f32_16x16x32_bf16 v[44:47], v[132:135], v[218:221], v[44:47]
	v_mfma_f32_16x16x32_bf16 v[32:35], v[154:157], v[218:221], v[32:35]
	v_mfma_f32_16x16x32_bf16 v[24:27], v[132:135], v[226:229], v[24:27]
	v_mfma_f32_16x16x32_bf16 v[16:19], v[154:157], v[226:229], v[16:19]
	s_setprio 0
	s_setprio 1
	v_mfma_f32_16x16x32_bf16 v[40:43], v[182:185], v[198:201], v[40:43]
	v_mfma_f32_16x16x32_bf16 v[36:39], v[190:193], v[198:201], v[36:39]
	v_mfma_f32_16x16x32_bf16 v[28:31], v[182:185], v[206:209], v[28:31]
	v_mfma_f32_16x16x32_bf16 v[20:23], v[190:193], v[206:209], v[20:23]
	v_mfma_f32_16x16x32_bf16 v[12:15], v[182:185], v[214:217], v[12:15]
	v_mfma_f32_16x16x32_bf16 v[8:11], v[190:193], v[214:217], v[8:11]
	v_mfma_f32_16x16x32_bf16 v[4:7], v[182:185], v[222:225], v[4:7]
	v_mfma_f32_16x16x32_bf16 v[0:3], v[190:193], v[222:225], v[0:3]
	v_mfma_f32_16x16x32_bf16 v[40:43], v[186:189], v[202:205], v[40:43]
	v_mfma_f32_16x16x32_bf16 v[36:39], v[194:197], v[202:205], v[36:39]
	v_mfma_f32_16x16x32_bf16 v[28:31], v[186:189], v[210:213], v[28:31]
	v_mfma_f32_16x16x32_bf16 v[20:23], v[194:197], v[210:213], v[20:23]
	v_mfma_f32_16x16x32_bf16 v[12:15], v[186:189], v[218:221], v[12:15]
	v_mfma_f32_16x16x32_bf16 v[8:11], v[194:197], v[218:221], v[8:11]
	v_mfma_f32_16x16x32_bf16 v[4:7], v[186:189], v[226:229], v[4:7]
	v_mfma_f32_16x16x32_bf16 v[0:3], v[194:197], v[226:229], v[0:3]
	s_setprio 0
	s_barrier
	s_add_u32 s6, s6, 0x100
	s_addc_u32 s7, s7, 0
	s_add_u32 s10, s10, 0x100
	s_addc_u32 s11, s11, 0
	s_cmp_ge_i32 s77, s29
	s_mov_b32 s70, s77
	s_cbranch_scc1 .Lkx_3

.Lkx_3:
	s_mov_b32 s99, 1
	s_and_b64 vcc, exec, s[68:69]
	s_cbranch_vccz .LBB0_1098

.LBB0_1210:
	s_add_i32 s34, s3, 0x18000
	s_mov_b64 s[66:67], 0x80
	v_lshl_add_u64 v[8:9], v[8:9], 0, s[66:67]
	s_mov_b32 m0, s34
	s_add_i32 s35, s3, 0x1a000
	s_waitcnt vmcnt(2)
	s_mov_b32 s99, 0
	s_barrier
	global_load_lds_dwordx4 v[8:9], off
	v_lshl_add_u64 v[4:5], v[4:5], 0, s[66:67]
	s_mov_b32 m0, s35
	s_add_i32 s80, s3, 0x8000
	global_load_lds_dwordx4 v[4:5], off
	v_lshl_add_u64 v[4:5], v[6:7], 0, s[66:67]
	s_mov_b32 m0, s80
	s_add_i32 s81, s3, 0xa000
	global_load_lds_dwordx4 v[4:5], off
	v_lshl_add_u64 v[4:5], v[10:11], 0, s[66:67]
	s_mov_b32 m0, s81
	s_add_i32 s82, s3, 0x1c000
	global_load_lds_dwordx4 v[4:5], off
	v_lshl_add_u64 v[2:3], v[2:3], 0, s[66:67]
	s_mov_b32 m0, s82
	s_add_i32 s83, s3, 0x1e000
	global_load_lds_dwordx4 v[2:3], off
	v_lshl_add_u64 v[0:1], v[0:1], 0, s[66:67]
	s_mov_b32 m0, s83
	s_ashr_i32 s0, s15, 31
	global_load_lds_dwordx4 v[0:1], off
	v_bfe_u32 v153, v12, 4, 2
	s_lshr_b32 s0, s0, 26
	v_and_b32_e32 v152, 15, v12
	s_add_i32 s0, s15, s0
	v_lshlrev_b32_e32 v0, 4, v153
	v_lshlrev_b32_e32 v1, 2, v12
	s_ashr_i32 s84, s0, 6
	v_lshl_or_b32 v0, v152, 6, v0
	s_lshl_b32 s0, s6, 13
	v_and_b32_e32 v1, 32, v1
	v_bitop3_b32 v154, v0, s0, v1 bitop3:0xde
	s_lshl_b32 s0, s7, 5
	s_and_b32 s88, s0, 0x60
	s_lshl_b32 s0, s88, 7
	v_bitop3_b32 v2, v0, s0, v1 bitop3:0xde
	v_add_u32_e32 v0, v15, v13
	s_lshl_b32 s85, s6, 6
	v_add_lshl_u32 v0, v0, v14, 1
	v_mov_b32_e32 v1, v131
	s_cmp_gt_i32 s15, 63
	v_lshl_add_u64 v[136:137], s[26:27], 0, v[0:1]
	v_add_u32_e32 v0, v18, v16
	s_waitcnt vmcnt(6)
	s_cselect_b64 s[0:1], -1, 0
	s_add_i32 s89, s84, -2
	v_readlane_b32 s4, v246, 5
	v_add_lshl_u32 v0, v0, v17, 1
	s_cmpk_lt_u32 s14, 0x100
	v_readlane_b32 s5, v246, 6
	v_lshl_add_u64 v[138:139], s[26:27], 0, v[0:1]
	v_cndmask_b32_e64 v0, 0, 1, s[0:1]
	s_cselect_b64 s[68:69], -1, 0
	s_ashr_i32 s90, s4, 31
	s_mov_b32 s91, s4
	s_ashr_i32 s92, s2, 31
	s_mov_b32 s93, 0
	v_mov_b64_e32 v[140:141], 0x180
	v_mov_b64_e32 v[142:143], 0x17f
	v_cmp_ne_u32_e64 s[4:5], 1, v0
	v_or_b32_e32 v155, 0x10000, v2
	v_add_u32_e32 v156, 0x10400, v2
	v_add_u32_e32 v157, 0x10800, v2
	v_add_u32_e32 v158, 0x10c00, v2
	v_or_b32_e32 v159, 0x14000, v2
	v_add_u32_e32 v160, 0x14400, v2
	v_add_u32_e32 v161, 0x14800, v2
	v_add_u32_e32 v164, 0x14c00, v2
	s_add_i32 s94, s3, 0xc000
	s_add_i32 s95, s3, 0xe000
	v_or_b32_e32 v165, 0x18000, v2
	v_add_u32_e32 v166, 0x18400, v2
	v_add_u32_e32 v167, 0x18800, v2
	v_add_u32_e32 v168, 0x18c00, v2
	v_or_b32_e32 v169, 0x1c000, v2
	v_add_u32_e32 v170, 0x1c400, v2
	v_add_u32_e32 v171, 0x1c800, v2
	v_add_u32_e32 v172, 0x1cc00, v2
	v_mov_b32_e32 v173, 0x358637bd
	s_mov_b32 s96, 0x800000
	s_movk_i32 s97, 0x600
	v_mbcnt_hi_u32_b32 v174, -1, v163
	s_barrier
	s_branch .LBB0_1213

.LBB0_1219:
	s_and_b64 vcc, exec, s[4:5]
	s_cbranch_vccnz .Lkz_4
	s_branch .Lkp_4

.Lkp_4:
	s_add_u32 s0, s10, 0x80
	s_addc_u32 s1, s11, 0
	s_add_u32 s10, s8, 0x100
	s_addc_u32 s11, s9, 0
	s_mov_b32 s8, 0
	ds_read_b128 v[144:147], v155
	ds_read_b128 v[148:151], v156
	ds_read_b128 v[176:179], v157
	ds_read_b128 v[180:183], v158
	ds_read_b128 v[184:187], v159
	ds_read_b128 v[188:191], v160
	ds_read_b128 v[192:195], v161
	ds_read_b128 v[196:199], v164
	s_add_i32 s14, s8, 2
	s_add_u32 s15, s0, 0x80
	s_addc_u32 s9, s1, 0
	s_cmp_eq_u32 s89, s8
	s_cselect_b32 s8, s70, s15
	s_cselect_b32 s9, s71, s9
	s_cselect_b32 s53, s73, s11
	s_cselect_b32 s52, s72, s10
	s_mov_b32 m0, s94
	v_lshl_add_u64 v[232:233], s[0:1], 0, v[136:137]
	ds_read_b128 v[200:203], v154
	ds_read_b128 v[204:207], v154 offset:1024
	ds_read_b128 v[208:211], v154 offset:2048
	ds_read_b128 v[212:215], v154 offset:3072
	ds_read_b128 v[216:219], v154 offset:4096
	ds_read_b128 v[220:223], v154 offset:5120
	ds_read_b128 v[224:227], v154 offset:6144
	ds_read_b128 v[228:231], v154 offset:7168
	global_load_lds_dwordx4 v[232:233], off
	v_lshl_add_u64 v[232:233], s[0:1], 0, v[138:139]
	s_mov_b32 m0, s95
	s_nop 0
	global_load_lds_dwordx4 v[232:233], off
	s_waitcnt vmcnt(8)
	s_waitcnt lgkmcnt(0)
	s_barrier
	s_setprio 1
	s_waitcnt lgkmcnt(0)
	v_mfma_f32_16x16x32_bf16 v[124:127], v[144:147], v[200:203], 0
	v_mfma_f32_16x16x32_bf16 v[120:123], v[176:179], v[200:203], 0
	v_mfma_f32_16x16x32_bf16 v[108:111], v[144:147], v[208:211], 0
	v_mfma_f32_16x16x32_bf16 v[104:107], v[176:179], v[208:211], 0
	v_mfma_f32_16x16x32_bf16 v[92:95], v[144:147], v[216:219], 0
	v_mfma_f32_16x16x32_bf16 v[88:91], v[176:179], v[216:219], 0
	v_mfma_f32_16x16x32_bf16 v[76:79], v[144:147], v[224:227], 0
	v_mfma_f32_16x16x32_bf16 v[72:75], v[176:179], v[224:227], 0
	v_mfma_f32_16x16x32_bf16 v[124:127], v[148:151], v[204:207], v[124:127]
	v_mfma_f32_16x16x32_bf16 v[120:123], v[180:183], v[204:207], v[120:123]
	v_mfma_f32_16x16x32_bf16 v[108:111], v[148:151], v[212:215], v[108:111]
	v_mfma_f32_16x16x32_bf16 v[104:107], v[180:183], v[212:215], v[104:107]
	v_mfma_f32_16x16x32_bf16 v[92:95], v[148:151], v[220:223], v[92:95]
	v_mfma_f32_16x16x32_bf16 v[88:91], v[180:183], v[220:223], v[88:91]
	v_mfma_f32_16x16x32_bf16 v[76:79], v[148:151], v[228:231], v[76:79]
	v_mfma_f32_16x16x32_bf16 v[72:75], v[180:183], v[228:231], v[72:75]
	s_setprio 0
	s_setprio 1
	v_mfma_f32_16x16x32_bf16 v[116:119], v[184:187], v[200:203], 0
	v_mfma_f32_16x16x32_bf16 v[112:115], v[192:195], v[200:203], 0
	v_mfma_f32_16x16x32_bf16 v[100:103], v[184:187], v[208:211], 0
	v_mfma_f32_16x16x32_bf16 v[96:99], v[192:195], v[208:211], 0
	v_mfma_f32_16x16x32_bf16 v[84:87], v[184:187], v[216:219], 0
	v_mfma_f32_16x16x32_bf16 v[80:83], v[192:195], v[216:219], 0
	v_mfma_f32_16x16x32_bf16 v[68:71], v[184:187], v[224:227], 0
	v_mfma_f32_16x16x32_bf16 v[64:67], v[192:195], v[224:227], 0
	v_mfma_f32_16x16x32_bf16 v[116:119], v[188:191], v[204:207], v[116:119]
	v_mfma_f32_16x16x32_bf16 v[112:115], v[196:199], v[204:207], v[112:115]
	v_mfma_f32_16x16x32_bf16 v[100:103], v[188:191], v[212:215], v[100:103]
	v_mfma_f32_16x16x32_bf16 v[96:99], v[196:199], v[212:215], v[96:99]
	v_mfma_f32_16x16x32_bf16 v[84:87], v[188:191], v[220:223], v[84:87]
	v_mfma_f32_16x16x32_bf16 v[80:83], v[196:199], v[220:223], v[80:83]
	v_mfma_f32_16x16x32_bf16 v[68:71], v[188:191], v[228:231], v[68:71]
	v_mfma_f32_16x16x32_bf16 v[64:67], v[196:199], v[228:231], v[64:67]
	s_setprio 0
	s_barrier
	s_mov_b32 m0, s20
	v_lshl_add_u64 v[232:233], s[52:53], 0, v[130:131]
	v_lshl_add_u64 v[234:235], s[52:53], 0, v[134:135]
	s_add_u32 s52, s52, s36
	ds_read_b128 v[200:203], v154 offset:16384
	ds_read_b128 v[204:207], v154 offset:17408
	ds_read_b128 v[208:211], v154 offset:18432
	ds_read_b128 v[212:215], v154 offset:19456
	ds_read_b128 v[216:219], v154 offset:20480
	ds_read_b128 v[220:223], v154 offset:21504
	ds_read_b128 v[224:227], v154 offset:22528
	ds_read_b128 v[228:231], v154 offset:23552
	global_load_lds_dwordx4 v[232:233], off
	s_mov_b32 m0, s21
	s_addc_u32 s53, s53, s37
	global_load_lds_dwordx4 v[234:235], off
	v_lshl_add_u64 v[236:237], s[52:53], 0, v[130:131]
	s_mov_b32 m0, s28
	v_lshl_add_u64 v[238:239], s[52:53], 0, v[134:135]
	global_load_lds_dwordx4 v[236:237], off
	s_mov_b32 m0, s29
	v_lshl_add_u64 v[240:241], s[8:9], 0, v[128:129]
	global_load_lds_dwordx4 v[238:239], off
	s_mov_b32 m0, s3
	v_lshl_add_u64 v[242:243], s[8:9], 0, v[132:133]
	global_load_lds_dwordx4 v[240:241], off
	s_mov_b32 m0, s30
	s_nop 0
	global_load_lds_dwordx4 v[242:243], off
	s_waitcnt vmcnt(8)
	s_waitcnt lgkmcnt(0)
	s_barrier
	s_setprio 1
	s_waitcnt lgkmcnt(0)
	v_mfma_f32_16x16x32_bf16 v[60:63], v[144:147], v[200:203], 0
	v_mfma_f32_16x16x32_bf16 v[56:59], v[176:179], v[200:203], 0
	v_mfma_f32_16x16x32_bf16 v[44:47], v[144:147], v[208:211], 0
	v_mfma_f32_16x16x32_bf16 v[40:43], v[176:179], v[208:211], 0
	v_mfma_f32_16x16x32_bf16 v[28:31], v[144:147], v[216:219], 0
	v_mfma_f32_16x16x32_bf16 v[24:27], v[176:179], v[216:219], 0
	v_mfma_f32_16x16x32_bf16 v[12:15], v[144:147], v[224:227], 0
	v_mfma_f32_16x16x32_bf16 v[8:11], v[176:179], v[224:227], 0
	v_mfma_f32_16x16x32_bf16 v[60:63], v[148:151], v[204:207], v[60:63]
	v_mfma_f32_16x16x32_bf16 v[56:59], v[180:183], v[204:207], v[56:59]
	v_mfma_f32_16x16x32_bf16 v[44:47], v[148:151], v[212:215], v[44:47]
	v_mfma_f32_16x16x32_bf16 v[40:43], v[180:183], v[212:215], v[40:43]
	v_mfma_f32_16x16x32_bf16 v[28:31], v[148:151], v[220:223], v[28:31]
	v_mfma_f32_16x16x32_bf16 v[24:27], v[180:183], v[220:223], v[24:27]
	v_mfma_f32_16x16x32_bf16 v[12:15], v[148:151], v[228:231], v[12:15]
	v_mfma_f32_16x16x32_bf16 v[8:11], v[180:183], v[228:231], v[8:11]
	s_setprio 0
	s_setprio 1
	v_mfma_f32_16x16x32_bf16 v[52:55], v[184:187], v[200:203], 0
	v_mfma_f32_16x16x32_bf16 v[48:51], v[192:195], v[200:203], 0
	v_mfma_f32_16x16x32_bf16 v[36:39], v[184:187], v[208:211], 0
	v_mfma_f32_16x16x32_bf16 v[32:35], v[192:195], v[208:211], 0
	v_mfma_f32_16x16x32_bf16 v[20:23], v[184:187], v[216:219], 0
	v_mfma_f32_16x16x32_bf16 v[16:19], v[192:195], v[216:219], 0
	v_mfma_f32_16x16x32_bf16 v[4:7], v[184:187], v[224:227], 0
	v_mfma_f32_16x16x32_bf16 v[0:3], v[192:195], v[224:227], 0
	v_mfma_f32_16x16x32_bf16 v[52:55], v[188:191], v[204:207], v[52:55]
	v_mfma_f32_16x16x32_bf16 v[48:51], v[196:199], v[204:207], v[48:51]
	v_mfma_f32_16x16x32_bf16 v[36:39], v[188:191], v[212:215], v[36:39]
	v_mfma_f32_16x16x32_bf16 v[32:35], v[196:199], v[212:215], v[32:35]
	v_mfma_f32_16x16x32_bf16 v[20:23], v[188:191], v[220:223], v[20:23]
	v_mfma_f32_16x16x32_bf16 v[16:19], v[196:199], v[220:223], v[16:19]
	v_mfma_f32_16x16x32_bf16 v[4:7], v[188:191], v[228:231], v[4:7]
	v_mfma_f32_16x16x32_bf16 v[0:3], v[196:199], v[228:231], v[0:3]
	s_setprio 0
	s_barrier
	ds_read_b128 v[144:147], v165
	ds_read_b128 v[148:151], v166
	ds_read_b128 v[176:179], v167
	ds_read_b128 v[180:183], v168
	ds_read_b128 v[184:187], v169
	ds_read_b128 v[188:191], v170
	ds_read_b128 v[192:195], v171
	ds_read_b128 v[196:199], v172
	s_add_u32 s8, s8, s26
	s_addc_u32 s9, s9, s27
	s_mov_b32 m0, s31
	v_lshl_add_u64 v[244:245], s[8:9], 0, v[128:129]
	ds_read_b128 v[200:203], v154 offset:32768
	ds_read_b128 v[204:207], v154 offset:33792
	ds_read_b128 v[208:211], v154 offset:34816
	ds_read_b128 v[212:215], v154 offset:35840
	ds_read_b128 v[216:219], v154 offset:36864
	ds_read_b128 v[220:223], v154 offset:37888
	ds_read_b128 v[224:227], v154 offset:38912
	ds_read_b128 v[228:231], v154 offset:39936
	global_load_lds_dwordx4 v[244:245], off
	v_lshl_add_u64 v[244:245], s[8:9], 0, v[132:133]
	s_mov_b32 m0, s33
	s_nop 0
	global_load_lds_dwordx4 v[244:245], off
	s_waitcnt vmcnt(8)
	s_waitcnt lgkmcnt(0)
	s_barrier
	s_setprio 1
	s_waitcnt lgkmcnt(0)
	v_mfma_f32_16x16x32_bf16 v[124:127], v[144:147], v[200:203], v[124:127]
	v_mfma_f32_16x16x32_bf16 v[120:123], v[176:179], v[200:203], v[120:123]
	v_mfma_f32_16x16x32_bf16 v[108:111], v[144:147], v[208:211], v[108:111]
	v_mfma_f32_16x16x32_bf16 v[104:107], v[176:179], v[208:211], v[104:107]
	v_mfma_f32_16x16x32_bf16 v[92:95], v[144:147], v[216:219], v[92:95]
	v_mfma_f32_16x16x32_bf16 v[88:91], v[176:179], v[216:219], v[88:91]
	v_mfma_f32_16x16x32_bf16 v[76:79], v[144:147], v[224:227], v[76:79]
	v_mfma_f32_16x16x32_bf16 v[72:75], v[176:179], v[224:227], v[72:75]
	v_mfma_f32_16x16x32_bf16 v[124:127], v[148:151], v[204:207], v[124:127]
	v_mfma_f32_16x16x32_bf16 v[120:123], v[180:183], v[204:207], v[120:123]
	v_mfma_f32_16x16x32_bf16 v[108:111], v[148:151], v[212:215], v[108:111]
	v_mfma_f32_16x16x32_bf16 v[104:107], v[180:183], v[212:215], v[104:107]
	v_mfma_f32_16x16x32_bf16 v[92:95], v[148:151], v[220:223], v[92:95]
	v_mfma_f32_16x16x32_bf16 v[88:91], v[180:183], v[220:223], v[88:91]
	v_mfma_f32_16x16x32_bf16 v[76:79], v[148:151], v[228:231], v[76:79]
	v_mfma_f32_16x16x32_bf16 v[72:75], v[180:183], v[228:231], v[72:75]
	s_setprio 0
	s_setprio 1
	v_mfma_f32_16x16x32_bf16 v[116:119], v[184:187], v[200:203], v[116:119]
	v_mfma_f32_16x16x32_bf16 v[112:115], v[192:195], v[200:203], v[112:115]
	v_mfma_f32_16x16x32_bf16 v[100:103], v[184:187], v[208:211], v[100:103]
	v_mfma_f32_16x16x32_bf16 v[96:99], v[192:195], v[208:211], v[96:99]
	v_mfma_f32_16x16x32_bf16 v[84:87], v[184:187], v[216:219], v[84:87]
	v_mfma_f32_16x16x32_bf16 v[80:83], v[192:195], v[216:219], v[80:83]
	v_mfma_f32_16x16x32_bf16 v[68:71], v[184:187], v[224:227], v[68:71]
	v_mfma_f32_16x16x32_bf16 v[64:67], v[192:195], v[224:227], v[64:67]
	v_mfma_f32_16x16x32_bf16 v[116:119], v[188:191], v[204:207], v[116:119]
	v_mfma_f32_16x16x32_bf16 v[112:115], v[196:199], v[204:207], v[112:115]
	v_mfma_f32_16x16x32_bf16 v[100:103], v[188:191], v[212:215], v[100:103]
	v_mfma_f32_16x16x32_bf16 v[96:99], v[196:199], v[212:215], v[96:99]
	v_mfma_f32_16x16x32_bf16 v[84:87], v[188:191], v[220:223], v[84:87]
	v_mfma_f32_16x16x32_bf16 v[80:83], v[196:199], v[220:223], v[80:83]
	v_mfma_f32_16x16x32_bf16 v[68:71], v[188:191], v[228:231], v[68:71]
	v_mfma_f32_16x16x32_bf16 v[64:67], v[196:199], v[228:231], v[64:67]
	s_setprio 0
	s_barrier
	s_mov_b32 m0, s34
	v_lshl_add_u64 v[232:233], v[232:233], 0, s[66:67]
	ds_read_b128 v[200:203], v154 offset:49152
	ds_read_b128 v[204:207], v154 offset:50176
	ds_read_b128 v[208:211], v154 offset:51200
	ds_read_b128 v[212:215], v154 offset:52224
	ds_read_b128 v[216:219], v154 offset:53248
	ds_read_b128 v[220:223], v154 offset:54272
	ds_read_b128 v[224:227], v154 offset:55296
	ds_read_b128 v[228:231], v154 offset:56320
	global_load_lds_dwordx4 v[232:233], off
	v_lshl_add_u64 v[232:233], v[234:235], 0, s[66:67]
	s_mov_b32 m0, s35
	s_nop 0
	global_load_lds_dwordx4 v[232:233], off
	v_lshl_add_u64 v[232:233], v[236:237], 0, s[66:67]
	s_mov_b32 m0, s82
	s_nop 0
	global_load_lds_dwordx4 v[232:233], off
	v_lshl_add_u64 v[232:233], v[238:239], 0, s[66:67]
	s_mov_b32 m0, s83
	s_nop 0
	global_load_lds_dwordx4 v[232:233], off
	v_lshl_add_u64 v[232:233], v[240:241], 0, s[66:67]
	s_mov_b32 m0, s80
	s_nop 0
	global_load_lds_dwordx4 v[232:233], off
	v_lshl_add_u64 v[232:233], v[242:243], 0, s[66:67]
	s_mov_b32 m0, s81
	s_nop 0
	global_load_lds_dwordx4 v[232:233], off
	s_waitcnt vmcnt(8)
	s_waitcnt lgkmcnt(0)
	s_barrier
	s_setprio 1
	s_waitcnt lgkmcnt(0)
	v_mfma_f32_16x16x32_bf16 v[60:63], v[144:147], v[200:203], v[60:63]
	v_mfma_f32_16x16x32_bf16 v[56:59], v[176:179], v[200:203], v[56:59]
	v_mfma_f32_16x16x32_bf16 v[44:47], v[144:147], v[208:211], v[44:47]
	v_mfma_f32_16x16x32_bf16 v[40:43], v[176:179], v[208:211], v[40:43]
	v_mfma_f32_16x16x32_bf16 v[28:31], v[144:147], v[216:219], v[28:31]
	v_mfma_f32_16x16x32_bf16 v[24:27], v[176:179], v[216:219], v[24:27]
	v_mfma_f32_16x16x32_bf16 v[12:15], v[144:147], v[224:227], v[12:15]
	v_mfma_f32_16x16x32_bf16 v[8:11], v[176:179], v[224:227], v[8:11]
	v_mfma_f32_16x16x32_bf16 v[60:63], v[148:151], v[204:207], v[60:63]
	v_mfma_f32_16x16x32_bf16 v[56:59], v[180:183], v[204:207], v[56:59]
	v_mfma_f32_16x16x32_bf16 v[44:47], v[148:151], v[212:215], v[44:47]
	v_mfma_f32_16x16x32_bf16 v[40:43], v[180:183], v[212:215], v[40:43]
	v_mfma_f32_16x16x32_bf16 v[28:31], v[148:151], v[220:223], v[28:31]
	v_mfma_f32_16x16x32_bf16 v[24:27], v[180:183], v[220:223], v[24:27]
	v_mfma_f32_16x16x32_bf16 v[12:15], v[148:151], v[228:231], v[12:15]
	v_mfma_f32_16x16x32_bf16 v[8:11], v[180:183], v[228:231], v[8:11]
	s_setprio 0
	s_setprio 1
	v_mfma_f32_16x16x32_bf16 v[52:55], v[184:187], v[200:203], v[52:55]
	v_mfma_f32_16x16x32_bf16 v[48:51], v[192:195], v[200:203], v[48:51]
	v_mfma_f32_16x16x32_bf16 v[36:39], v[184:187], v[208:211], v[36:39]
	v_mfma_f32_16x16x32_bf16 v[32:35], v[192:195], v[208:211], v[32:35]
	v_mfma_f32_16x16x32_bf16 v[20:23], v[184:187], v[216:219], v[20:23]
	v_mfma_f32_16x16x32_bf16 v[16:19], v[192:195], v[216:219], v[16:19]
	v_mfma_f32_16x16x32_bf16 v[4:7], v[184:187], v[224:227], v[4:7]
	v_mfma_f32_16x16x32_bf16 v[0:3], v[192:195], v[224:227], v[0:3]
	v_mfma_f32_16x16x32_bf16 v[52:55], v[188:191], v[204:207], v[52:55]
	v_mfma_f32_16x16x32_bf16 v[48:51], v[196:199], v[204:207], v[48:51]
	v_mfma_f32_16x16x32_bf16 v[36:39], v[188:191], v[212:215], v[36:39]
	v_mfma_f32_16x16x32_bf16 v[32:35], v[196:199], v[212:215], v[32:35]
	v_mfma_f32_16x16x32_bf16 v[20:23], v[188:191], v[220:223], v[20:23]
	v_mfma_f32_16x16x32_bf16 v[16:19], v[196:199], v[220:223], v[16:19]
	v_mfma_f32_16x16x32_bf16 v[4:7], v[188:191], v[228:231], v[4:7]
	v_mfma_f32_16x16x32_bf16 v[0:3], v[196:199], v[228:231], v[0:3]
	s_setprio 0
	s_barrier
	s_add_u32 s0, s0, 0x100
	s_addc_u32 s1, s1, 0
	s_add_u32 s10, s10, 0x100
	s_addc_u32 s11, s11, 0
	s_cmp_ge_i32 s14, s84
	s_mov_b32 s8, s14
	s_cbranch_scc1 .Lkx_4

.LBB0_1273:
	s_add_i32 s68, s21, 0x18000
	s_mov_b64 s[26:27], 0x80
	v_lshl_add_u64 v[8:9], v[8:9], 0, s[26:27]
	s_mov_b32 m0, s68
	s_add_i32 s69, s21, 0x1a000
	s_waitcnt vmcnt(2)
	s_mov_b32 s99, 0
	s_barrier
	global_load_lds_dwordx4 v[8:9], off
	v_lshl_add_u64 v[4:5], v[4:5], 0, s[26:27]
	s_mov_b32 m0, s69
	s_add_i32 s70, s21, 0x8000
	global_load_lds_dwordx4 v[4:5], off
	v_lshl_add_u64 v[4:5], v[6:7], 0, s[26:27]
	s_mov_b32 m0, s70
	s_add_i32 s71, s21, 0xa000
	global_load_lds_dwordx4 v[4:5], off
	v_lshl_add_u64 v[4:5], v[10:11], 0, s[26:27]
	s_mov_b32 m0, s71
	s_add_i32 s72, s21, 0x1c000
	global_load_lds_dwordx4 v[4:5], off
	v_lshl_add_u64 v[2:3], v[2:3], 0, s[26:27]
	s_mov_b32 m0, s72
	s_add_i32 s73, s21, 0x1e000
	global_load_lds_dwordx4 v[2:3], off
	v_lshl_add_u64 v[0:1], v[0:1], 0, s[26:27]
	s_mov_b32 m0, s73
	s_ashr_i32 s6, s36, 31
	global_load_lds_dwordx4 v[0:1], off
	v_bfe_u32 v145, v12, 4, 2
	s_lshr_b32 s6, s6, 26
	v_and_b32_e32 v144, 15, v12
	s_add_i32 s6, s36, s6
	v_lshlrev_b32_e32 v0, 4, v145
	v_lshlrev_b32_e32 v1, 2, v12
	s_ashr_i32 s74, s6, 6
	v_lshl_or_b32 v0, v144, 6, v0
	s_lshl_b32 s6, s37, 13
	v_and_b32_e32 v1, 32, v1
	v_bitop3_b32 v146, v0, s6, v1 bitop3:0xde
	s_lshl_b32 s6, s43, 5
	s_and_b32 s8, s6, 0x60
	s_lshl_b32 s75, s37, 6
	s_lshl_b32 s6, s8, 7
	v_bitop3_b32 v2, v0, s6, v1 bitop3:0xde
	s_cmp_gt_i32 s36, 63
	v_add_u32_e32 v0, v15, v13
	s_cselect_b64 s[6:7], -1, 0
	s_cmpk_lt_i32 s2, 0x80
	v_add_lshl_u32 v0, v0, v14, 1
	v_mov_b32_e32 v1, v131
	s_cselect_b64 s[36:37], -1, 0
	s_lshl_b32 s76, s2, 2
	v_lshl_add_u64 v[136:137], s[0:1], 0, v[0:1]
	v_add_u32_e32 v0, v18, v16
	s_waitcnt vmcnt(6)
	s_addk_i32 s76, 0xfe00
	s_add_i32 s77, s74, -2
	v_add_lshl_u32 v0, v0, v17, 1
	s_cmpk_lt_u32 s42, 0x100
	s_mov_b32 s47, 0
	v_lshl_add_u64 v[138:139], s[0:1], 0, v[0:1]
	v_cndmask_b32_e64 v0, 0, 1, s[6:7]
	s_cselect_b64 s[42:43], -1, 0
	v_cmp_ne_u32_e64 s[6:7], 1, v0
	v_or_b32_e32 v147, 0x10000, v2
	v_add_u32_e32 v148, 0x10400, v2
	v_add_u32_e32 v149, 0x10800, v2
	v_add_u32_e32 v150, 0x10c00, v2
	v_or_b32_e32 v151, 0x14000, v2
	v_add_u32_e32 v152, 0x14400, v2
	v_add_u32_e32 v153, 0x14800, v2
	v_add_u32_e32 v154, 0x14c00, v2
	s_add_i32 s80, s21, 0xc000
	s_add_i32 s81, s21, 0xe000
	v_or_b32_e32 v155, 0x18000, v2
	v_add_u32_e32 v156, 0x18400, v2
	v_add_u32_e32 v157, 0x18800, v2
	v_add_u32_e32 v158, 0x18c00, v2
	v_or_b32_e32 v159, 0x1c000, v2
	v_add_u32_e32 v160, 0x1c400, v2
	v_add_u32_e32 v161, 0x1c800, v2
	v_add_u32_e32 v164, 0x1cc00, v2
	v_mov_b32_e32 v165, 0x358637bd
	s_mov_b32 s82, 0x800000
	s_lshl_b32 s46, s8, 1
	s_mov_b32 s51, s47
	s_barrier
	s_branch .LBB0_1276

.Lkp_5:
	s_add_u32 s52, s90, 0x80
	s_addc_u32 s53, s91, 0
	s_add_u32 s90, s78, 0x100
	s_addc_u32 s91, s79, 0
	s_mov_b32 s66, 0
	ds_read_b128 v[140:143], v147
	ds_read_b128 v[166:169], v148
	ds_read_b128 v[170:173], v149
	ds_read_b128 v[174:177], v150
	ds_read_b128 v[178:181], v151
	ds_read_b128 v[182:185], v152
	ds_read_b128 v[186:189], v153
	ds_read_b128 v[190:193], v154
	s_add_i32 s92, s66, 2
	s_add_u32 s54, s52, 0x80
	s_addc_u32 s55, s53, 0
	s_cmp_eq_u32 s77, s66
	s_cselect_b32 s66, s48, s54
	s_cselect_b32 s67, s49, s55
	s_cselect_b32 s55, s51, s91
	s_cselect_b32 s54, s50, s90
	s_mov_b32 m0, s80
	v_lshl_add_u64 v[226:227], s[52:53], 0, v[136:137]
	ds_read_b128 v[194:197], v146
	ds_read_b128 v[198:201], v146 offset:1024
	ds_read_b128 v[202:205], v146 offset:2048
	ds_read_b128 v[206:209], v146 offset:3072
	ds_read_b128 v[210:213], v146 offset:4096
	ds_read_b128 v[214:217], v146 offset:5120
	ds_read_b128 v[218:221], v146 offset:6144
	ds_read_b128 v[222:225], v146 offset:7168
	global_load_lds_dwordx4 v[226:227], off
	v_lshl_add_u64 v[226:227], s[52:53], 0, v[138:139]
	s_mov_b32 m0, s81
	s_nop 0
	global_load_lds_dwordx4 v[226:227], off
	s_cmp_lg_u32 s99, 0
	s_cbranch_scc1 .Lsw_5_0
	s_waitcnt vmcnt(8)
.Lsw_5_0:
	s_waitcnt vmcnt(24)
	s_waitcnt lgkmcnt(0)
	s_barrier
	s_setprio 1
	s_waitcnt lgkmcnt(0)
	v_mfma_f32_16x16x32_bf16 v[124:127], v[140:143], v[194:197], 0
	v_mfma_f32_16x16x32_bf16 v[120:123], v[170:173], v[194:197], 0
	v_mfma_f32_16x16x32_bf16 v[108:111], v[140:143], v[202:205], 0
	v_mfma_f32_16x16x32_bf16 v[104:107], v[170:173], v[202:205], 0
	v_mfma_f32_16x16x32_bf16 v[92:95], v[140:143], v[210:213], 0
	v_mfma_f32_16x16x32_bf16 v[88:91], v[170:173], v[210:213], 0
	v_mfma_f32_16x16x32_bf16 v[76:79], v[140:143], v[218:221], 0
	v_mfma_f32_16x16x32_bf16 v[72:75], v[170:173], v[218:221], 0
	v_mfma_f32_16x16x32_bf16 v[124:127], v[166:169], v[198:201], v[124:127]
	v_mfma_f32_16x16x32_bf16 v[120:123], v[174:177], v[198:201], v[120:123]
	v_mfma_f32_16x16x32_bf16 v[108:111], v[166:169], v[206:209], v[108:111]
	v_mfma_f32_16x16x32_bf16 v[104:107], v[174:177], v[206:209], v[104:107]
	v_mfma_f32_16x16x32_bf16 v[92:95], v[166:169], v[214:217], v[92:95]
	v_mfma_f32_16x16x32_bf16 v[88:91], v[174:177], v[214:217], v[88:91]
	v_mfma_f32_16x16x32_bf16 v[76:79], v[166:169], v[222:225], v[76:79]
	v_mfma_f32_16x16x32_bf16 v[72:75], v[174:177], v[222:225], v[72:75]
	s_setprio 0
	s_setprio 1
	v_mfma_f32_16x16x32_bf16 v[116:119], v[178:181], v[194:197], 0
	v_mfma_f32_16x16x32_bf16 v[112:115], v[186:189], v[194:197], 0
	v_mfma_f32_16x16x32_bf16 v[100:103], v[178:181], v[202:205], 0
	v_mfma_f32_16x16x32_bf16 v[96:99], v[186:189], v[202:205], 0
	v_mfma_f32_16x16x32_bf16 v[84:87], v[178:181], v[210:213], 0
	v_mfma_f32_16x16x32_bf16 v[80:83], v[186:189], v[210:213], 0
	v_mfma_f32_16x16x32_bf16 v[68:71], v[178:181], v[218:221], 0
	v_mfma_f32_16x16x32_bf16 v[64:67], v[186:189], v[218:221], 0
	v_mfma_f32_16x16x32_bf16 v[116:119], v[182:185], v[198:201], v[116:119]
	v_mfma_f32_16x16x32_bf16 v[112:115], v[190:193], v[198:201], v[112:115]
	v_mfma_f32_16x16x32_bf16 v[100:103], v[182:185], v[206:209], v[100:103]
	v_mfma_f32_16x16x32_bf16 v[96:99], v[190:193], v[206:209], v[96:99]
	v_mfma_f32_16x16x32_bf16 v[84:87], v[182:185], v[214:217], v[84:87]
	v_mfma_f32_16x16x32_bf16 v[80:83], v[190:193], v[214:217], v[80:83]
	v_mfma_f32_16x16x32_bf16 v[68:71], v[182:185], v[222:225], v[68:71]
	v_mfma_f32_16x16x32_bf16 v[64:67], v[190:193], v[222:225], v[64:67]
	s_setprio 0
	s_barrier
	s_mov_b32 m0, s28
	v_lshl_add_u64 v[226:227], s[54:55], 0, v[130:131]
	v_lshl_add_u64 v[228:229], s[54:55], 0, v[134:135]
	s_add_u32 s54, s54, s10
	ds_read_b128 v[194:197], v146 offset:16384
	ds_read_b128 v[198:201], v146 offset:17408
	ds_read_b128 v[202:205], v146 offset:18432
	ds_read_b128 v[206:209], v146 offset:19456
	ds_read_b128 v[210:213], v146 offset:20480
	ds_read_b128 v[214:217], v146 offset:21504
	ds_read_b128 v[218:221], v146 offset:22528
	ds_read_b128 v[222:225], v146 offset:23552
	global_load_lds_dwordx4 v[226:227], off
	s_mov_b32 m0, s29
	s_addc_u32 s55, s55, s11
	global_load_lds_dwordx4 v[228:229], off
	v_lshl_add_u64 v[230:231], s[54:55], 0, v[130:131]
	s_mov_b32 m0, s30
	v_lshl_add_u64 v[232:233], s[54:55], 0, v[134:135]
	global_load_lds_dwordx4 v[230:231], off
	s_mov_b32 m0, s31
	v_lshl_add_u64 v[234:235], s[66:67], 0, v[128:129]
	global_load_lds_dwordx4 v[232:233], off
	s_mov_b32 m0, s21
	v_lshl_add_u64 v[236:237], s[66:67], 0, v[132:133]
	global_load_lds_dwordx4 v[234:235], off
	s_mov_b32 m0, s33
	s_nop 0
	global_load_lds_dwordx4 v[236:237], off
	s_cmp_lg_u32 s99, 0
	s_cbranch_scc1 .Lsw_5_1
	s_waitcnt vmcnt(8)
.Lsw_5_1:
	s_waitcnt vmcnt(24)
	s_waitcnt lgkmcnt(0)
	s_barrier
	s_setprio 1
	s_waitcnt lgkmcnt(0)
	v_mfma_f32_16x16x32_bf16 v[60:63], v[140:143], v[194:197], 0
	v_mfma_f32_16x16x32_bf16 v[56:59], v[170:173], v[194:197], 0
	v_mfma_f32_16x16x32_bf16 v[44:47], v[140:143], v[202:205], 0
	v_mfma_f32_16x16x32_bf16 v[40:43], v[170:173], v[202:205], 0
	v_mfma_f32_16x16x32_bf16 v[28:31], v[140:143], v[210:213], 0
	v_mfma_f32_16x16x32_bf16 v[24:27], v[170:173], v[210:213], 0
	v_mfma_f32_16x16x32_bf16 v[12:15], v[140:143], v[218:221], 0
	v_mfma_f32_16x16x32_bf16 v[8:11], v[170:173], v[218:221], 0
	v_mfma_f32_16x16x32_bf16 v[60:63], v[166:169], v[198:201], v[60:63]
	v_mfma_f32_16x16x32_bf16 v[56:59], v[174:177], v[198:201], v[56:59]
	v_mfma_f32_16x16x32_bf16 v[44:47], v[166:169], v[206:209], v[44:47]
	v_mfma_f32_16x16x32_bf16 v[40:43], v[174:177], v[206:209], v[40:43]
	v_mfma_f32_16x16x32_bf16 v[28:31], v[166:169], v[214:217], v[28:31]
	v_mfma_f32_16x16x32_bf16 v[24:27], v[174:177], v[214:217], v[24:27]
	v_mfma_f32_16x16x32_bf16 v[12:15], v[166:169], v[222:225], v[12:15]
	v_mfma_f32_16x16x32_bf16 v[8:11], v[174:177], v[222:225], v[8:11]
	s_setprio 0
	s_setprio 1
	v_mfma_f32_16x16x32_bf16 v[52:55], v[178:181], v[194:197], 0
	v_mfma_f32_16x16x32_bf16 v[48:51], v[186:189], v[194:197], 0
	v_mfma_f32_16x16x32_bf16 v[36:39], v[178:181], v[202:205], 0
	v_mfma_f32_16x16x32_bf16 v[32:35], v[186:189], v[202:205], 0
	v_mfma_f32_16x16x32_bf16 v[20:23], v[178:181], v[210:213], 0
	v_mfma_f32_16x16x32_bf16 v[16:19], v[186:189], v[210:213], 0
	v_mfma_f32_16x16x32_bf16 v[4:7], v[178:181], v[218:221], 0
	v_mfma_f32_16x16x32_bf16 v[0:3], v[186:189], v[218:221], 0
	v_mfma_f32_16x16x32_bf16 v[52:55], v[182:185], v[198:201], v[52:55]
	v_mfma_f32_16x16x32_bf16 v[48:51], v[190:193], v[198:201], v[48:51]
	v_mfma_f32_16x16x32_bf16 v[36:39], v[182:185], v[206:209], v[36:39]
	v_mfma_f32_16x16x32_bf16 v[32:35], v[190:193], v[206:209], v[32:35]
	v_mfma_f32_16x16x32_bf16 v[20:23], v[182:185], v[214:217], v[20:23]
	v_mfma_f32_16x16x32_bf16 v[16:19], v[190:193], v[214:217], v[16:19]
	v_mfma_f32_16x16x32_bf16 v[4:7], v[182:185], v[222:225], v[4:7]
	v_mfma_f32_16x16x32_bf16 v[0:3], v[190:193], v[222:225], v[0:3]
	s_setprio 0
	s_barrier
	ds_read_b128 v[140:143], v155
	ds_read_b128 v[166:169], v156
	ds_read_b128 v[170:173], v157
	ds_read_b128 v[174:177], v158
	ds_read_b128 v[178:181], v159
	ds_read_b128 v[182:185], v160
	ds_read_b128 v[186:189], v161
	ds_read_b128 v[190:193], v164
	s_add_u32 s54, s66, s0
	s_addc_u32 s55, s67, s1
	s_mov_b32 m0, s34
	v_lshl_add_u64 v[238:239], s[54:55], 0, v[128:129]
	ds_read_b128 v[194:197], v146 offset:32768
	ds_read_b128 v[198:201], v146 offset:33792
	ds_read_b128 v[202:205], v146 offset:34816
	ds_read_b128 v[206:209], v146 offset:35840
	ds_read_b128 v[210:213], v146 offset:36864
	ds_read_b128 v[214:217], v146 offset:37888
	ds_read_b128 v[218:221], v146 offset:38912
	ds_read_b128 v[222:225], v146 offset:39936
	global_load_lds_dwordx4 v[238:239], off
	v_lshl_add_u64 v[238:239], s[54:55], 0, v[132:133]
	s_mov_b32 m0, s35
	s_nop 0
	global_load_lds_dwordx4 v[238:239], off
	s_waitcnt vmcnt(8)
	s_waitcnt lgkmcnt(0)
	s_barrier
	s_setprio 1
	s_waitcnt lgkmcnt(0)
	v_mfma_f32_16x16x32_bf16 v[124:127], v[140:143], v[194:197], v[124:127]
	v_mfma_f32_16x16x32_bf16 v[120:123], v[170:173], v[194:197], v[120:123]
	v_mfma_f32_16x16x32_bf16 v[108:111], v[140:143], v[202:205], v[108:111]
	v_mfma_f32_16x16x32_bf16 v[104:107], v[170:173], v[202:205], v[104:107]
	v_mfma_f32_16x16x32_bf16 v[92:95], v[140:143], v[210:213], v[92:95]
	v_mfma_f32_16x16x32_bf16 v[88:91], v[170:173], v[210:213], v[88:91]
	v_mfma_f32_16x16x32_bf16 v[76:79], v[140:143], v[218:221], v[76:79]
	v_mfma_f32_16x16x32_bf16 v[72:75], v[170:173], v[218:221], v[72:75]
	v_mfma_f32_16x16x32_bf16 v[124:127], v[166:169], v[198:201], v[124:127]
	v_mfma_f32_16x16x32_bf16 v[120:123], v[174:177], v[198:201], v[120:123]
	v_mfma_f32_16x16x32_bf16 v[108:111], v[166:169], v[206:209], v[108:111]
	v_mfma_f32_16x16x32_bf16 v[104:107], v[174:177], v[206:209], v[104:107]
	v_mfma_f32_16x16x32_bf16 v[92:95], v[166:169], v[214:217], v[92:95]
	v_mfma_f32_16x16x32_bf16 v[88:91], v[174:177], v[214:217], v[88:91]
	v_mfma_f32_16x16x32_bf16 v[76:79], v[166:169], v[222:225], v[76:79]
	v_mfma_f32_16x16x32_bf16 v[72:75], v[174:177], v[222:225], v[72:75]
	s_setprio 0
	s_setprio 1
	v_mfma_f32_16x16x32_bf16 v[116:119], v[178:181], v[194:197], v[116:119]
	v_mfma_f32_16x16x32_bf16 v[112:115], v[186:189], v[194:197], v[112:115]
	v_mfma_f32_16x16x32_bf16 v[100:103], v[178:181], v[202:205], v[100:103]
	v_mfma_f32_16x16x32_bf16 v[96:99], v[186:189], v[202:205], v[96:99]
	v_mfma_f32_16x16x32_bf16 v[84:87], v[178:181], v[210:213], v[84:87]
	v_mfma_f32_16x16x32_bf16 v[80:83], v[186:189], v[210:213], v[80:83]
	v_mfma_f32_16x16x32_bf16 v[68:71], v[178:181], v[218:221], v[68:71]
	v_mfma_f32_16x16x32_bf16 v[64:67], v[186:189], v[218:221], v[64:67]
	v_mfma_f32_16x16x32_bf16 v[116:119], v[182:185], v[198:201], v[116:119]
	v_mfma_f32_16x16x32_bf16 v[112:115], v[190:193], v[198:201], v[112:115]
	v_mfma_f32_16x16x32_bf16 v[100:103], v[182:185], v[206:209], v[100:103]
	v_mfma_f32_16x16x32_bf16 v[96:99], v[190:193], v[206:209], v[96:99]
	v_mfma_f32_16x16x32_bf16 v[84:87], v[182:185], v[214:217], v[84:87]
	v_mfma_f32_16x16x32_bf16 v[80:83], v[190:193], v[214:217], v[80:83]
	v_mfma_f32_16x16x32_bf16 v[68:71], v[182:185], v[222:225], v[68:71]
	v_mfma_f32_16x16x32_bf16 v[64:67], v[190:193], v[222:225], v[64:67]
	s_setprio 0
	s_barrier
	s_mov_b32 m0, s68
	v_lshl_add_u64 v[226:227], v[226:227], 0, s[26:27]
	ds_read_b128 v[194:197], v146 offset:49152
	ds_read_b128 v[198:201], v146 offset:50176
	ds_read_b128 v[202:205], v146 offset:51200
	ds_read_b128 v[206:209], v146 offset:52224
	ds_read_b128 v[210:213], v146 offset:53248
	ds_read_b128 v[214:217], v146 offset:54272
	ds_read_b128 v[218:221], v146 offset:55296
	ds_read_b128 v[222:225], v146 offset:56320
	global_load_lds_dwordx4 v[226:227], off
	v_lshl_add_u64 v[226:227], v[228:229], 0, s[26:27]
	s_mov_b32 m0, s69
	s_nop 0
	global_load_lds_dwordx4 v[226:227], off
	v_lshl_add_u64 v[226:227], v[230:231], 0, s[26:27]
	s_mov_b32 m0, s72
	s_nop 0
	global_load_lds_dwordx4 v[226:227], off
	v_lshl_add_u64 v[226:227], v[232:233], 0, s[26:27]
	s_mov_b32 m0, s73
	s_nop 0
	global_load_lds_dwordx4 v[226:227], off
	v_lshl_add_u64 v[226:227], v[234:235], 0, s[26:27]
	s_mov_b32 m0, s70
	s_nop 0
	global_load_lds_dwordx4 v[226:227], off
	v_lshl_add_u64 v[226:227], v[236:237], 0, s[26:27]
	s_mov_b32 m0, s71
	s_nop 0
	global_load_lds_dwordx4 v[226:227], off
	s_waitcnt vmcnt(8)
	s_waitcnt lgkmcnt(0)
	s_barrier
	s_setprio 1
	s_waitcnt lgkmcnt(0)
	v_mfma_f32_16x16x32_bf16 v[60:63], v[140:143], v[194:197], v[60:63]
	v_mfma_f32_16x16x32_bf16 v[56:59], v[170:173], v[194:197], v[56:59]
	v_mfma_f32_16x16x32_bf16 v[44:47], v[140:143], v[202:205], v[44:47]
	v_mfma_f32_16x16x32_bf16 v[40:43], v[170:173], v[202:205], v[40:43]
	v_mfma_f32_16x16x32_bf16 v[28:31], v[140:143], v[210:213], v[28:31]
	v_mfma_f32_16x16x32_bf16 v[24:27], v[170:173], v[210:213], v[24:27]
	v_mfma_f32_16x16x32_bf16 v[12:15], v[140:143], v[218:221], v[12:15]
	v_mfma_f32_16x16x32_bf16 v[8:11], v[170:173], v[218:221], v[8:11]
	v_mfma_f32_16x16x32_bf16 v[60:63], v[166:169], v[198:201], v[60:63]
	v_mfma_f32_16x16x32_bf16 v[56:59], v[174:177], v[198:201], v[56:59]
	v_mfma_f32_16x16x32_bf16 v[44:47], v[166:169], v[206:209], v[44:47]
	v_mfma_f32_16x16x32_bf16 v[40:43], v[174:177], v[206:209], v[40:43]
	v_mfma_f32_16x16x32_bf16 v[28:31], v[166:169], v[214:217], v[28:31]
	v_mfma_f32_16x16x32_bf16 v[24:27], v[174:177], v[214:217], v[24:27]
	v_mfma_f32_16x16x32_bf16 v[12:15], v[166:169], v[222:225], v[12:15]
	v_mfma_f32_16x16x32_bf16 v[8:11], v[174:177], v[222:225], v[8:11]
	s_setprio 0
	s_setprio 1
	v_mfma_f32_16x16x32_bf16 v[52:55], v[178:181], v[194:197], v[52:55]
	v_mfma_f32_16x16x32_bf16 v[48:51], v[186:189], v[194:197], v[48:51]
	v_mfma_f32_16x16x32_bf16 v[36:39], v[178:181], v[202:205], v[36:39]
	v_mfma_f32_16x16x32_bf16 v[32:35], v[186:189], v[202:205], v[32:35]
	v_mfma_f32_16x16x32_bf16 v[20:23], v[178:181], v[210:213], v[20:23]
	v_mfma_f32_16x16x32_bf16 v[16:19], v[186:189], v[210:213], v[16:19]
	v_mfma_f32_16x16x32_bf16 v[4:7], v[178:181], v[218:221], v[4:7]
	v_mfma_f32_16x16x32_bf16 v[0:3], v[186:189], v[218:221], v[0:3]
	v_mfma_f32_16x16x32_bf16 v[52:55], v[182:185], v[198:201], v[52:55]
	v_mfma_f32_16x16x32_bf16 v[48:51], v[190:193], v[198:201], v[48:51]
	v_mfma_f32_16x16x32_bf16 v[36:39], v[182:185], v[206:209], v[36:39]
	v_mfma_f32_16x16x32_bf16 v[32:35], v[190:193], v[206:209], v[32:35]
	v_mfma_f32_16x16x32_bf16 v[20:23], v[182:185], v[214:217], v[20:23]
	v_mfma_f32_16x16x32_bf16 v[16:19], v[190:193], v[214:217], v[16:19]
	v_mfma_f32_16x16x32_bf16 v[4:7], v[182:185], v[222:225], v[4:7]
	v_mfma_f32_16x16x32_bf16 v[0:3], v[190:193], v[222:225], v[0:3]
	s_setprio 0
	s_barrier
	s_add_u32 s52, s52, 0x100
	s_addc_u32 s53, s53, 0
	s_add_u32 s90, s90, 0x100
	s_addc_u32 s91, s91, 0
	s_cmp_ge_i32 s92, s74
	s_mov_b32 s66, s92
	s_cbranch_scc1 .Lkx_5

.LBB0_1469:
	s_add_i32 s78, s21, 0x18000
	s_mov_b64 s[26:27], 0x80
	v_lshl_add_u64 v[8:9], v[8:9], 0, s[26:27]
	s_mov_b32 m0, s78
	s_add_i32 s79, s21, 0x1a000
	s_waitcnt vmcnt(2)
	s_mov_b32 s99, 0
	s_barrier
	global_load_lds_dwordx4 v[8:9], off
	v_lshl_add_u64 v[4:5], v[4:5], 0, s[26:27]
	s_mov_b32 m0, s79
	s_add_i32 s85, s21, 0x8000
	global_load_lds_dwordx4 v[4:5], off
	v_lshl_add_u64 v[4:5], v[6:7], 0, s[26:27]
	s_mov_b32 m0, s85
	s_add_i32 s88, s21, 0xa000
	global_load_lds_dwordx4 v[4:5], off
	v_lshl_add_u64 v[4:5], v[10:11], 0, s[26:27]
	s_mov_b32 m0, s88
	s_add_i32 s89, s21, 0x1c000
	global_load_lds_dwordx4 v[4:5], off
	v_lshl_add_u64 v[2:3], v[2:3], 0, s[26:27]
	s_mov_b32 m0, s89
	s_add_i32 s90, s21, 0x1e000
	global_load_lds_dwordx4 v[2:3], off
	v_lshl_add_u64 v[0:1], v[0:1], 0, s[26:27]
	s_mov_b32 m0, s90
	s_ashr_i32 s0, s37, 31
	global_load_lds_dwordx4 v[0:1], off
	v_bfe_u32 v149, v12, 4, 2
	s_lshr_b32 s0, s0, 26
	v_and_b32_e32 v148, 15, v12
	s_add_i32 s0, s37, s0
	v_lshlrev_b32_e32 v0, 4, v149
	v_lshlrev_b32_e32 v1, 2, v12
	s_ashr_i32 s68, s0, 6
	v_lshl_or_b32 v0, v148, 6, v0
	s_lshl_b32 s0, s7, 13
	v_and_b32_e32 v1, 32, v1
	v_bitop3_b32 v150, v0, s0, v1 bitop3:0xde
	s_lshl_b32 s0, s42, 5
	s_and_b32 s70, s0, 0x60
	s_lshl_b32 s0, s70, 7
	v_bitop3_b32 v2, v0, s0, v1 bitop3:0xde
	v_add_u32_e32 v0, v15, v13
	s_lshl_b32 s69, s7, 6
	v_add_lshl_u32 v0, v0, v14, 1
	v_mov_b32_e32 v1, v131
	s_cmp_gt_i32 s37, 63
	v_lshl_add_u64 v[136:137], s[10:11], 0, v[0:1]
	v_add_u32_e32 v0, v18, v16
	s_waitcnt vmcnt(6)
	s_cselect_b64 s[0:1], -1, 0
	s_add_i32 s71, s68, -2
	v_readlane_b32 s4, v246, 5
	v_add_lshl_u32 v0, v0, v17, 1
	s_cmpk_lt_u32 s36, 0x100
	v_readlane_b32 s5, v246, 6
	v_lshl_add_u64 v[138:139], s[10:11], 0, v[0:1]
	v_cndmask_b32_e64 v0, 0, 1, s[0:1]
	s_sext_i32_i8 s82, s6
	s_cselect_b64 s[36:37], -1, 0
	s_ashr_i32 s72, s69, 31
	s_ashr_i32 s73, s4, 31
	s_mov_b32 s74, s4
	s_mov_b32 s75, 0
	v_mov_b64_e32 v[140:141], 0x200
	v_mov_b64_e32 v[142:143], 0x1ff
	v_cmp_ne_u32_e64 s[4:5], 1, v0
	v_or_b32_e32 v151, 0x10000, v2
	v_add_u32_e32 v152, 0x10400, v2
	v_add_u32_e32 v153, 0x10800, v2
	v_add_u32_e32 v154, 0x10c00, v2
	v_or_b32_e32 v155, 0x14000, v2
	v_add_u32_e32 v156, 0x14400, v2
	v_add_u32_e32 v157, 0x14800, v2
	v_add_u32_e32 v158, 0x14c00, v2
	s_add_i32 s76, s21, 0xc000
	s_add_i32 s77, s21, 0xe000
	v_or_b32_e32 v159, 0x18000, v2
	v_add_u32_e32 v160, 0x18400, v2
	v_add_u32_e32 v161, 0x18800, v2
	v_add_u32_e32 v164, 0x18c00, v2
	v_or_b32_e32 v165, 0x1c000, v2
	v_add_u32_e32 v166, 0x1c400, v2
	v_add_u32_e32 v167, 0x1c800, v2
	v_add_u32_e32 v168, 0x1cc00, v2
	s_barrier
	s_branch .LBB0_1472

.Lkp_6:
	s_add_u32 s48, s48, 0x80
	s_addc_u32 s49, s49, 0
	s_add_u32 s47, s50, 0x100
	s_addc_u32 s83, s51, 0
	s_mov_b32 s50, 0
	ds_read_b128 v[144:147], v151
	ds_read_b128 v[170:173], v152
	ds_read_b128 v[174:177], v153
	ds_read_b128 v[178:181], v154
	ds_read_b128 v[182:185], v155
	ds_read_b128 v[186:189], v156
	ds_read_b128 v[190:193], v157
	ds_read_b128 v[194:197], v158
	s_add_i32 s84, s50, 2
	s_add_u32 s56, s48, 0x80
	s_addc_u32 s51, s49, 0
	s_cmp_eq_u32 s71, s50
	s_cselect_b32 s50, s0, s56
	s_cselect_b32 s51, s1, s51
	s_cselect_b32 s57, s43, s83
	s_cselect_b32 s56, s42, s47
	s_mov_b32 m0, s76
	v_lshl_add_u64 v[230:231], s[48:49], 0, v[136:137]
	ds_read_b128 v[198:201], v150
	ds_read_b128 v[202:205], v150 offset:1024
	ds_read_b128 v[206:209], v150 offset:2048
	ds_read_b128 v[210:213], v150 offset:3072
	ds_read_b128 v[214:217], v150 offset:4096
	ds_read_b128 v[218:221], v150 offset:5120
	ds_read_b128 v[222:225], v150 offset:6144
	ds_read_b128 v[226:229], v150 offset:7168
	global_load_lds_dwordx4 v[230:231], off
	v_lshl_add_u64 v[230:231], s[48:49], 0, v[138:139]
	s_mov_b32 m0, s77
	s_nop 0
	global_load_lds_dwordx4 v[230:231], off
	s_cmp_lg_u32 s99, 0
	s_cbranch_scc1 .Lsw_6_0
	s_waitcnt vmcnt(8)
.Lsw_6_0:
	s_waitcnt vmcnt(24)
	s_waitcnt lgkmcnt(0)
	s_barrier
	s_setprio 1
	s_waitcnt lgkmcnt(0)
	v_mfma_f32_16x16x32_bf16 v[124:127], v[144:147], v[198:201], 0
	v_mfma_f32_16x16x32_bf16 v[120:123], v[174:177], v[198:201], 0
	v_mfma_f32_16x16x32_bf16 v[108:111], v[144:147], v[206:209], 0
	v_mfma_f32_16x16x32_bf16 v[104:107], v[174:177], v[206:209], 0
	v_mfma_f32_16x16x32_bf16 v[92:95], v[144:147], v[214:217], 0
	v_mfma_f32_16x16x32_bf16 v[88:91], v[174:177], v[214:217], 0
	v_mfma_f32_16x16x32_bf16 v[76:79], v[144:147], v[222:225], 0
	v_mfma_f32_16x16x32_bf16 v[72:75], v[174:177], v[222:225], 0
	v_mfma_f32_16x16x32_bf16 v[124:127], v[170:173], v[202:205], v[124:127]
	v_mfma_f32_16x16x32_bf16 v[120:123], v[178:181], v[202:205], v[120:123]
	v_mfma_f32_16x16x32_bf16 v[108:111], v[170:173], v[210:213], v[108:111]
	v_mfma_f32_16x16x32_bf16 v[104:107], v[178:181], v[210:213], v[104:107]
	v_mfma_f32_16x16x32_bf16 v[92:95], v[170:173], v[218:221], v[92:95]
	v_mfma_f32_16x16x32_bf16 v[88:91], v[178:181], v[218:221], v[88:91]
	v_mfma_f32_16x16x32_bf16 v[76:79], v[170:173], v[226:229], v[76:79]
	v_mfma_f32_16x16x32_bf16 v[72:75], v[178:181], v[226:229], v[72:75]
	s_setprio 0
	s_setprio 1
	v_mfma_f32_16x16x32_bf16 v[116:119], v[182:185], v[198:201], 0
	v_mfma_f32_16x16x32_bf16 v[112:115], v[190:193], v[198:201], 0
	v_mfma_f32_16x16x32_bf16 v[100:103], v[182:185], v[206:209], 0
	v_mfma_f32_16x16x32_bf16 v[96:99], v[190:193], v[206:209], 0
	v_mfma_f32_16x16x32_bf16 v[84:87], v[182:185], v[214:217], 0
	v_mfma_f32_16x16x32_bf16 v[80:83], v[190:193], v[214:217], 0
	v_mfma_f32_16x16x32_bf16 v[68:71], v[182:185], v[222:225], 0
	v_mfma_f32_16x16x32_bf16 v[64:67], v[190:193], v[222:225], 0
	v_mfma_f32_16x16x32_bf16 v[116:119], v[186:189], v[202:205], v[116:119]
	v_mfma_f32_16x16x32_bf16 v[112:115], v[194:197], v[202:205], v[112:115]
	v_mfma_f32_16x16x32_bf16 v[100:103], v[186:189], v[210:213], v[100:103]
	v_mfma_f32_16x16x32_bf16 v[96:99], v[194:197], v[210:213], v[96:99]
	v_mfma_f32_16x16x32_bf16 v[84:87], v[186:189], v[218:221], v[84:87]
	v_mfma_f32_16x16x32_bf16 v[80:83], v[194:197], v[218:221], v[80:83]
	v_mfma_f32_16x16x32_bf16 v[68:71], v[186:189], v[226:229], v[68:71]
	v_mfma_f32_16x16x32_bf16 v[64:67], v[194:197], v[226:229], v[64:67]
	s_setprio 0
	s_barrier
	s_mov_b32 m0, s28
	v_lshl_add_u64 v[230:231], s[56:57], 0, v[130:131]
	v_lshl_add_u64 v[232:233], s[56:57], 0, v[134:135]
	s_add_u32 s56, s56, s12
	ds_read_b128 v[198:201], v150 offset:16384
	ds_read_b128 v[202:205], v150 offset:17408
	ds_read_b128 v[206:209], v150 offset:18432
	ds_read_b128 v[210:213], v150 offset:19456
	ds_read_b128 v[214:217], v150 offset:20480
	ds_read_b128 v[218:221], v150 offset:21504
	ds_read_b128 v[222:225], v150 offset:22528
	ds_read_b128 v[226:229], v150 offset:23552
	global_load_lds_dwordx4 v[230:231], off
	s_mov_b32 m0, s29
	s_addc_u32 s57, s57, s13
	global_load_lds_dwordx4 v[232:233], off
	v_lshl_add_u64 v[234:235], s[56:57], 0, v[130:131]
	s_mov_b32 m0, s30
	v_lshl_add_u64 v[236:237], s[56:57], 0, v[134:135]
	global_load_lds_dwordx4 v[234:235], off
	s_mov_b32 m0, s31
	v_lshl_add_u64 v[238:239], s[50:51], 0, v[128:129]
	global_load_lds_dwordx4 v[236:237], off
	s_mov_b32 m0, s21
	v_lshl_add_u64 v[240:241], s[50:51], 0, v[132:133]
	global_load_lds_dwordx4 v[238:239], off
	s_mov_b32 m0, s33
	s_nop 0
	global_load_lds_dwordx4 v[240:241], off
	s_cmp_lg_u32 s99, 0
	s_cbranch_scc1 .Lsw_6_1
	s_waitcnt vmcnt(8)
.Lsw_6_1:
	s_waitcnt vmcnt(24)
	s_waitcnt lgkmcnt(0)
	s_barrier
	s_setprio 1
	s_waitcnt lgkmcnt(0)
	v_mfma_f32_16x16x32_bf16 v[60:63], v[144:147], v[198:201], 0
	v_mfma_f32_16x16x32_bf16 v[56:59], v[174:177], v[198:201], 0
	v_mfma_f32_16x16x32_bf16 v[44:47], v[144:147], v[206:209], 0
	v_mfma_f32_16x16x32_bf16 v[40:43], v[174:177], v[206:209], 0
	v_mfma_f32_16x16x32_bf16 v[28:31], v[144:147], v[214:217], 0
	v_mfma_f32_16x16x32_bf16 v[24:27], v[174:177], v[214:217], 0
	v_mfma_f32_16x16x32_bf16 v[12:15], v[144:147], v[222:225], 0
	v_mfma_f32_16x16x32_bf16 v[8:11], v[174:177], v[222:225], 0
	v_mfma_f32_16x16x32_bf16 v[60:63], v[170:173], v[202:205], v[60:63]
	v_mfma_f32_16x16x32_bf16 v[56:59], v[178:181], v[202:205], v[56:59]
	v_mfma_f32_16x16x32_bf16 v[44:47], v[170:173], v[210:213], v[44:47]
	v_mfma_f32_16x16x32_bf16 v[40:43], v[178:181], v[210:213], v[40:43]
	v_mfma_f32_16x16x32_bf16 v[28:31], v[170:173], v[218:221], v[28:31]
	v_mfma_f32_16x16x32_bf16 v[24:27], v[178:181], v[218:221], v[24:27]
	v_mfma_f32_16x16x32_bf16 v[12:15], v[170:173], v[226:229], v[12:15]
	v_mfma_f32_16x16x32_bf16 v[8:11], v[178:181], v[226:229], v[8:11]
	s_setprio 0
	s_setprio 1
	v_mfma_f32_16x16x32_bf16 v[52:55], v[182:185], v[198:201], 0
	v_mfma_f32_16x16x32_bf16 v[48:51], v[190:193], v[198:201], 0
	v_mfma_f32_16x16x32_bf16 v[36:39], v[182:185], v[206:209], 0
	v_mfma_f32_16x16x32_bf16 v[32:35], v[190:193], v[206:209], 0
	v_mfma_f32_16x16x32_bf16 v[20:23], v[182:185], v[214:217], 0
	v_mfma_f32_16x16x32_bf16 v[16:19], v[190:193], v[214:217], 0
	v_mfma_f32_16x16x32_bf16 v[4:7], v[182:185], v[222:225], 0
	v_mfma_f32_16x16x32_bf16 v[0:3], v[190:193], v[222:225], 0
	v_mfma_f32_16x16x32_bf16 v[52:55], v[186:189], v[202:205], v[52:55]
	v_mfma_f32_16x16x32_bf16 v[48:51], v[194:197], v[202:205], v[48:51]
	v_mfma_f32_16x16x32_bf16 v[36:39], v[186:189], v[210:213], v[36:39]
	v_mfma_f32_16x16x32_bf16 v[32:35], v[194:197], v[210:213], v[32:35]
	v_mfma_f32_16x16x32_bf16 v[20:23], v[186:189], v[218:221], v[20:23]
	v_mfma_f32_16x16x32_bf16 v[16:19], v[194:197], v[218:221], v[16:19]
	v_mfma_f32_16x16x32_bf16 v[4:7], v[186:189], v[226:229], v[4:7]
	v_mfma_f32_16x16x32_bf16 v[0:3], v[194:197], v[226:229], v[0:3]
	s_setprio 0
	s_barrier
	ds_read_b128 v[144:147], v159
	ds_read_b128 v[170:173], v160
	ds_read_b128 v[174:177], v161
	ds_read_b128 v[178:181], v164
	ds_read_b128 v[182:185], v165
	ds_read_b128 v[186:189], v166
	ds_read_b128 v[190:193], v167
	ds_read_b128 v[194:197], v168
	s_add_u32 s50, s50, s10
	s_addc_u32 s51, s51, s11
	s_mov_b32 m0, s34
	v_lshl_add_u64 v[242:243], s[50:51], 0, v[128:129]
	ds_read_b128 v[198:201], v150 offset:32768
	ds_read_b128 v[202:205], v150 offset:33792
	ds_read_b128 v[206:209], v150 offset:34816
	ds_read_b128 v[210:213], v150 offset:35840
	ds_read_b128 v[214:217], v150 offset:36864
	ds_read_b128 v[218:221], v150 offset:37888
	ds_read_b128 v[222:225], v150 offset:38912
	ds_read_b128 v[226:229], v150 offset:39936
	global_load_lds_dwordx4 v[242:243], off
	v_lshl_add_u64 v[242:243], s[50:51], 0, v[132:133]
	s_mov_b32 m0, s35
	s_nop 0
	global_load_lds_dwordx4 v[242:243], off
	s_waitcnt vmcnt(8)
	s_waitcnt lgkmcnt(0)
	s_barrier
	s_setprio 1
	s_waitcnt lgkmcnt(0)
	v_mfma_f32_16x16x32_bf16 v[124:127], v[144:147], v[198:201], v[124:127]
	v_mfma_f32_16x16x32_bf16 v[120:123], v[174:177], v[198:201], v[120:123]
	v_mfma_f32_16x16x32_bf16 v[108:111], v[144:147], v[206:209], v[108:111]
	v_mfma_f32_16x16x32_bf16 v[104:107], v[174:177], v[206:209], v[104:107]
	v_mfma_f32_16x16x32_bf16 v[92:95], v[144:147], v[214:217], v[92:95]
	v_mfma_f32_16x16x32_bf16 v[88:91], v[174:177], v[214:217], v[88:91]
	v_mfma_f32_16x16x32_bf16 v[76:79], v[144:147], v[222:225], v[76:79]
	v_mfma_f32_16x16x32_bf16 v[72:75], v[174:177], v[222:225], v[72:75]
	v_mfma_f32_16x16x32_bf16 v[124:127], v[170:173], v[202:205], v[124:127]
	v_mfma_f32_16x16x32_bf16 v[120:123], v[178:181], v[202:205], v[120:123]
	v_mfma_f32_16x16x32_bf16 v[108:111], v[170:173], v[210:213], v[108:111]
	v_mfma_f32_16x16x32_bf16 v[104:107], v[178:181], v[210:213], v[104:107]
	v_mfma_f32_16x16x32_bf16 v[92:95], v[170:173], v[218:221], v[92:95]
	v_mfma_f32_16x16x32_bf16 v[88:91], v[178:181], v[218:221], v[88:91]
	v_mfma_f32_16x16x32_bf16 v[76:79], v[170:173], v[226:229], v[76:79]
	v_mfma_f32_16x16x32_bf16 v[72:75], v[178:181], v[226:229], v[72:75]
	s_setprio 0
	s_setprio 1
	v_mfma_f32_16x16x32_bf16 v[116:119], v[182:185], v[198:201], v[116:119]
	v_mfma_f32_16x16x32_bf16 v[112:115], v[190:193], v[198:201], v[112:115]
	v_mfma_f32_16x16x32_bf16 v[100:103], v[182:185], v[206:209], v[100:103]
	v_mfma_f32_16x16x32_bf16 v[96:99], v[190:193], v[206:209], v[96:99]
	v_mfma_f32_16x16x32_bf16 v[84:87], v[182:185], v[214:217], v[84:87]
	v_mfma_f32_16x16x32_bf16 v[80:83], v[190:193], v[214:217], v[80:83]
	v_mfma_f32_16x16x32_bf16 v[68:71], v[182:185], v[222:225], v[68:71]
	v_mfma_f32_16x16x32_bf16 v[64:67], v[190:193], v[222:225], v[64:67]
	v_mfma_f32_16x16x32_bf16 v[116:119], v[186:189], v[202:205], v[116:119]
	v_mfma_f32_16x16x32_bf16 v[112:115], v[194:197], v[202:205], v[112:115]
	v_mfma_f32_16x16x32_bf16 v[100:103], v[186:189], v[210:213], v[100:103]
	v_mfma_f32_16x16x32_bf16 v[96:99], v[194:197], v[210:213], v[96:99]
	v_mfma_f32_16x16x32_bf16 v[84:87], v[186:189], v[218:221], v[84:87]
	v_mfma_f32_16x16x32_bf16 v[80:83], v[194:197], v[218:221], v[80:83]
	v_mfma_f32_16x16x32_bf16 v[68:71], v[186:189], v[226:229], v[68:71]
	v_mfma_f32_16x16x32_bf16 v[64:67], v[194:197], v[226:229], v[64:67]
	s_setprio 0
	s_barrier
	s_mov_b32 m0, s78
	v_lshl_add_u64 v[230:231], v[230:231], 0, s[26:27]
	ds_read_b128 v[198:201], v150 offset:49152
	ds_read_b128 v[202:205], v150 offset:50176
	ds_read_b128 v[206:209], v150 offset:51200
	ds_read_b128 v[210:213], v150 offset:52224
	ds_read_b128 v[214:217], v150 offset:53248
	ds_read_b128 v[218:221], v150 offset:54272
	ds_read_b128 v[222:225], v150 offset:55296
	ds_read_b128 v[226:229], v150 offset:56320
	global_load_lds_dwordx4 v[230:231], off
	v_lshl_add_u64 v[230:231], v[232:233], 0, s[26:27]
	s_mov_b32 m0, s79
	s_nop 0
	global_load_lds_dwordx4 v[230:231], off
	v_lshl_add_u64 v[230:231], v[234:235], 0, s[26:27]
	s_mov_b32 m0, s89
	s_nop 0
	global_load_lds_dwordx4 v[230:231], off
	v_lshl_add_u64 v[230:231], v[236:237], 0, s[26:27]
	s_mov_b32 m0, s90
	s_nop 0
	global_load_lds_dwordx4 v[230:231], off
	v_lshl_add_u64 v[230:231], v[238:239], 0, s[26:27]
	s_mov_b32 m0, s85
	s_nop 0
	global_load_lds_dwordx4 v[230:231], off
	v_lshl_add_u64 v[230:231], v[240:241], 0, s[26:27]
	s_mov_b32 m0, s88
	s_nop 0
	global_load_lds_dwordx4 v[230:231], off
	s_waitcnt vmcnt(8)
	s_waitcnt lgkmcnt(0)
	s_barrier
	s_setprio 1
	s_waitcnt lgkmcnt(0)
	v_mfma_f32_16x16x32_bf16 v[60:63], v[144:147], v[198:201], v[60:63]
	v_mfma_f32_16x16x32_bf16 v[56:59], v[174:177], v[198:201], v[56:59]
	v_mfma_f32_16x16x32_bf16 v[44:47], v[144:147], v[206:209], v[44:47]
	v_mfma_f32_16x16x32_bf16 v[40:43], v[174:177], v[206:209], v[40:43]
	v_mfma_f32_16x16x32_bf16 v[28:31], v[144:147], v[214:217], v[28:31]
	v_mfma_f32_16x16x32_bf16 v[24:27], v[174:177], v[214:217], v[24:27]
	v_mfma_f32_16x16x32_bf16 v[12:15], v[144:147], v[222:225], v[12:15]
	v_mfma_f32_16x16x32_bf16 v[8:11], v[174:177], v[222:225], v[8:11]
	v_mfma_f32_16x16x32_bf16 v[60:63], v[170:173], v[202:205], v[60:63]
	v_mfma_f32_16x16x32_bf16 v[56:59], v[178:181], v[202:205], v[56:59]
	v_mfma_f32_16x16x32_bf16 v[44:47], v[170:173], v[210:213], v[44:47]
	v_mfma_f32_16x16x32_bf16 v[40:43], v[178:181], v[210:213], v[40:43]
	v_mfma_f32_16x16x32_bf16 v[28:31], v[170:173], v[218:221], v[28:31]
	v_mfma_f32_16x16x32_bf16 v[24:27], v[178:181], v[218:221], v[24:27]
	v_mfma_f32_16x16x32_bf16 v[12:15], v[170:173], v[226:229], v[12:15]
	v_mfma_f32_16x16x32_bf16 v[8:11], v[178:181], v[226:229], v[8:11]
	s_setprio 0
	s_setprio 1
	v_mfma_f32_16x16x32_bf16 v[52:55], v[182:185], v[198:201], v[52:55]
	v_mfma_f32_16x16x32_bf16 v[48:51], v[190:193], v[198:201], v[48:51]
	v_mfma_f32_16x16x32_bf16 v[36:39], v[182:185], v[206:209], v[36:39]
	v_mfma_f32_16x16x32_bf16 v[32:35], v[190:193], v[206:209], v[32:35]
	v_mfma_f32_16x16x32_bf16 v[20:23], v[182:185], v[214:217], v[20:23]
	v_mfma_f32_16x16x32_bf16 v[16:19], v[190:193], v[214:217], v[16:19]
	v_mfma_f32_16x16x32_bf16 v[4:7], v[182:185], v[222:225], v[4:7]
	v_mfma_f32_16x16x32_bf16 v[0:3], v[190:193], v[222:225], v[0:3]
	v_mfma_f32_16x16x32_bf16 v[52:55], v[186:189], v[202:205], v[52:55]
	v_mfma_f32_16x16x32_bf16 v[48:51], v[194:197], v[202:205], v[48:51]
	v_mfma_f32_16x16x32_bf16 v[36:39], v[186:189], v[210:213], v[36:39]
	v_mfma_f32_16x16x32_bf16 v[32:35], v[194:197], v[210:213], v[32:35]
	v_mfma_f32_16x16x32_bf16 v[20:23], v[186:189], v[218:221], v[20:23]
	v_mfma_f32_16x16x32_bf16 v[16:19], v[194:197], v[218:221], v[16:19]
	v_mfma_f32_16x16x32_bf16 v[4:7], v[186:189], v[226:229], v[4:7]
	v_mfma_f32_16x16x32_bf16 v[0:3], v[194:197], v[226:229], v[0:3]
	s_setprio 0
	s_barrier
	s_add_u32 s48, s48, 0x100
	s_addc_u32 s49, s49, 0
	s_add_u32 s47, s47, 0x100
	s_addc_u32 s83, s83, 0
	s_cmp_ge_i32 s84, s68
	s_mov_b32 s50, s84
	s_cbranch_scc1 .Lkx_6

.LBB0_1498:
	s_add_i32 s35, s20, 0x18000
	s_mov_b64 s[24:25], 0x80
	v_lshl_add_u64 v[8:9], v[8:9], 0, s[24:25]
	s_mov_b32 m0, s35
	s_add_i32 s78, s20, 0x1a000
	s_waitcnt vmcnt(2)
	s_mov_b32 s99, 0
	s_barrier
	global_load_lds_dwordx4 v[8:9], off
	v_lshl_add_u64 v[4:5], v[4:5], 0, s[24:25]
	s_mov_b32 m0, s78
	s_add_i32 s79, s20, 0x8000
	global_load_lds_dwordx4 v[4:5], off
	v_lshl_add_u64 v[4:5], v[6:7], 0, s[24:25]
	s_mov_b32 m0, s79
	s_add_i32 s82, s20, 0xa000
	global_load_lds_dwordx4 v[4:5], off
	v_lshl_add_u64 v[4:5], v[10:11], 0, s[24:25]
	s_mov_b32 m0, s82
	s_add_i32 s83, s20, 0x1c000
	global_load_lds_dwordx4 v[4:5], off
	v_lshl_add_u64 v[2:3], v[2:3], 0, s[24:25]
	s_mov_b32 m0, s83
	s_add_i32 s84, s20, 0x1e000
	global_load_lds_dwordx4 v[2:3], off
	v_lshl_add_u64 v[0:1], v[0:1], 0, s[24:25]
	s_mov_b32 m0, s84
	s_ashr_i32 s0, s7, 31
	global_load_lds_dwordx4 v[0:1], off
	v_bfe_u32 v149, v12, 4, 2
	s_lshr_b32 s0, s0, 26
	v_and_b32_e32 v148, 15, v12
	s_add_i32 s0, s7, s0
	v_lshlrev_b32_e32 v0, 4, v149
	v_lshlrev_b32_e32 v1, 2, v12
	s_ashr_i32 s85, s0, 6
	v_lshl_or_b32 v0, v148, 6, v0
	s_lshl_b32 s0, s5, 13
	v_and_b32_e32 v1, 32, v1
	v_bitop3_b32 v150, v0, s0, v1 bitop3:0xde
	s_lshl_b32 s0, s26, 5
	s_and_b32 s89, s0, 0x60
	s_lshl_b32 s0, s89, 7
	v_bitop3_b32 v2, v0, s0, v1 bitop3:0xde
	v_add_u32_e32 v0, v15, v13
	s_lshl_b32 s88, s5, 6
	v_add_lshl_u32 v0, v0, v14, 1
	v_mov_b32_e32 v1, v131
	s_cmp_gt_i32 s7, 63
	v_lshl_add_u64 v[136:137], s[10:11], 0, v[0:1]
	v_add_u32_e32 v0, v18, v16
	s_sext_i32_i8 s77, s4
	s_waitcnt vmcnt(6)
	s_cselect_b64 s[0:1], -1, 0
	s_add_i32 s68, s85, -2
	v_readlane_b32 s4, v246, 5
	v_add_lshl_u32 v0, v0, v17, 1
	s_cmpk_lt_u32 s6, 0x100
	v_readlane_b32 s5, v246, 6
	v_lshl_add_u64 v[138:139], s[10:11], 0, v[0:1]
	v_cndmask_b32_e64 v0, 0, 1, s[0:1]
	s_cselect_b64 s[26:27], -1, 0
	s_ashr_i32 s69, s88, 31
	s_ashr_i32 s70, s4, 31
	s_mov_b32 s71, s4
	s_mov_b32 s72, 0
	v_mov_b64_e32 v[140:141], 0x200
	v_mov_b64_e32 v[142:143], 0x1ff
	v_cmp_ne_u32_e64 s[4:5], 1, v0
	v_or_b32_e32 v151, 0x10000, v2
	v_add_u32_e32 v152, 0x10400, v2
	v_add_u32_e32 v153, 0x10800, v2
	v_add_u32_e32 v154, 0x10c00, v2
	v_or_b32_e32 v155, 0x14000, v2
	v_add_u32_e32 v156, 0x14400, v2
	v_add_u32_e32 v157, 0x14800, v2
	v_add_u32_e32 v158, 0x14c00, v2
	s_add_i32 s73, s20, 0xc000
	s_add_i32 s74, s20, 0xe000
	v_or_b32_e32 v159, 0x18000, v2
	v_add_u32_e32 v160, 0x18400, v2
	v_add_u32_e32 v161, 0x18800, v2
	v_add_u32_e32 v164, 0x18c00, v2
	v_or_b32_e32 v165, 0x1c000, v2
	v_add_u32_e32 v166, 0x1c400, v2
	v_add_u32_e32 v167, 0x1c800, v2
	v_add_u32_e32 v168, 0x1cc00, v2
	s_mov_b64 s[36:37], 0xb0
	s_barrier
	s_branch .LBB0_1501

.Lkp_7:
	s_add_u32 s48, s48, 0x80
	s_addc_u32 s49, s49, 0
	s_add_u32 s47, s50, 0x100
	s_addc_u32 s80, s51, 0
	s_mov_b32 s50, 0
	ds_read_b128 v[144:147], v151
	ds_read_b128 v[170:173], v152
	ds_read_b128 v[174:177], v153
	ds_read_b128 v[178:181], v154
	ds_read_b128 v[182:185], v155
	ds_read_b128 v[186:189], v156
	ds_read_b128 v[190:193], v157
	ds_read_b128 v[194:197], v158
	s_add_i32 s81, s50, 2
	s_add_u32 s58, s48, 0x80
	s_addc_u32 s51, s49, 0
	s_cmp_eq_u32 s68, s50
	s_cselect_b32 s50, s0, s58
	s_cselect_b32 s51, s1, s51
	s_cselect_b32 s59, s43, s80
	s_cselect_b32 s58, s42, s47
	s_mov_b32 m0, s73
	v_lshl_add_u64 v[230:231], s[48:49], 0, v[136:137]
	ds_read_b128 v[198:201], v150
	ds_read_b128 v[202:205], v150 offset:1024
	ds_read_b128 v[206:209], v150 offset:2048
	ds_read_b128 v[210:213], v150 offset:3072
	ds_read_b128 v[214:217], v150 offset:4096
	ds_read_b128 v[218:221], v150 offset:5120
	ds_read_b128 v[222:225], v150 offset:6144
	ds_read_b128 v[226:229], v150 offset:7168
	global_load_lds_dwordx4 v[230:231], off
	v_lshl_add_u64 v[230:231], s[48:49], 0, v[138:139]
	s_mov_b32 m0, s74
	s_nop 0
	global_load_lds_dwordx4 v[230:231], off
	s_cmp_lg_u32 s99, 0
	s_cbranch_scc1 .Lsw_7_0
	s_waitcnt vmcnt(8)
.Lsw_7_0:
	s_waitcnt vmcnt(24)
	s_waitcnt lgkmcnt(0)
	s_barrier
	s_setprio 1
	s_waitcnt lgkmcnt(0)
	v_mfma_f32_16x16x32_bf16 v[124:127], v[144:147], v[198:201], 0
	v_mfma_f32_16x16x32_bf16 v[120:123], v[174:177], v[198:201], 0
	v_mfma_f32_16x16x32_bf16 v[108:111], v[144:147], v[206:209], 0
	v_mfma_f32_16x16x32_bf16 v[104:107], v[174:177], v[206:209], 0
	v_mfma_f32_16x16x32_bf16 v[92:95], v[144:147], v[214:217], 0
	v_mfma_f32_16x16x32_bf16 v[88:91], v[174:177], v[214:217], 0
	v_mfma_f32_16x16x32_bf16 v[76:79], v[144:147], v[222:225], 0
	v_mfma_f32_16x16x32_bf16 v[72:75], v[174:177], v[222:225], 0
	v_mfma_f32_16x16x32_bf16 v[124:127], v[170:173], v[202:205], v[124:127]
	v_mfma_f32_16x16x32_bf16 v[120:123], v[178:181], v[202:205], v[120:123]
	v_mfma_f32_16x16x32_bf16 v[108:111], v[170:173], v[210:213], v[108:111]
	v_mfma_f32_16x16x32_bf16 v[104:107], v[178:181], v[210:213], v[104:107]
	v_mfma_f32_16x16x32_bf16 v[92:95], v[170:173], v[218:221], v[92:95]
	v_mfma_f32_16x16x32_bf16 v[88:91], v[178:181], v[218:221], v[88:91]
	v_mfma_f32_16x16x32_bf16 v[76:79], v[170:173], v[226:229], v[76:79]
	v_mfma_f32_16x16x32_bf16 v[72:75], v[178:181], v[226:229], v[72:75]
	s_setprio 0
	s_setprio 1
	v_mfma_f32_16x16x32_bf16 v[116:119], v[182:185], v[198:201], 0
	v_mfma_f32_16x16x32_bf16 v[112:115], v[190:193], v[198:201], 0
	v_mfma_f32_16x16x32_bf16 v[100:103], v[182:185], v[206:209], 0
	v_mfma_f32_16x16x32_bf16 v[96:99], v[190:193], v[206:209], 0
	v_mfma_f32_16x16x32_bf16 v[84:87], v[182:185], v[214:217], 0
	v_mfma_f32_16x16x32_bf16 v[80:83], v[190:193], v[214:217], 0
	v_mfma_f32_16x16x32_bf16 v[68:71], v[182:185], v[222:225], 0
	v_mfma_f32_16x16x32_bf16 v[64:67], v[190:193], v[222:225], 0
	v_mfma_f32_16x16x32_bf16 v[116:119], v[186:189], v[202:205], v[116:119]
	v_mfma_f32_16x16x32_bf16 v[112:115], v[194:197], v[202:205], v[112:115]
	v_mfma_f32_16x16x32_bf16 v[100:103], v[186:189], v[210:213], v[100:103]
	v_mfma_f32_16x16x32_bf16 v[96:99], v[194:197], v[210:213], v[96:99]
	v_mfma_f32_16x16x32_bf16 v[84:87], v[186:189], v[218:221], v[84:87]
	v_mfma_f32_16x16x32_bf16 v[80:83], v[194:197], v[218:221], v[80:83]
	v_mfma_f32_16x16x32_bf16 v[68:71], v[186:189], v[226:229], v[68:71]
	v_mfma_f32_16x16x32_bf16 v[64:67], v[194:197], v[226:229], v[64:67]
	s_setprio 0
	s_barrier
	s_mov_b32 m0, s21
	v_lshl_add_u64 v[230:231], s[58:59], 0, v[130:131]
	v_lshl_add_u64 v[232:233], s[58:59], 0, v[134:135]
	s_add_u32 s58, s58, s12
	ds_read_b128 v[198:201], v150 offset:16384
	ds_read_b128 v[202:205], v150 offset:17408
	ds_read_b128 v[206:209], v150 offset:18432
	ds_read_b128 v[210:213], v150 offset:19456
	ds_read_b128 v[214:217], v150 offset:20480
	ds_read_b128 v[218:221], v150 offset:21504
	ds_read_b128 v[222:225], v150 offset:22528
	ds_read_b128 v[226:229], v150 offset:23552
	global_load_lds_dwordx4 v[230:231], off
	s_mov_b32 m0, s28
	s_addc_u32 s59, s59, s13
	global_load_lds_dwordx4 v[232:233], off
	v_lshl_add_u64 v[234:235], s[58:59], 0, v[130:131]
	s_mov_b32 m0, s29
	v_lshl_add_u64 v[236:237], s[58:59], 0, v[134:135]
	global_load_lds_dwordx4 v[234:235], off
	s_mov_b32 m0, s30
	v_lshl_add_u64 v[238:239], s[50:51], 0, v[128:129]
	global_load_lds_dwordx4 v[236:237], off
	s_mov_b32 m0, s20
	v_lshl_add_u64 v[240:241], s[50:51], 0, v[132:133]
	global_load_lds_dwordx4 v[238:239], off
	s_mov_b32 m0, s31
	s_nop 0
	global_load_lds_dwordx4 v[240:241], off
	s_cmp_lg_u32 s99, 0
	s_cbranch_scc1 .Lsw_7_1
	s_waitcnt vmcnt(8)
.Lsw_7_1:
	s_waitcnt vmcnt(24)
	s_waitcnt lgkmcnt(0)
	s_barrier
	s_setprio 1
	s_waitcnt lgkmcnt(0)
	v_mfma_f32_16x16x32_bf16 v[60:63], v[144:147], v[198:201], 0
	v_mfma_f32_16x16x32_bf16 v[56:59], v[174:177], v[198:201], 0
	v_mfma_f32_16x16x32_bf16 v[44:47], v[144:147], v[206:209], 0
	v_mfma_f32_16x16x32_bf16 v[40:43], v[174:177], v[206:209], 0
	v_mfma_f32_16x16x32_bf16 v[28:31], v[144:147], v[214:217], 0
	v_mfma_f32_16x16x32_bf16 v[24:27], v[174:177], v[214:217], 0
	v_mfma_f32_16x16x32_bf16 v[12:15], v[144:147], v[222:225], 0
	v_mfma_f32_16x16x32_bf16 v[8:11], v[174:177], v[222:225], 0
	v_mfma_f32_16x16x32_bf16 v[60:63], v[170:173], v[202:205], v[60:63]
	v_mfma_f32_16x16x32_bf16 v[56:59], v[178:181], v[202:205], v[56:59]
	v_mfma_f32_16x16x32_bf16 v[44:47], v[170:173], v[210:213], v[44:47]
	v_mfma_f32_16x16x32_bf16 v[40:43], v[178:181], v[210:213], v[40:43]
	v_mfma_f32_16x16x32_bf16 v[28:31], v[170:173], v[218:221], v[28:31]
	v_mfma_f32_16x16x32_bf16 v[24:27], v[178:181], v[218:221], v[24:27]
	v_mfma_f32_16x16x32_bf16 v[12:15], v[170:173], v[226:229], v[12:15]
	v_mfma_f32_16x16x32_bf16 v[8:11], v[178:181], v[226:229], v[8:11]
	s_setprio 0
	s_setprio 1
	v_mfma_f32_16x16x32_bf16 v[52:55], v[182:185], v[198:201], 0
	v_mfma_f32_16x16x32_bf16 v[48:51], v[190:193], v[198:201], 0
	v_mfma_f32_16x16x32_bf16 v[36:39], v[182:185], v[206:209], 0
	v_mfma_f32_16x16x32_bf16 v[32:35], v[190:193], v[206:209], 0
	v_mfma_f32_16x16x32_bf16 v[20:23], v[182:185], v[214:217], 0
	v_mfma_f32_16x16x32_bf16 v[16:19], v[190:193], v[214:217], 0
	v_mfma_f32_16x16x32_bf16 v[4:7], v[182:185], v[222:225], 0
	v_mfma_f32_16x16x32_bf16 v[0:3], v[190:193], v[222:225], 0
	v_mfma_f32_16x16x32_bf16 v[52:55], v[186:189], v[202:205], v[52:55]
	v_mfma_f32_16x16x32_bf16 v[48:51], v[194:197], v[202:205], v[48:51]
	v_mfma_f32_16x16x32_bf16 v[36:39], v[186:189], v[210:213], v[36:39]
	v_mfma_f32_16x16x32_bf16 v[32:35], v[194:197], v[210:213], v[32:35]
	v_mfma_f32_16x16x32_bf16 v[20:23], v[186:189], v[218:221], v[20:23]
	v_mfma_f32_16x16x32_bf16 v[16:19], v[194:197], v[218:221], v[16:19]
	v_mfma_f32_16x16x32_bf16 v[4:7], v[186:189], v[226:229], v[4:7]
	v_mfma_f32_16x16x32_bf16 v[0:3], v[194:197], v[226:229], v[0:3]
	s_setprio 0
	s_barrier
	ds_read_b128 v[144:147], v159
	ds_read_b128 v[170:173], v160
	ds_read_b128 v[174:177], v161
	ds_read_b128 v[178:181], v164
	ds_read_b128 v[182:185], v165
	ds_read_b128 v[186:189], v166
	ds_read_b128 v[190:193], v167
	ds_read_b128 v[194:197], v168
	s_add_u32 s50, s50, s10
	s_addc_u32 s51, s51, s11
	s_mov_b32 m0, s33
	v_lshl_add_u64 v[242:243], s[50:51], 0, v[128:129]
	ds_read_b128 v[198:201], v150 offset:32768
	ds_read_b128 v[202:205], v150 offset:33792
	ds_read_b128 v[206:209], v150 offset:34816
	ds_read_b128 v[210:213], v150 offset:35840
	ds_read_b128 v[214:217], v150 offset:36864
	ds_read_b128 v[218:221], v150 offset:37888
	ds_read_b128 v[222:225], v150 offset:38912
	ds_read_b128 v[226:229], v150 offset:39936
	global_load_lds_dwordx4 v[242:243], off
	v_lshl_add_u64 v[242:243], s[50:51], 0, v[132:133]
	s_mov_b32 m0, s34
	s_nop 0
	global_load_lds_dwordx4 v[242:243], off
	s_waitcnt vmcnt(8)
	s_waitcnt lgkmcnt(0)
	s_barrier
	s_setprio 1
	s_waitcnt lgkmcnt(0)
	v_mfma_f32_16x16x32_bf16 v[124:127], v[144:147], v[198:201], v[124:127]
	v_mfma_f32_16x16x32_bf16 v[120:123], v[174:177], v[198:201], v[120:123]
	v_mfma_f32_16x16x32_bf16 v[108:111], v[144:147], v[206:209], v[108:111]
	v_mfma_f32_16x16x32_bf16 v[104:107], v[174:177], v[206:209], v[104:107]
	v_mfma_f32_16x16x32_bf16 v[92:95], v[144:147], v[214:217], v[92:95]
	v_mfma_f32_16x16x32_bf16 v[88:91], v[174:177], v[214:217], v[88:91]
	v_mfma_f32_16x16x32_bf16 v[76:79], v[144:147], v[222:225], v[76:79]
	v_mfma_f32_16x16x32_bf16 v[72:75], v[174:177], v[222:225], v[72:75]
	v_mfma_f32_16x16x32_bf16 v[124:127], v[170:173], v[202:205], v[124:127]
	v_mfma_f32_16x16x32_bf16 v[120:123], v[178:181], v[202:205], v[120:123]
	v_mfma_f32_16x16x32_bf16 v[108:111], v[170:173], v[210:213], v[108:111]
	v_mfma_f32_16x16x32_bf16 v[104:107], v[178:181], v[210:213], v[104:107]
	v_mfma_f32_16x16x32_bf16 v[92:95], v[170:173], v[218:221], v[92:95]
	v_mfma_f32_16x16x32_bf16 v[88:91], v[178:181], v[218:221], v[88:91]
	v_mfma_f32_16x16x32_bf16 v[76:79], v[170:173], v[226:229], v[76:79]
	v_mfma_f32_16x16x32_bf16 v[72:75], v[178:181], v[226:229], v[72:75]
	s_setprio 0
	s_setprio 1
	v_mfma_f32_16x16x32_bf16 v[116:119], v[182:185], v[198:201], v[116:119]
	v_mfma_f32_16x16x32_bf16 v[112:115], v[190:193], v[198:201], v[112:115]
	v_mfma_f32_16x16x32_bf16 v[100:103], v[182:185], v[206:209], v[100:103]
	v_mfma_f32_16x16x32_bf16 v[96:99], v[190:193], v[206:209], v[96:99]
	v_mfma_f32_16x16x32_bf16 v[84:87], v[182:185], v[214:217], v[84:87]
	v_mfma_f32_16x16x32_bf16 v[80:83], v[190:193], v[214:217], v[80:83]
	v_mfma_f32_16x16x32_bf16 v[68:71], v[182:185], v[222:225], v[68:71]
	v_mfma_f32_16x16x32_bf16 v[64:67], v[190:193], v[222:225], v[64:67]
	v_mfma_f32_16x16x32_bf16 v[116:119], v[186:189], v[202:205], v[116:119]
	v_mfma_f32_16x16x32_bf16 v[112:115], v[194:197], v[202:205], v[112:115]
	v_mfma_f32_16x16x32_bf16 v[100:103], v[186:189], v[210:213], v[100:103]
	v_mfma_f32_16x16x32_bf16 v[96:99], v[194:197], v[210:213], v[96:99]
	v_mfma_f32_16x16x32_bf16 v[84:87], v[186:189], v[218:221], v[84:87]
	v_mfma_f32_16x16x32_bf16 v[80:83], v[194:197], v[218:221], v[80:83]
	v_mfma_f32_16x16x32_bf16 v[68:71], v[186:189], v[226:229], v[68:71]
	v_mfma_f32_16x16x32_bf16 v[64:67], v[194:197], v[226:229], v[64:67]
	s_setprio 0
	s_barrier
	s_mov_b32 m0, s35
	v_lshl_add_u64 v[230:231], v[230:231], 0, s[24:25]
	ds_read_b128 v[198:201], v150 offset:49152
	ds_read_b128 v[202:205], v150 offset:50176
	ds_read_b128 v[206:209], v150 offset:51200
	ds_read_b128 v[210:213], v150 offset:52224
	ds_read_b128 v[214:217], v150 offset:53248
	ds_read_b128 v[218:221], v150 offset:54272
	ds_read_b128 v[222:225], v150 offset:55296
	ds_read_b128 v[226:229], v150 offset:56320
	global_load_lds_dwordx4 v[230:231], off
	v_lshl_add_u64 v[230:231], v[232:233], 0, s[24:25]
	s_mov_b32 m0, s78
	s_nop 0
	global_load_lds_dwordx4 v[230:231], off
	v_lshl_add_u64 v[230:231], v[234:235], 0, s[24:25]
	s_mov_b32 m0, s83
	s_nop 0
	global_load_lds_dwordx4 v[230:231], off
	v_lshl_add_u64 v[230:231], v[236:237], 0, s[24:25]
	s_mov_b32 m0, s84
	s_nop 0
	global_load_lds_dwordx4 v[230:231], off
	v_lshl_add_u64 v[230:231], v[238:239], 0, s[24:25]
	s_mov_b32 m0, s79
	s_nop 0
	global_load_lds_dwordx4 v[230:231], off
	v_lshl_add_u64 v[230:231], v[240:241], 0, s[24:25]
	s_mov_b32 m0, s82
	s_nop 0
	global_load_lds_dwordx4 v[230:231], off
	s_waitcnt vmcnt(8)
	s_waitcnt lgkmcnt(0)
	s_barrier
	s_setprio 1
	s_waitcnt lgkmcnt(0)
	v_mfma_f32_16x16x32_bf16 v[60:63], v[144:147], v[198:201], v[60:63]
	v_mfma_f32_16x16x32_bf16 v[56:59], v[174:177], v[198:201], v[56:59]
	v_mfma_f32_16x16x32_bf16 v[44:47], v[144:147], v[206:209], v[44:47]
	v_mfma_f32_16x16x32_bf16 v[40:43], v[174:177], v[206:209], v[40:43]
	v_mfma_f32_16x16x32_bf16 v[28:31], v[144:147], v[214:217], v[28:31]
	v_mfma_f32_16x16x32_bf16 v[24:27], v[174:177], v[214:217], v[24:27]
	v_mfma_f32_16x16x32_bf16 v[12:15], v[144:147], v[222:225], v[12:15]
	v_mfma_f32_16x16x32_bf16 v[8:11], v[174:177], v[222:225], v[8:11]
	v_mfma_f32_16x16x32_bf16 v[60:63], v[170:173], v[202:205], v[60:63]
	v_mfma_f32_16x16x32_bf16 v[56:59], v[178:181], v[202:205], v[56:59]
	v_mfma_f32_16x16x32_bf16 v[44:47], v[170:173], v[210:213], v[44:47]
	v_mfma_f32_16x16x32_bf16 v[40:43], v[178:181], v[210:213], v[40:43]
	v_mfma_f32_16x16x32_bf16 v[28:31], v[170:173], v[218:221], v[28:31]
	v_mfma_f32_16x16x32_bf16 v[24:27], v[178:181], v[218:221], v[24:27]
	v_mfma_f32_16x16x32_bf16 v[12:15], v[170:173], v[226:229], v[12:15]
	v_mfma_f32_16x16x32_bf16 v[8:11], v[178:181], v[226:229], v[8:11]
	s_setprio 0
	s_setprio 1
	v_mfma_f32_16x16x32_bf16 v[52:55], v[182:185], v[198:201], v[52:55]
	v_mfma_f32_16x16x32_bf16 v[48:51], v[190:193], v[198:201], v[48:51]
	v_mfma_f32_16x16x32_bf16 v[36:39], v[182:185], v[206:209], v[36:39]
	v_mfma_f32_16x16x32_bf16 v[32:35], v[190:193], v[206:209], v[32:35]
	v_mfma_f32_16x16x32_bf16 v[20:23], v[182:185], v[214:217], v[20:23]
	v_mfma_f32_16x16x32_bf16 v[16:19], v[190:193], v[214:217], v[16:19]
	v_mfma_f32_16x16x32_bf16 v[4:7], v[182:185], v[222:225], v[4:7]
	v_mfma_f32_16x16x32_bf16 v[0:3], v[190:193], v[222:225], v[0:3]
	v_mfma_f32_16x16x32_bf16 v[52:55], v[186:189], v[202:205], v[52:55]
	v_mfma_f32_16x16x32_bf16 v[48:51], v[194:197], v[202:205], v[48:51]
	v_mfma_f32_16x16x32_bf16 v[36:39], v[186:189], v[210:213], v[36:39]
	v_mfma_f32_16x16x32_bf16 v[32:35], v[194:197], v[210:213], v[32:35]
	v_mfma_f32_16x16x32_bf16 v[20:23], v[186:189], v[218:221], v[20:23]
	v_mfma_f32_16x16x32_bf16 v[16:19], v[194:197], v[218:221], v[16:19]
	v_mfma_f32_16x16x32_bf16 v[4:7], v[186:189], v[226:229], v[4:7]
	v_mfma_f32_16x16x32_bf16 v[0:3], v[194:197], v[226:229], v[0:3]
	s_setprio 0
	s_barrier
	s_add_u32 s48, s48, 0x100
	s_addc_u32 s49, s49, 0
	s_add_u32 s47, s47, 0x100
	s_addc_u32 s80, s80, 0
	s_cmp_ge_i32 s81, s85
	s_mov_b32 s50, s81
	s_cbranch_scc1 .Lkx_7

.LBB0_1581:
	s_add_i32 s34, s3, 0x18000
	s_mov_b64 s[26:27], 0x80
	v_lshl_add_u64 v[8:9], v[8:9], 0, s[26:27]
	s_mov_b32 m0, s34
	s_add_i32 s35, s3, 0x1a000
	s_waitcnt vmcnt(2)
	s_mov_b32 s99, 0
	s_barrier
	global_load_lds_dwordx4 v[8:9], off
	v_lshl_add_u64 v[4:5], v[4:5], 0, s[26:27]
	s_mov_b32 m0, s35
	s_add_i32 s84, s3, 0x8000
	global_load_lds_dwordx4 v[4:5], off
	v_lshl_add_u64 v[4:5], v[6:7], 0, s[26:27]
	s_mov_b32 m0, s84
	s_add_i32 s85, s3, 0xa000
	global_load_lds_dwordx4 v[4:5], off
	v_lshl_add_u64 v[4:5], v[10:11], 0, s[26:27]
	s_mov_b32 m0, s85
	s_add_i32 s88, s3, 0x1c000
	global_load_lds_dwordx4 v[4:5], off
	v_lshl_add_u64 v[2:3], v[2:3], 0, s[26:27]
	s_mov_b32 m0, s88
	s_add_i32 s89, s3, 0x1e000
	global_load_lds_dwordx4 v[2:3], off
	v_lshl_add_u64 v[0:1], v[0:1], 0, s[26:27]
	s_mov_b32 m0, s89
	s_ashr_i32 s0, s37, 31
	global_load_lds_dwordx4 v[0:1], off
	v_bfe_u32 v149, v12, 4, 2
	s_lshr_b32 s0, s0, 26
	v_and_b32_e32 v148, 15, v12
	s_add_i32 s0, s37, s0
	v_lshlrev_b32_e32 v0, 4, v149
	v_lshlrev_b32_e32 v1, 2, v12
	s_ashr_i32 s90, s0, 6
	v_lshl_or_b32 v0, v148, 6, v0
	s_lshl_b32 s0, s6, 13
	v_and_b32_e32 v1, 32, v1
	v_bitop3_b32 v150, v0, s0, v1 bitop3:0xde
	s_lshl_b32 s0, s7, 5
	s_lshl_b32 s91, s6, 6
	s_and_b32 s6, s0, 0x60
	s_lshl_b32 s0, s6, 7
	v_bitop3_b32 v2, v0, s0, v1 bitop3:0xde
	v_add_u32_e32 v0, v15, v13
	v_add_lshl_u32 v0, v0, v14, 1
	v_mov_b32_e32 v1, v131
	s_cmp_gt_i32 s37, 63
	v_lshl_add_u64 v[136:137], s[12:13], 0, v[0:1]
	v_add_u32_e32 v0, v18, v16
	s_waitcnt vmcnt(6)
	s_cselect_b64 s[0:1], -1, 0
	s_add_i32 s68, s90, -2
	v_readlane_b32 s4, v246, 5
	v_add_lshl_u32 v0, v0, v17, 1
	s_cmpk_lt_u32 s36, 0x100
	s_mov_b32 s43, 0
	v_readlane_b32 s5, v246, 6
	v_lshl_add_u64 v[138:139], s[12:13], 0, v[0:1]
	v_cndmask_b32_e64 v0, 0, 1, s[0:1]
	v_readlane_b32 s64, v246, 12
	s_cselect_b64 s[36:37], -1, 0
	s_ashr_i32 s69, s91, 31
	s_ashr_i32 s70, s4, 31
	s_mov_b32 s71, s4
	s_ashr_i32 s72, s2, 31
	v_mov_b64_e32 v[140:141], 0x200
	v_mov_b64_e32 v[142:143], 0x1ff
	v_cmp_ne_u32_e64 s[4:5], 1, v0
	v_or_b32_e32 v151, 0x10000, v2
	v_add_u32_e32 v152, 0x10400, v2
	v_add_u32_e32 v153, 0x10800, v2
	v_add_u32_e32 v154, 0x10c00, v2
	v_or_b32_e32 v155, 0x14000, v2
	v_add_u32_e32 v156, 0x14400, v2
	v_add_u32_e32 v157, 0x14800, v2
	v_add_u32_e32 v158, 0x14c00, v2
	s_add_i32 s73, s3, 0xc000
	s_add_i32 s74, s3, 0xe000
	v_or_b32_e32 v159, 0x18000, v2
	v_add_u32_e32 v160, 0x18400, v2
	v_add_u32_e32 v161, 0x18800, v2
	v_add_u32_e32 v164, 0x18c00, v2
	v_or_b32_e32 v165, 0x1c000, v2
	v_add_u32_e32 v166, 0x1c400, v2
	v_add_u32_e32 v167, 0x1c800, v2
	v_add_u32_e32 v168, 0x1cc00, v2
	v_mbcnt_hi_u32_b32 v169, -1, v163
	s_lshl_b32 s42, s6, 1
	s_mov_b64 s[46:47], 0xb0
	s_mov_b32 s75, s43
	v_readlane_b32 s65, v246, 13
	s_barrier
	s_branch .LBB0_1584

.Lkp_8:
	s_add_u32 s52, s82, 0x80
	s_addc_u32 s53, s83, 0
	s_add_u32 s51, s80, 0x100
	s_addc_u32 s79, s81, 0
	s_mov_b32 s54, 0
	ds_read_b128 v[144:147], v151
	ds_read_b128 v[170:173], v152
	ds_read_b128 v[174:177], v153
	ds_read_b128 v[178:181], v154
	ds_read_b128 v[182:185], v155
	ds_read_b128 v[186:189], v156
	ds_read_b128 v[190:193], v157
	ds_read_b128 v[194:197], v158
	s_add_i32 s80, s54, 2
	s_add_u32 s60, s52, 0x80
	s_addc_u32 s55, s53, 0
	s_cmp_eq_u32 s68, s54
	s_cselect_b32 s54, s0, s60
	s_cselect_b32 s55, s1, s55
	s_cselect_b32 s61, s49, s79
	s_cselect_b32 s60, s48, s51
	s_mov_b32 m0, s73
	v_lshl_add_u64 v[230:231], s[52:53], 0, v[136:137]
	ds_read_b128 v[198:201], v150
	ds_read_b128 v[202:205], v150 offset:1024
	ds_read_b128 v[206:209], v150 offset:2048
	ds_read_b128 v[210:213], v150 offset:3072
	ds_read_b128 v[214:217], v150 offset:4096
	ds_read_b128 v[218:221], v150 offset:5120
	ds_read_b128 v[222:225], v150 offset:6144
	ds_read_b128 v[226:229], v150 offset:7168
	global_load_lds_dwordx4 v[230:231], off
	v_lshl_add_u64 v[230:231], s[52:53], 0, v[138:139]
	s_mov_b32 m0, s74
	s_nop 0
	global_load_lds_dwordx4 v[230:231], off
	s_cmp_lg_u32 s99, 0
	s_cbranch_scc1 .Lsw_8_0
	s_waitcnt vmcnt(8)
.Lsw_8_0:
	s_waitcnt vmcnt(24)
	s_waitcnt lgkmcnt(0)
	s_barrier
	s_setprio 1
	s_waitcnt lgkmcnt(0)
	v_mfma_f32_16x16x32_bf16 v[124:127], v[144:147], v[198:201], 0
	v_mfma_f32_16x16x32_bf16 v[120:123], v[174:177], v[198:201], 0
	v_mfma_f32_16x16x32_bf16 v[108:111], v[144:147], v[206:209], 0
	v_mfma_f32_16x16x32_bf16 v[104:107], v[174:177], v[206:209], 0
	v_mfma_f32_16x16x32_bf16 v[92:95], v[144:147], v[214:217], 0
	v_mfma_f32_16x16x32_bf16 v[88:91], v[174:177], v[214:217], 0
	v_mfma_f32_16x16x32_bf16 v[76:79], v[144:147], v[222:225], 0
	v_mfma_f32_16x16x32_bf16 v[72:75], v[174:177], v[222:225], 0
	v_mfma_f32_16x16x32_bf16 v[124:127], v[170:173], v[202:205], v[124:127]
	v_mfma_f32_16x16x32_bf16 v[120:123], v[178:181], v[202:205], v[120:123]
	v_mfma_f32_16x16x32_bf16 v[108:111], v[170:173], v[210:213], v[108:111]
	v_mfma_f32_16x16x32_bf16 v[104:107], v[178:181], v[210:213], v[104:107]
	v_mfma_f32_16x16x32_bf16 v[92:95], v[170:173], v[218:221], v[92:95]
	v_mfma_f32_16x16x32_bf16 v[88:91], v[178:181], v[218:221], v[88:91]
	v_mfma_f32_16x16x32_bf16 v[76:79], v[170:173], v[226:229], v[76:79]
	v_mfma_f32_16x16x32_bf16 v[72:75], v[178:181], v[226:229], v[72:75]
	s_setprio 0
	s_setprio 1
	v_mfma_f32_16x16x32_bf16 v[116:119], v[182:185], v[198:201], 0
	v_mfma_f32_16x16x32_bf16 v[112:115], v[190:193], v[198:201], 0
	v_mfma_f32_16x16x32_bf16 v[100:103], v[182:185], v[206:209], 0
	v_mfma_f32_16x16x32_bf16 v[96:99], v[190:193], v[206:209], 0
	v_mfma_f32_16x16x32_bf16 v[84:87], v[182:185], v[214:217], 0
	v_mfma_f32_16x16x32_bf16 v[80:83], v[190:193], v[214:217], 0
	v_mfma_f32_16x16x32_bf16 v[68:71], v[182:185], v[222:225], 0
	v_mfma_f32_16x16x32_bf16 v[64:67], v[190:193], v[222:225], 0
	v_mfma_f32_16x16x32_bf16 v[116:119], v[186:189], v[202:205], v[116:119]
	v_mfma_f32_16x16x32_bf16 v[112:115], v[194:197], v[202:205], v[112:115]
	v_mfma_f32_16x16x32_bf16 v[100:103], v[186:189], v[210:213], v[100:103]
	v_mfma_f32_16x16x32_bf16 v[96:99], v[194:197], v[210:213], v[96:99]
	v_mfma_f32_16x16x32_bf16 v[84:87], v[186:189], v[218:221], v[84:87]
	v_mfma_f32_16x16x32_bf16 v[80:83], v[194:197], v[218:221], v[80:83]
	v_mfma_f32_16x16x32_bf16 v[68:71], v[186:189], v[226:229], v[68:71]
	v_mfma_f32_16x16x32_bf16 v[64:67], v[194:197], v[226:229], v[64:67]
	s_setprio 0
	s_barrier
	s_mov_b32 m0, s20
	v_lshl_add_u64 v[230:231], s[60:61], 0, v[130:131]
	v_lshl_add_u64 v[232:233], s[60:61], 0, v[134:135]
	s_add_u32 s60, s60, s14
	ds_read_b128 v[198:201], v150 offset:16384
	ds_read_b128 v[202:205], v150 offset:17408
	ds_read_b128 v[206:209], v150 offset:18432
	ds_read_b128 v[210:213], v150 offset:19456
	ds_read_b128 v[214:217], v150 offset:20480
	ds_read_b128 v[218:221], v150 offset:21504
	ds_read_b128 v[222:225], v150 offset:22528
	ds_read_b128 v[226:229], v150 offset:23552
	global_load_lds_dwordx4 v[230:231], off
	s_mov_b32 m0, s21
	s_addc_u32 s61, s61, s15
	global_load_lds_dwordx4 v[232:233], off
	v_lshl_add_u64 v[234:235], s[60:61], 0, v[130:131]
	s_mov_b32 m0, s28
	v_lshl_add_u64 v[236:237], s[60:61], 0, v[134:135]
	global_load_lds_dwordx4 v[234:235], off
	s_mov_b32 m0, s29
	v_lshl_add_u64 v[238:239], s[54:55], 0, v[128:129]
	global_load_lds_dwordx4 v[236:237], off
	s_mov_b32 m0, s3
	v_lshl_add_u64 v[240:241], s[54:55], 0, v[132:133]
	global_load_lds_dwordx4 v[238:239], off
	s_mov_b32 m0, s30
	s_nop 0
	global_load_lds_dwordx4 v[240:241], off
	s_cmp_lg_u32 s99, 0
	s_cbranch_scc1 .Lsw_8_1
	s_waitcnt vmcnt(8)
.Lsw_8_1:
	s_waitcnt vmcnt(24)
	s_waitcnt lgkmcnt(0)
	s_barrier
	s_setprio 1
	s_waitcnt lgkmcnt(0)
	v_mfma_f32_16x16x32_bf16 v[60:63], v[144:147], v[198:201], 0
	v_mfma_f32_16x16x32_bf16 v[56:59], v[174:177], v[198:201], 0
	v_mfma_f32_16x16x32_bf16 v[44:47], v[144:147], v[206:209], 0
	v_mfma_f32_16x16x32_bf16 v[40:43], v[174:177], v[206:209], 0
	v_mfma_f32_16x16x32_bf16 v[28:31], v[144:147], v[214:217], 0
	v_mfma_f32_16x16x32_bf16 v[24:27], v[174:177], v[214:217], 0
	v_mfma_f32_16x16x32_bf16 v[12:15], v[144:147], v[222:225], 0
	v_mfma_f32_16x16x32_bf16 v[8:11], v[174:177], v[222:225], 0
	v_mfma_f32_16x16x32_bf16 v[60:63], v[170:173], v[202:205], v[60:63]
	v_mfma_f32_16x16x32_bf16 v[56:59], v[178:181], v[202:205], v[56:59]
	v_mfma_f32_16x16x32_bf16 v[44:47], v[170:173], v[210:213], v[44:47]
	v_mfma_f32_16x16x32_bf16 v[40:43], v[178:181], v[210:213], v[40:43]
	v_mfma_f32_16x16x32_bf16 v[28:31], v[170:173], v[218:221], v[28:31]
	v_mfma_f32_16x16x32_bf16 v[24:27], v[178:181], v[218:221], v[24:27]
	v_mfma_f32_16x16x32_bf16 v[12:15], v[170:173], v[226:229], v[12:15]
	v_mfma_f32_16x16x32_bf16 v[8:11], v[178:181], v[226:229], v[8:11]
	s_setprio 0
	s_setprio 1
	v_mfma_f32_16x16x32_bf16 v[52:55], v[182:185], v[198:201], 0
	v_mfma_f32_16x16x32_bf16 v[48:51], v[190:193], v[198:201], 0
	v_mfma_f32_16x16x32_bf16 v[36:39], v[182:185], v[206:209], 0
	v_mfma_f32_16x16x32_bf16 v[32:35], v[190:193], v[206:209], 0
	v_mfma_f32_16x16x32_bf16 v[20:23], v[182:185], v[214:217], 0
	v_mfma_f32_16x16x32_bf16 v[16:19], v[190:193], v[214:217], 0
	v_mfma_f32_16x16x32_bf16 v[4:7], v[182:185], v[222:225], 0
	v_mfma_f32_16x16x32_bf16 v[0:3], v[190:193], v[222:225], 0
	v_mfma_f32_16x16x32_bf16 v[52:55], v[186:189], v[202:205], v[52:55]
	v_mfma_f32_16x16x32_bf16 v[48:51], v[194:197], v[202:205], v[48:51]
	v_mfma_f32_16x16x32_bf16 v[36:39], v[186:189], v[210:213], v[36:39]
	v_mfma_f32_16x16x32_bf16 v[32:35], v[194:197], v[210:213], v[32:35]
	v_mfma_f32_16x16x32_bf16 v[20:23], v[186:189], v[218:221], v[20:23]
	v_mfma_f32_16x16x32_bf16 v[16:19], v[194:197], v[218:221], v[16:19]
	v_mfma_f32_16x16x32_bf16 v[4:7], v[186:189], v[226:229], v[4:7]
	v_mfma_f32_16x16x32_bf16 v[0:3], v[194:197], v[226:229], v[0:3]
	s_setprio 0
	s_barrier
	ds_read_b128 v[144:147], v159
	ds_read_b128 v[170:173], v160
	ds_read_b128 v[174:177], v161
	ds_read_b128 v[178:181], v164
	ds_read_b128 v[182:185], v165
	ds_read_b128 v[186:189], v166
	ds_read_b128 v[190:193], v167
	ds_read_b128 v[194:197], v168
	s_add_u32 s54, s54, s12
	s_addc_u32 s55, s55, s13
	s_mov_b32 m0, s31
	v_lshl_add_u64 v[242:243], s[54:55], 0, v[128:129]
	ds_read_b128 v[198:201], v150 offset:32768
	ds_read_b128 v[202:205], v150 offset:33792
	ds_read_b128 v[206:209], v150 offset:34816
	ds_read_b128 v[210:213], v150 offset:35840
	ds_read_b128 v[214:217], v150 offset:36864
	ds_read_b128 v[218:221], v150 offset:37888
	ds_read_b128 v[222:225], v150 offset:38912
	ds_read_b128 v[226:229], v150 offset:39936
	global_load_lds_dwordx4 v[242:243], off
	v_lshl_add_u64 v[242:243], s[54:55], 0, v[132:133]
	s_mov_b32 m0, s33
	s_nop 0
	global_load_lds_dwordx4 v[242:243], off
	s_waitcnt vmcnt(8)
	s_waitcnt lgkmcnt(0)
	s_barrier
	s_setprio 1
	s_waitcnt lgkmcnt(0)
	v_mfma_f32_16x16x32_bf16 v[124:127], v[144:147], v[198:201], v[124:127]
	v_mfma_f32_16x16x32_bf16 v[120:123], v[174:177], v[198:201], v[120:123]
	v_mfma_f32_16x16x32_bf16 v[108:111], v[144:147], v[206:209], v[108:111]
	v_mfma_f32_16x16x32_bf16 v[104:107], v[174:177], v[206:209], v[104:107]
	v_mfma_f32_16x16x32_bf16 v[92:95], v[144:147], v[214:217], v[92:95]
	v_mfma_f32_16x16x32_bf16 v[88:91], v[174:177], v[214:217], v[88:91]
	v_mfma_f32_16x16x32_bf16 v[76:79], v[144:147], v[222:225], v[76:79]
	v_mfma_f32_16x16x32_bf16 v[72:75], v[174:177], v[222:225], v[72:75]
	v_mfma_f32_16x16x32_bf16 v[124:127], v[170:173], v[202:205], v[124:127]
	v_mfma_f32_16x16x32_bf16 v[120:123], v[178:181], v[202:205], v[120:123]
	v_mfma_f32_16x16x32_bf16 v[108:111], v[170:173], v[210:213], v[108:111]
	v_mfma_f32_16x16x32_bf16 v[104:107], v[178:181], v[210:213], v[104:107]
	v_mfma_f32_16x16x32_bf16 v[92:95], v[170:173], v[218:221], v[92:95]
	v_mfma_f32_16x16x32_bf16 v[88:91], v[178:181], v[218:221], v[88:91]
	v_mfma_f32_16x16x32_bf16 v[76:79], v[170:173], v[226:229], v[76:79]
	v_mfma_f32_16x16x32_bf16 v[72:75], v[178:181], v[226:229], v[72:75]
	s_setprio 0
	s_setprio 1
	v_mfma_f32_16x16x32_bf16 v[116:119], v[182:185], v[198:201], v[116:119]
	v_mfma_f32_16x16x32_bf16 v[112:115], v[190:193], v[198:201], v[112:115]
	v_mfma_f32_16x16x32_bf16 v[100:103], v[182:185], v[206:209], v[100:103]
	v_mfma_f32_16x16x32_bf16 v[96:99], v[190:193], v[206:209], v[96:99]
	v_mfma_f32_16x16x32_bf16 v[84:87], v[182:185], v[214:217], v[84:87]
	v_mfma_f32_16x16x32_bf16 v[80:83], v[190:193], v[214:217], v[80:83]
	v_mfma_f32_16x16x32_bf16 v[68:71], v[182:185], v[222:225], v[68:71]
	v_mfma_f32_16x16x32_bf16 v[64:67], v[190:193], v[222:225], v[64:67]
	v_mfma_f32_16x16x32_bf16 v[116:119], v[186:189], v[202:205], v[116:119]
	v_mfma_f32_16x16x32_bf16 v[112:115], v[194:197], v[202:205], v[112:115]
	v_mfma_f32_16x16x32_bf16 v[100:103], v[186:189], v[210:213], v[100:103]
	v_mfma_f32_16x16x32_bf16 v[96:99], v[194:197], v[210:213], v[96:99]
	v_mfma_f32_16x16x32_bf16 v[84:87], v[186:189], v[218:221], v[84:87]
	v_mfma_f32_16x16x32_bf16 v[80:83], v[194:197], v[218:221], v[80:83]
	v_mfma_f32_16x16x32_bf16 v[68:71], v[186:189], v[226:229], v[68:71]
	v_mfma_f32_16x16x32_bf16 v[64:67], v[194:197], v[226:229], v[64:67]
	s_setprio 0
	s_barrier
	s_mov_b32 m0, s34
	v_lshl_add_u64 v[230:231], v[230:231], 0, s[26:27]
	ds_read_b128 v[198:201], v150 offset:49152
	ds_read_b128 v[202:205], v150 offset:50176
	ds_read_b128 v[206:209], v150 offset:51200
	ds_read_b128 v[210:213], v150 offset:52224
	ds_read_b128 v[214:217], v150 offset:53248
	ds_read_b128 v[218:221], v150 offset:54272
	ds_read_b128 v[222:225], v150 offset:55296
	ds_read_b128 v[226:229], v150 offset:56320
	global_load_lds_dwordx4 v[230:231], off
	v_lshl_add_u64 v[230:231], v[232:233], 0, s[26:27]
	s_mov_b32 m0, s35
	s_nop 0
	global_load_lds_dwordx4 v[230:231], off
	v_lshl_add_u64 v[230:231], v[234:235], 0, s[26:27]
	s_mov_b32 m0, s88
	s_nop 0
	global_load_lds_dwordx4 v[230:231], off
	v_lshl_add_u64 v[230:231], v[236:237], 0, s[26:27]
	s_mov_b32 m0, s89
	s_nop 0
	global_load_lds_dwordx4 v[230:231], off
	v_lshl_add_u64 v[230:231], v[238:239], 0, s[26:27]
	s_mov_b32 m0, s84
	s_nop 0
	global_load_lds_dwordx4 v[230:231], off
	v_lshl_add_u64 v[230:231], v[240:241], 0, s[26:27]
	s_mov_b32 m0, s85
	s_nop 0
	global_load_lds_dwordx4 v[230:231], off
	s_waitcnt vmcnt(8)
	s_waitcnt lgkmcnt(0)
	s_barrier
	s_setprio 1
	s_waitcnt lgkmcnt(0)
	v_mfma_f32_16x16x32_bf16 v[60:63], v[144:147], v[198:201], v[60:63]
	v_mfma_f32_16x16x32_bf16 v[56:59], v[174:177], v[198:201], v[56:59]
	v_mfma_f32_16x16x32_bf16 v[44:47], v[144:147], v[206:209], v[44:47]
	v_mfma_f32_16x16x32_bf16 v[40:43], v[174:177], v[206:209], v[40:43]
	v_mfma_f32_16x16x32_bf16 v[28:31], v[144:147], v[214:217], v[28:31]
	v_mfma_f32_16x16x32_bf16 v[24:27], v[174:177], v[214:217], v[24:27]
	v_mfma_f32_16x16x32_bf16 v[12:15], v[144:147], v[222:225], v[12:15]
	v_mfma_f32_16x16x32_bf16 v[8:11], v[174:177], v[222:225], v[8:11]
	v_mfma_f32_16x16x32_bf16 v[60:63], v[170:173], v[202:205], v[60:63]
	v_mfma_f32_16x16x32_bf16 v[56:59], v[178:181], v[202:205], v[56:59]
	v_mfma_f32_16x16x32_bf16 v[44:47], v[170:173], v[210:213], v[44:47]
	v_mfma_f32_16x16x32_bf16 v[40:43], v[178:181], v[210:213], v[40:43]
	v_mfma_f32_16x16x32_bf16 v[28:31], v[170:173], v[218:221], v[28:31]
	v_mfma_f32_16x16x32_bf16 v[24:27], v[178:181], v[218:221], v[24:27]
	v_mfma_f32_16x16x32_bf16 v[12:15], v[170:173], v[226:229], v[12:15]
	v_mfma_f32_16x16x32_bf16 v[8:11], v[178:181], v[226:229], v[8:11]
	s_setprio 0
	s_setprio 1
	v_mfma_f32_16x16x32_bf16 v[52:55], v[182:185], v[198:201], v[52:55]
	v_mfma_f32_16x16x32_bf16 v[48:51], v[190:193], v[198:201], v[48:51]
	v_mfma_f32_16x16x32_bf16 v[36:39], v[182:185], v[206:209], v[36:39]
	v_mfma_f32_16x16x32_bf16 v[32:35], v[190:193], v[206:209], v[32:35]
	v_mfma_f32_16x16x32_bf16 v[20:23], v[182:185], v[214:217], v[20:23]
	v_mfma_f32_16x16x32_bf16 v[16:19], v[190:193], v[214:217], v[16:19]
	v_mfma_f32_16x16x32_bf16 v[4:7], v[182:185], v[222:225], v[4:7]
	v_mfma_f32_16x16x32_bf16 v[0:3], v[190:193], v[222:225], v[0:3]
	v_mfma_f32_16x16x32_bf16 v[52:55], v[186:189], v[202:205], v[52:55]
	v_mfma_f32_16x16x32_bf16 v[48:51], v[194:197], v[202:205], v[48:51]
	v_mfma_f32_16x16x32_bf16 v[36:39], v[186:189], v[210:213], v[36:39]
	v_mfma_f32_16x16x32_bf16 v[32:35], v[194:197], v[210:213], v[32:35]
	v_mfma_f32_16x16x32_bf16 v[20:23], v[186:189], v[218:221], v[20:23]
	v_mfma_f32_16x16x32_bf16 v[16:19], v[194:197], v[218:221], v[16:19]
	v_mfma_f32_16x16x32_bf16 v[4:7], v[186:189], v[226:229], v[4:7]
	v_mfma_f32_16x16x32_bf16 v[0:3], v[194:197], v[226:229], v[0:3]
	s_setprio 0
	s_barrier
	s_add_u32 s52, s52, 0x100
	s_addc_u32 s53, s53, 0
	s_add_u32 s51, s51, 0x100
	s_addc_u32 s79, s79, 0
	s_cmp_ge_i32 s80, s90
	s_mov_b32 s54, s80
	s_cbranch_scc1 .Lkx_8

.LBB0_1738:
	s_add_i32 s51, s3, 0x18000
	s_mov_b64 s[24:25], 0x80
	v_lshl_add_u64 v[6:7], v[6:7], 0, s[24:25]
	s_mov_b32 m0, s51
	s_add_i32 s81, s3, 0x1a000
	s_waitcnt vmcnt(2)
	s_mov_b32 s99, 0
	s_barrier
	global_load_lds_dwordx4 v[6:7], off
	v_lshl_add_u64 v[4:5], v[4:5], 0, s[24:25]
	s_mov_b32 m0, s81
	s_add_i32 s84, s3, 0x8000
	global_load_lds_dwordx4 v[4:5], off
	v_lshl_add_u64 v[4:5], v[8:9], 0, s[24:25]
	s_mov_b32 m0, s84
	s_add_i32 s85, s3, 0xa000
	global_load_lds_dwordx4 v[4:5], off
	v_lshl_add_u64 v[4:5], v[10:11], 0, s[24:25]
	s_mov_b32 m0, s85
	s_add_i32 s88, s3, 0x1c000
	global_load_lds_dwordx4 v[4:5], off
	v_lshl_add_u64 v[2:3], v[2:3], 0, s[24:25]
	s_mov_b32 m0, s88
	s_add_i32 s89, s3, 0x1e000
	global_load_lds_dwordx4 v[2:3], off
	v_lshl_add_u64 v[0:1], v[0:1], 0, s[24:25]
	s_mov_b32 m0, s89
	s_sext_i32_i8 s78, s0
	global_load_lds_dwordx4 v[0:1], off
	s_ashr_i32 s0, s16, 31
	v_bfe_u32 v145, v12, 4, 2
	s_lshr_b32 s0, s0, 26
	v_and_b32_e32 v144, 15, v12
	s_add_i32 s0, s16, s0
	v_lshlrev_b32_e32 v0, 4, v145
	v_lshlrev_b32_e32 v1, 2, v12
	s_ashr_i32 s91, s0, 6
	v_lshl_or_b32 v0, v144, 6, v0
	s_lshl_b32 s0, s27, 13
	v_and_b32_e32 v1, 32, v1
	v_bitop3_b32 v146, v0, s0, v1 bitop3:0xde
	s_lshl_b32 s0, s26, 5
	s_and_b32 s0, s0, 0x60
	s_lshl_b32 s4, s0, 7
	v_bitop3_b32 v2, v0, s4, v1 bitop3:0xde
	v_add_u32_e32 v0, v18, v16
	s_lshl_b32 s92, s27, 6
	v_add_lshl_u32 v0, v0, v17, 1
	v_mov_b32_e32 v1, v133
	s_cmp_gt_i32 s16, 63
	v_lshl_add_u64 v[136:137], s[8:9], 0, v[0:1]
	v_add_u32_e32 v0, v15, v13
	s_waitcnt vmcnt(6)
	s_cselect_b64 s[4:5], -1, 0
	s_add_i32 s96, s91, -2
	v_add_lshl_u32 v0, v0, v14, 1
	s_cmpk_lt_u32 s1, 0x100
	v_readlane_b32 s6, v246, 5
	v_lshl_add_u64 v[138:139], s[8:9], 0, v[0:1]
	v_cndmask_b32_e64 v0, 0, 1, s[4:5]
	s_cselect_b64 s[26:27], -1, 0
	s_ashr_i32 s97, s92, 31
	s_ashr_i32 s94, s6, 31
	s_mov_b32 s95, s6
	v_mov_b64_e32 v[140:141], 0xb00
	v_mov_b64_e32 v[142:143], 0xaff
	v_cmp_ne_u32_e64 s[4:5], 1, v0
	v_or_b32_e32 v147, 0x10000, v2
	v_add_u32_e32 v148, 0x10400, v2
	v_add_u32_e32 v149, 0x10800, v2
	v_add_u32_e32 v150, 0x10c00, v2
	v_or_b32_e32 v151, 0x14000, v2
	v_add_u32_e32 v152, 0x14400, v2
	v_add_u32_e32 v153, 0x14800, v2
	v_add_u32_e32 v154, 0x14c00, v2
	s_add_i32 s90, s3, 0xc000
	s_add_i32 s68, s3, 0xe000
	v_or_b32_e32 v155, 0x18000, v2
	v_add_u32_e32 v156, 0x18400, v2
	v_add_u32_e32 v157, 0x18800, v2
	v_add_u32_e32 v158, 0x18c00, v2
	v_or_b32_e32 v159, 0x1c000, v2
	v_add_u32_e32 v160, 0x1c400, v2
	v_add_u32_e32 v161, 0x1c800, v2
	v_add_u32_e32 v164, 0x1cc00, v2
	s_movk_i32 s69, 0x1600
	s_lshl_b32 s16, s0, 1
	s_mov_b32 s70, 0x2c000
	s_mov_b32 s71, 0x42000
	s_mov_b32 s72, 0xb0000
	s_mov_b32 s73, 0xc6000
	s_mov_b32 s74, 0xdc000
	s_mov_b32 s75, s17
	s_barrier
	v_readlane_b32 s7, v246, 6
	s_branch .LBB0_1741

.Lkp_9:
	s_add_u32 s46, s46, 0x80
	s_addc_u32 s47, s47, 0
	s_add_u32 s43, s48, 0x100
	s_addc_u32 s79, s49, 0
	s_mov_b32 s48, 0
	ds_read_b128 v[166:169], v147
	ds_read_b128 v[170:173], v148
	ds_read_b128 v[174:177], v149
	ds_read_b128 v[178:181], v150
	ds_read_b128 v[182:185], v151
	ds_read_b128 v[186:189], v152
	ds_read_b128 v[190:193], v153
	ds_read_b128 v[194:197], v154
	s_add_i32 s80, s48, 2
	s_add_u32 s62, s46, 0x80
	s_addc_u32 s49, s47, 0
	s_cmp_eq_u32 s96, s48
	s_cselect_b32 s48, s0, s62
	s_cselect_b32 s49, s1, s49
	s_cselect_b32 s63, s37, s79
	s_cselect_b32 s62, s36, s43
	s_mov_b32 m0, s90
	v_lshl_add_u64 v[230:231], s[46:47], 0, v[136:137]
	ds_read_b128 v[198:201], v146
	ds_read_b128 v[202:205], v146 offset:1024
	ds_read_b128 v[206:209], v146 offset:2048
	ds_read_b128 v[210:213], v146 offset:3072
	ds_read_b128 v[214:217], v146 offset:4096
	ds_read_b128 v[218:221], v146 offset:5120
	ds_read_b128 v[222:225], v146 offset:6144
	ds_read_b128 v[226:229], v146 offset:7168
	global_load_lds_dwordx4 v[230:231], off
	v_lshl_add_u64 v[230:231], s[46:47], 0, v[138:139]
	s_mov_b32 m0, s68
	s_nop 0
	global_load_lds_dwordx4 v[230:231], off
	s_cmp_lg_u32 s99, 0
	s_cbranch_scc1 .Lsw_9_0
	s_waitcnt vmcnt(8)
.Lsw_9_0:
	s_waitcnt vmcnt(16)
	s_waitcnt lgkmcnt(0)
	s_barrier
	s_setprio 1
	s_waitcnt lgkmcnt(0)
	v_mfma_f32_16x16x32_bf16 v[124:127], v[166:169], v[198:201], 0
	v_mfma_f32_16x16x32_bf16 v[116:119], v[174:177], v[198:201], 0
	v_mfma_f32_16x16x32_bf16 v[108:111], v[166:169], v[206:209], 0
	v_mfma_f32_16x16x32_bf16 v[100:103], v[174:177], v[206:209], 0
	v_mfma_f32_16x16x32_bf16 v[92:95], v[166:169], v[214:217], 0
	v_mfma_f32_16x16x32_bf16 v[84:87], v[174:177], v[214:217], 0
	v_mfma_f32_16x16x32_bf16 v[76:79], v[166:169], v[222:225], 0
	v_mfma_f32_16x16x32_bf16 v[68:71], v[174:177], v[222:225], 0
	v_mfma_f32_16x16x32_bf16 v[124:127], v[170:173], v[202:205], v[124:127]
	v_mfma_f32_16x16x32_bf16 v[116:119], v[178:181], v[202:205], v[116:119]
	v_mfma_f32_16x16x32_bf16 v[108:111], v[170:173], v[210:213], v[108:111]
	v_mfma_f32_16x16x32_bf16 v[100:103], v[178:181], v[210:213], v[100:103]
	v_mfma_f32_16x16x32_bf16 v[92:95], v[170:173], v[218:221], v[92:95]
	v_mfma_f32_16x16x32_bf16 v[84:87], v[178:181], v[218:221], v[84:87]
	v_mfma_f32_16x16x32_bf16 v[76:79], v[170:173], v[226:229], v[76:79]
	v_mfma_f32_16x16x32_bf16 v[68:71], v[178:181], v[226:229], v[68:71]
	s_setprio 0
	s_setprio 1
	v_mfma_f32_16x16x32_bf16 v[120:123], v[182:185], v[198:201], 0
	v_mfma_f32_16x16x32_bf16 v[112:115], v[190:193], v[198:201], 0
	v_mfma_f32_16x16x32_bf16 v[104:107], v[182:185], v[206:209], 0
	v_mfma_f32_16x16x32_bf16 v[96:99], v[190:193], v[206:209], 0
	v_mfma_f32_16x16x32_bf16 v[88:91], v[182:185], v[214:217], 0
	v_mfma_f32_16x16x32_bf16 v[80:83], v[190:193], v[214:217], 0
	v_mfma_f32_16x16x32_bf16 v[72:75], v[182:185], v[222:225], 0
	v_mfma_f32_16x16x32_bf16 v[64:67], v[190:193], v[222:225], 0
	v_mfma_f32_16x16x32_bf16 v[120:123], v[186:189], v[202:205], v[120:123]
	v_mfma_f32_16x16x32_bf16 v[112:115], v[194:197], v[202:205], v[112:115]
	v_mfma_f32_16x16x32_bf16 v[104:107], v[186:189], v[210:213], v[104:107]
	v_mfma_f32_16x16x32_bf16 v[96:99], v[194:197], v[210:213], v[96:99]
	v_mfma_f32_16x16x32_bf16 v[88:91], v[186:189], v[218:221], v[88:91]
	v_mfma_f32_16x16x32_bf16 v[80:83], v[194:197], v[218:221], v[80:83]
	v_mfma_f32_16x16x32_bf16 v[72:75], v[186:189], v[226:229], v[72:75]
	v_mfma_f32_16x16x32_bf16 v[64:67], v[194:197], v[226:229], v[64:67]
	s_setprio 0
	s_barrier
	s_mov_b32 m0, s28
	v_lshl_add_u64 v[230:231], s[62:63], 0, v[132:133]
	v_lshl_add_u64 v[232:233], s[62:63], 0, v[128:129]
	s_add_u32 s62, s62, s10
	ds_read_b128 v[198:201], v146 offset:16384
	ds_read_b128 v[202:205], v146 offset:17408
	ds_read_b128 v[206:209], v146 offset:18432
	ds_read_b128 v[210:213], v146 offset:19456
	ds_read_b128 v[214:217], v146 offset:20480
	ds_read_b128 v[218:221], v146 offset:21504
	ds_read_b128 v[222:225], v146 offset:22528
	ds_read_b128 v[226:229], v146 offset:23552
	global_load_lds_dwordx4 v[230:231], off
	s_mov_b32 m0, s29
	s_addc_u32 s63, s63, s11
	global_load_lds_dwordx4 v[232:233], off
	v_lshl_add_u64 v[234:235], s[62:63], 0, v[132:133]
	s_mov_b32 m0, s30
	v_lshl_add_u64 v[236:237], s[62:63], 0, v[128:129]
	global_load_lds_dwordx4 v[234:235], off
	s_mov_b32 m0, s31
	v_lshl_add_u64 v[238:239], s[48:49], 0, v[134:135]
	global_load_lds_dwordx4 v[236:237], off
	s_mov_b32 m0, s3
	v_lshl_add_u64 v[240:241], s[48:49], 0, v[130:131]
	global_load_lds_dwordx4 v[238:239], off
	s_mov_b32 m0, s33
	s_nop 0
	global_load_lds_dwordx4 v[240:241], off
	s_cmp_lg_u32 s99, 0
	s_cbranch_scc1 .Lsw_9_1
	s_waitcnt vmcnt(8)
.Lsw_9_1:
	s_waitcnt vmcnt(16)
	s_waitcnt lgkmcnt(0)
	s_barrier
	s_setprio 1
	s_waitcnt lgkmcnt(0)
	v_mfma_f32_16x16x32_bf16 v[60:63], v[166:169], v[198:201], 0
	v_mfma_f32_16x16x32_bf16 v[52:55], v[174:177], v[198:201], 0
	v_mfma_f32_16x16x32_bf16 v[44:47], v[166:169], v[206:209], 0
	v_mfma_f32_16x16x32_bf16 v[36:39], v[174:177], v[206:209], 0
	v_mfma_f32_16x16x32_bf16 v[28:31], v[166:169], v[214:217], 0
	v_mfma_f32_16x16x32_bf16 v[20:23], v[174:177], v[214:217], 0
	v_mfma_f32_16x16x32_bf16 v[12:15], v[166:169], v[222:225], 0
	v_mfma_f32_16x16x32_bf16 v[4:7], v[174:177], v[222:225], 0
	v_mfma_f32_16x16x32_bf16 v[60:63], v[170:173], v[202:205], v[60:63]
	v_mfma_f32_16x16x32_bf16 v[52:55], v[178:181], v[202:205], v[52:55]
	v_mfma_f32_16x16x32_bf16 v[44:47], v[170:173], v[210:213], v[44:47]
	v_mfma_f32_16x16x32_bf16 v[36:39], v[178:181], v[210:213], v[36:39]
	v_mfma_f32_16x16x32_bf16 v[28:31], v[170:173], v[218:221], v[28:31]
	v_mfma_f32_16x16x32_bf16 v[20:23], v[178:181], v[218:221], v[20:23]
	v_mfma_f32_16x16x32_bf16 v[12:15], v[170:173], v[226:229], v[12:15]
	v_mfma_f32_16x16x32_bf16 v[4:7], v[178:181], v[226:229], v[4:7]
	s_setprio 0
	s_setprio 1
	v_mfma_f32_16x16x32_bf16 v[56:59], v[182:185], v[198:201], 0
	v_mfma_f32_16x16x32_bf16 v[48:51], v[190:193], v[198:201], 0
	v_mfma_f32_16x16x32_bf16 v[40:43], v[182:185], v[206:209], 0
	v_mfma_f32_16x16x32_bf16 v[32:35], v[190:193], v[206:209], 0
	v_mfma_f32_16x16x32_bf16 v[24:27], v[182:185], v[214:217], 0
	v_mfma_f32_16x16x32_bf16 v[16:19], v[190:193], v[214:217], 0
	v_mfma_f32_16x16x32_bf16 v[8:11], v[182:185], v[222:225], 0
	v_mfma_f32_16x16x32_bf16 v[0:3], v[190:193], v[222:225], 0
	v_mfma_f32_16x16x32_bf16 v[56:59], v[186:189], v[202:205], v[56:59]
	v_mfma_f32_16x16x32_bf16 v[48:51], v[194:197], v[202:205], v[48:51]
	v_mfma_f32_16x16x32_bf16 v[40:43], v[186:189], v[210:213], v[40:43]
	v_mfma_f32_16x16x32_bf16 v[32:35], v[194:197], v[210:213], v[32:35]
	v_mfma_f32_16x16x32_bf16 v[24:27], v[186:189], v[218:221], v[24:27]
	v_mfma_f32_16x16x32_bf16 v[16:19], v[194:197], v[218:221], v[16:19]
	v_mfma_f32_16x16x32_bf16 v[8:11], v[186:189], v[226:229], v[8:11]
	v_mfma_f32_16x16x32_bf16 v[0:3], v[194:197], v[226:229], v[0:3]
	s_setprio 0
	s_barrier
	ds_read_b128 v[166:169], v155
	ds_read_b128 v[170:173], v156
	ds_read_b128 v[174:177], v157
	ds_read_b128 v[178:181], v158
	ds_read_b128 v[182:185], v159
	ds_read_b128 v[186:189], v160
	ds_read_b128 v[190:193], v161
	ds_read_b128 v[194:197], v164
	s_add_u32 s48, s48, s8
	s_addc_u32 s49, s49, s9
	s_mov_b32 m0, s34
	v_lshl_add_u64 v[242:243], s[48:49], 0, v[134:135]
	ds_read_b128 v[198:201], v146 offset:32768
	ds_read_b128 v[202:205], v146 offset:33792
	ds_read_b128 v[206:209], v146 offset:34816
	ds_read_b128 v[210:213], v146 offset:35840
	ds_read_b128 v[214:217], v146 offset:36864
	ds_read_b128 v[218:221], v146 offset:37888
	ds_read_b128 v[222:225], v146 offset:38912
	ds_read_b128 v[226:229], v146 offset:39936
	global_load_lds_dwordx4 v[242:243], off
	v_lshl_add_u64 v[242:243], s[48:49], 0, v[130:131]
	s_mov_b32 m0, s35
	s_nop 0
	global_load_lds_dwordx4 v[242:243], off
	s_waitcnt vmcnt(8)
	s_waitcnt lgkmcnt(0)
	s_barrier
	s_setprio 1
	s_waitcnt lgkmcnt(0)
	v_mfma_f32_16x16x32_bf16 v[124:127], v[166:169], v[198:201], v[124:127]
	v_mfma_f32_16x16x32_bf16 v[116:119], v[174:177], v[198:201], v[116:119]
	v_mfma_f32_16x16x32_bf16 v[108:111], v[166:169], v[206:209], v[108:111]
	v_mfma_f32_16x16x32_bf16 v[100:103], v[174:177], v[206:209], v[100:103]
	v_mfma_f32_16x16x32_bf16 v[92:95], v[166:169], v[214:217], v[92:95]
	v_mfma_f32_16x16x32_bf16 v[84:87], v[174:177], v[214:217], v[84:87]
	v_mfma_f32_16x16x32_bf16 v[76:79], v[166:169], v[222:225], v[76:79]
	v_mfma_f32_16x16x32_bf16 v[68:71], v[174:177], v[222:225], v[68:71]
	v_mfma_f32_16x16x32_bf16 v[124:127], v[170:173], v[202:205], v[124:127]
	v_mfma_f32_16x16x32_bf16 v[116:119], v[178:181], v[202:205], v[116:119]
	v_mfma_f32_16x16x32_bf16 v[108:111], v[170:173], v[210:213], v[108:111]
	v_mfma_f32_16x16x32_bf16 v[100:103], v[178:181], v[210:213], v[100:103]
	v_mfma_f32_16x16x32_bf16 v[92:95], v[170:173], v[218:221], v[92:95]
	v_mfma_f32_16x16x32_bf16 v[84:87], v[178:181], v[218:221], v[84:87]
	v_mfma_f32_16x16x32_bf16 v[76:79], v[170:173], v[226:229], v[76:79]
	v_mfma_f32_16x16x32_bf16 v[68:71], v[178:181], v[226:229], v[68:71]
	s_setprio 0
	s_setprio 1
	v_mfma_f32_16x16x32_bf16 v[120:123], v[182:185], v[198:201], v[120:123]
	v_mfma_f32_16x16x32_bf16 v[112:115], v[190:193], v[198:201], v[112:115]
	v_mfma_f32_16x16x32_bf16 v[104:107], v[182:185], v[206:209], v[104:107]
	v_mfma_f32_16x16x32_bf16 v[96:99], v[190:193], v[206:209], v[96:99]
	v_mfma_f32_16x16x32_bf16 v[88:91], v[182:185], v[214:217], v[88:91]
	v_mfma_f32_16x16x32_bf16 v[80:83], v[190:193], v[214:217], v[80:83]
	v_mfma_f32_16x16x32_bf16 v[72:75], v[182:185], v[222:225], v[72:75]
	v_mfma_f32_16x16x32_bf16 v[64:67], v[190:193], v[222:225], v[64:67]
	v_mfma_f32_16x16x32_bf16 v[120:123], v[186:189], v[202:205], v[120:123]
	v_mfma_f32_16x16x32_bf16 v[112:115], v[194:197], v[202:205], v[112:115]
	v_mfma_f32_16x16x32_bf16 v[104:107], v[186:189], v[210:213], v[104:107]
	v_mfma_f32_16x16x32_bf16 v[96:99], v[194:197], v[210:213], v[96:99]
	v_mfma_f32_16x16x32_bf16 v[88:91], v[186:189], v[218:221], v[88:91]
	v_mfma_f32_16x16x32_bf16 v[80:83], v[194:197], v[218:221], v[80:83]
	v_mfma_f32_16x16x32_bf16 v[72:75], v[186:189], v[226:229], v[72:75]
	v_mfma_f32_16x16x32_bf16 v[64:67], v[194:197], v[226:229], v[64:67]
	s_setprio 0
	s_barrier
	s_mov_b32 m0, s51
	v_lshl_add_u64 v[230:231], v[230:231], 0, s[24:25]
	ds_read_b128 v[198:201], v146 offset:49152
	ds_read_b128 v[202:205], v146 offset:50176
	ds_read_b128 v[206:209], v146 offset:51200
	ds_read_b128 v[210:213], v146 offset:52224
	ds_read_b128 v[214:217], v146 offset:53248
	ds_read_b128 v[218:221], v146 offset:54272
	ds_read_b128 v[222:225], v146 offset:55296
	ds_read_b128 v[226:229], v146 offset:56320
	global_load_lds_dwordx4 v[230:231], off
	v_lshl_add_u64 v[230:231], v[232:233], 0, s[24:25]
	s_mov_b32 m0, s81
	s_nop 0
	global_load_lds_dwordx4 v[230:231], off
	v_lshl_add_u64 v[230:231], v[234:235], 0, s[24:25]
	s_mov_b32 m0, s88
	s_nop 0
	global_load_lds_dwordx4 v[230:231], off
	v_lshl_add_u64 v[230:231], v[236:237], 0, s[24:25]
	s_mov_b32 m0, s89
	s_nop 0
	global_load_lds_dwordx4 v[230:231], off
	v_lshl_add_u64 v[230:231], v[238:239], 0, s[24:25]
	s_mov_b32 m0, s84
	s_nop 0
	global_load_lds_dwordx4 v[230:231], off
	v_lshl_add_u64 v[230:231], v[240:241], 0, s[24:25]
	s_mov_b32 m0, s85
	s_nop 0
	global_load_lds_dwordx4 v[230:231], off
	s_waitcnt vmcnt(8)
	s_waitcnt lgkmcnt(0)
	s_barrier
	s_setprio 1
	s_waitcnt lgkmcnt(0)
	v_mfma_f32_16x16x32_bf16 v[60:63], v[166:169], v[198:201], v[60:63]
	v_mfma_f32_16x16x32_bf16 v[52:55], v[174:177], v[198:201], v[52:55]
	v_mfma_f32_16x16x32_bf16 v[44:47], v[166:169], v[206:209], v[44:47]
	v_mfma_f32_16x16x32_bf16 v[36:39], v[174:177], v[206:209], v[36:39]
	v_mfma_f32_16x16x32_bf16 v[28:31], v[166:169], v[214:217], v[28:31]
	v_mfma_f32_16x16x32_bf16 v[20:23], v[174:177], v[214:217], v[20:23]
	v_mfma_f32_16x16x32_bf16 v[12:15], v[166:169], v[222:225], v[12:15]
	v_mfma_f32_16x16x32_bf16 v[4:7], v[174:177], v[222:225], v[4:7]
	v_mfma_f32_16x16x32_bf16 v[60:63], v[170:173], v[202:205], v[60:63]
	v_mfma_f32_16x16x32_bf16 v[52:55], v[178:181], v[202:205], v[52:55]
	v_mfma_f32_16x16x32_bf16 v[44:47], v[170:173], v[210:213], v[44:47]
	v_mfma_f32_16x16x32_bf16 v[36:39], v[178:181], v[210:213], v[36:39]
	v_mfma_f32_16x16x32_bf16 v[28:31], v[170:173], v[218:221], v[28:31]
	v_mfma_f32_16x16x32_bf16 v[20:23], v[178:181], v[218:221], v[20:23]
	v_mfma_f32_16x16x32_bf16 v[12:15], v[170:173], v[226:229], v[12:15]
	v_mfma_f32_16x16x32_bf16 v[4:7], v[178:181], v[226:229], v[4:7]
	s_setprio 0
	s_setprio 1
	v_mfma_f32_16x16x32_bf16 v[56:59], v[182:185], v[198:201], v[56:59]
	v_mfma_f32_16x16x32_bf16 v[48:51], v[190:193], v[198:201], v[48:51]
	v_mfma_f32_16x16x32_bf16 v[40:43], v[182:185], v[206:209], v[40:43]
	v_mfma_f32_16x16x32_bf16 v[32:35], v[190:193], v[206:209], v[32:35]
	v_mfma_f32_16x16x32_bf16 v[24:27], v[182:185], v[214:217], v[24:27]
	v_mfma_f32_16x16x32_bf16 v[16:19], v[190:193], v[214:217], v[16:19]
	v_mfma_f32_16x16x32_bf16 v[8:11], v[182:185], v[222:225], v[8:11]
	v_mfma_f32_16x16x32_bf16 v[0:3], v[190:193], v[222:225], v[0:3]
	v_mfma_f32_16x16x32_bf16 v[56:59], v[186:189], v[202:205], v[56:59]
	v_mfma_f32_16x16x32_bf16 v[48:51], v[194:197], v[202:205], v[48:51]
	v_mfma_f32_16x16x32_bf16 v[40:43], v[186:189], v[210:213], v[40:43]
	v_mfma_f32_16x16x32_bf16 v[32:35], v[194:197], v[210:213], v[32:35]
	v_mfma_f32_16x16x32_bf16 v[24:27], v[186:189], v[218:221], v[24:27]
	v_mfma_f32_16x16x32_bf16 v[16:19], v[194:197], v[218:221], v[16:19]
	v_mfma_f32_16x16x32_bf16 v[8:11], v[186:189], v[226:229], v[8:11]
	v_mfma_f32_16x16x32_bf16 v[0:3], v[194:197], v[226:229], v[0:3]
	s_setprio 0
	s_barrier
	s_add_u32 s46, s46, 0x100
	s_addc_u32 s47, s47, 0
	s_add_u32 s43, s43, 0x100
	s_addc_u32 s79, s79, 0
	s_cmp_ge_i32 s80, s91
	s_mov_b32 s48, s80
	s_cbranch_scc1 .Lkx_9

.LBB0_1817:
	s_add_i32 s84, s3, 0x18000
	s_mov_b64 s[20:21], 0x80
	v_lshl_add_u64 v[8:9], v[8:9], 0, s[20:21]
	s_mov_b32 m0, s84
	s_add_i32 s85, s3, 0x1a000
	s_waitcnt vmcnt(2)
	s_mov_b32 s99, 0
	s_barrier
	global_load_lds_dwordx4 v[8:9], off
	v_lshl_add_u64 v[4:5], v[4:5], 0, s[20:21]
	s_mov_b32 m0, s85
	s_add_i32 s86, s3, 0x8000
	global_load_lds_dwordx4 v[4:5], off
	v_lshl_add_u64 v[4:5], v[6:7], 0, s[20:21]
	s_mov_b32 m0, s86
	s_add_i32 s87, s3, 0xa000
	global_load_lds_dwordx4 v[4:5], off
	v_lshl_add_u64 v[4:5], v[10:11], 0, s[20:21]
	s_mov_b32 m0, s87
	s_add_i32 s88, s3, 0x1c000
	global_load_lds_dwordx4 v[4:5], off
	v_lshl_add_u64 v[2:3], v[2:3], 0, s[20:21]
	s_mov_b32 m0, s88
	s_add_i32 s89, s3, 0x1e000
	global_load_lds_dwordx4 v[2:3], off
	v_lshl_add_u64 v[0:1], v[0:1], 0, s[20:21]
	s_mov_b32 m0, s89
	s_ashr_i32 s0, s25, 31
	global_load_lds_dwordx4 v[0:1], off
	v_bfe_u32 v149, v12, 4, 2
	s_lshr_b32 s0, s0, 26
	v_and_b32_e32 v148, 15, v12
	s_add_i32 s0, s25, s0
	v_lshlrev_b32_e32 v0, 4, v149
	v_lshlrev_b32_e32 v1, 2, v12
	s_ashr_i32 s90, s0, 6
	v_lshl_or_b32 v0, v148, 6, v0
	s_lshl_b32 s0, s6, 13
	v_and_b32_e32 v1, 32, v1
	v_bitop3_b32 v150, v0, s0, v1 bitop3:0xde
	s_lshl_b32 s0, s7, 5
	s_and_b32 s4, s0, 0x60
	s_lshl_b32 s0, s4, 7
	v_bitop3_b32 v2, v0, s0, v1 bitop3:0xde
	v_add_u32_e32 v0, v15, v13
	s_lshl_b32 s91, s6, 6
	v_add_lshl_u32 v0, v0, v14, 1
	v_mov_b32_e32 v1, v131
	s_cmp_gt_i32 s25, 63
	v_lshl_add_u64 v[136:137], s[10:11], 0, v[0:1]
	v_add_u32_e32 v0, v18, v16
	s_waitcnt vmcnt(6)
	s_cselect_b64 s[0:1], -1, 0
	s_add_i32 s92, s90, -2
	v_readlane_b32 s6, v246, 5
	v_add_lshl_u32 v0, v0, v17, 1
	s_cmpk_lt_u32 s24, 0x100
	s_mov_b32 s27, 0
	v_readlane_b32 s7, v246, 6
	v_lshl_add_u64 v[138:139], s[10:11], 0, v[0:1]
	v_cndmask_b32_e64 v0, 0, 1, s[0:1]
	s_cselect_b64 s[24:25], -1, 0
	s_ashr_i32 s94, s91, 31
	s_ashr_i32 s68, s6, 31
	s_mov_b32 s69, s6
	s_ashr_i32 s70, s2, 31
	v_mov_b64_e32 v[140:141], 0x200
	v_mov_b64_e32 v[142:143], 0x1ff
	v_cmp_ne_u32_e64 s[6:7], 1, v0
	v_or_b32_e32 v151, 0x10000, v2
	v_add_u32_e32 v152, 0x10400, v2
	v_add_u32_e32 v153, 0x10800, v2
	v_add_u32_e32 v154, 0x10c00, v2
	v_or_b32_e32 v155, 0x14000, v2
	v_add_u32_e32 v156, 0x14400, v2
	v_add_u32_e32 v157, 0x14800, v2
	v_add_u32_e32 v158, 0x14c00, v2
	s_add_i32 s71, s3, 0xc000
	s_add_i32 s72, s3, 0xe000
	v_or_b32_e32 v159, 0x18000, v2
	v_add_u32_e32 v160, 0x18400, v2
	v_add_u32_e32 v161, 0x18800, v2
	v_add_u32_e32 v164, 0x18c00, v2
	v_or_b32_e32 v165, 0x1c000, v2
	v_add_u32_e32 v166, 0x1c400, v2
	v_add_u32_e32 v167, 0x1c800, v2
	v_add_u32_e32 v168, 0x1cc00, v2
	v_mbcnt_hi_u32_b32 v163, -1, v163
	s_lshl_b32 s26, s4, 1
	s_mov_b64 s[36:37], 0x90
	s_mov_b64 s[42:43], 0xa0
	s_mov_b64 s[46:47], 0xb0
	s_mov_b32 s73, s27
	s_barrier
	s_branch .LBB0_1820

.LBB0_1830:
	s_and_b64 vcc, exec, s[6:7]
	s_waitcnt lgkmcnt(0)
	s_cbranch_vccnz .Lkz_10
	s_branch .Lkp_10

.Lkp_10:
	s_add_u32 s52, s80, 0x80
	s_addc_u32 s53, s81, 0
	s_add_u32 s51, s78, 0x100
	s_addc_u32 s77, s79, 0
	s_mov_b32 s54, 0
	ds_read_b128 v[144:147], v151
	ds_read_b128 v[170:173], v152
	ds_read_b128 v[174:177], v153
	ds_read_b128 v[178:181], v154
	ds_read_b128 v[182:185], v155
	ds_read_b128 v[186:189], v156
	ds_read_b128 v[190:193], v157
	ds_read_b128 v[194:197], v158
	s_add_i32 s78, s54, 2
	s_add_u32 s64, s52, 0x80
	s_addc_u32 s55, s53, 0
	s_cmp_eq_u32 s92, s54
	s_cselect_b32 s54, s0, s64
	s_cselect_b32 s55, s1, s55
	s_cselect_b32 s65, s49, s77
	s_cselect_b32 s64, s48, s51
	s_mov_b32 m0, s71
	v_lshl_add_u64 v[230:231], s[52:53], 0, v[136:137]
	ds_read_b128 v[198:201], v150
	ds_read_b128 v[202:205], v150 offset:1024
	ds_read_b128 v[206:209], v150 offset:2048
	ds_read_b128 v[210:213], v150 offset:3072
	ds_read_b128 v[214:217], v150 offset:4096
	ds_read_b128 v[218:221], v150 offset:5120
	ds_read_b128 v[222:225], v150 offset:6144
	ds_read_b128 v[226:229], v150 offset:7168
	global_load_lds_dwordx4 v[230:231], off
	v_lshl_add_u64 v[230:231], s[52:53], 0, v[138:139]
	s_mov_b32 m0, s72
	s_nop 0
	global_load_lds_dwordx4 v[230:231], off
	s_cmp_lg_u32 s99, 0
	s_cbranch_scc1 .Lsw_10_0
	s_waitcnt vmcnt(8)
.Lsw_10_0:
	s_waitcnt vmcnt(24)
	s_waitcnt lgkmcnt(0)
	s_barrier
	s_setprio 1
	s_waitcnt lgkmcnt(0)
	v_mfma_f32_16x16x32_bf16 v[124:127], v[144:147], v[198:201], 0
	v_mfma_f32_16x16x32_bf16 v[120:123], v[174:177], v[198:201], 0
	v_mfma_f32_16x16x32_bf16 v[108:111], v[144:147], v[206:209], 0
	v_mfma_f32_16x16x32_bf16 v[104:107], v[174:177], v[206:209], 0
	v_mfma_f32_16x16x32_bf16 v[92:95], v[144:147], v[214:217], 0
	v_mfma_f32_16x16x32_bf16 v[88:91], v[174:177], v[214:217], 0
	v_mfma_f32_16x16x32_bf16 v[76:79], v[144:147], v[222:225], 0
	v_mfma_f32_16x16x32_bf16 v[72:75], v[174:177], v[222:225], 0
	v_mfma_f32_16x16x32_bf16 v[124:127], v[170:173], v[202:205], v[124:127]
	v_mfma_f32_16x16x32_bf16 v[120:123], v[178:181], v[202:205], v[120:123]
	v_mfma_f32_16x16x32_bf16 v[108:111], v[170:173], v[210:213], v[108:111]
	v_mfma_f32_16x16x32_bf16 v[104:107], v[178:181], v[210:213], v[104:107]
	v_mfma_f32_16x16x32_bf16 v[92:95], v[170:173], v[218:221], v[92:95]
	v_mfma_f32_16x16x32_bf16 v[88:91], v[178:181], v[218:221], v[88:91]
	v_mfma_f32_16x16x32_bf16 v[76:79], v[170:173], v[226:229], v[76:79]
	v_mfma_f32_16x16x32_bf16 v[72:75], v[178:181], v[226:229], v[72:75]
	s_setprio 0
	s_setprio 1
	v_mfma_f32_16x16x32_bf16 v[116:119], v[182:185], v[198:201], 0
	v_mfma_f32_16x16x32_bf16 v[112:115], v[190:193], v[198:201], 0
	v_mfma_f32_16x16x32_bf16 v[100:103], v[182:185], v[206:209], 0
	v_mfma_f32_16x16x32_bf16 v[96:99], v[190:193], v[206:209], 0
	v_mfma_f32_16x16x32_bf16 v[84:87], v[182:185], v[214:217], 0
	v_mfma_f32_16x16x32_bf16 v[80:83], v[190:193], v[214:217], 0
	v_mfma_f32_16x16x32_bf16 v[68:71], v[182:185], v[222:225], 0
	v_mfma_f32_16x16x32_bf16 v[64:67], v[190:193], v[222:225], 0
	v_mfma_f32_16x16x32_bf16 v[116:119], v[186:189], v[202:205], v[116:119]
	v_mfma_f32_16x16x32_bf16 v[112:115], v[194:197], v[202:205], v[112:115]
	v_mfma_f32_16x16x32_bf16 v[100:103], v[186:189], v[210:213], v[100:103]
	v_mfma_f32_16x16x32_bf16 v[96:99], v[194:197], v[210:213], v[96:99]
	v_mfma_f32_16x16x32_bf16 v[84:87], v[186:189], v[218:221], v[84:87]
	v_mfma_f32_16x16x32_bf16 v[80:83], v[194:197], v[218:221], v[80:83]
	v_mfma_f32_16x16x32_bf16 v[68:71], v[186:189], v[226:229], v[68:71]
	v_mfma_f32_16x16x32_bf16 v[64:67], v[194:197], v[226:229], v[64:67]
	s_setprio 0
	s_barrier
	s_mov_b32 m0, s28
	v_lshl_add_u64 v[230:231], s[64:65], 0, v[130:131]
	v_lshl_add_u64 v[232:233], s[64:65], 0, v[134:135]
	s_add_u32 s64, s64, s12
	ds_read_b128 v[198:201], v150 offset:16384
	ds_read_b128 v[202:205], v150 offset:17408
	ds_read_b128 v[206:209], v150 offset:18432
	ds_read_b128 v[210:213], v150 offset:19456
	ds_read_b128 v[214:217], v150 offset:20480
	ds_read_b128 v[218:221], v150 offset:21504
	ds_read_b128 v[222:225], v150 offset:22528
	ds_read_b128 v[226:229], v150 offset:23552
	global_load_lds_dwordx4 v[230:231], off
	s_mov_b32 m0, s29
	s_addc_u32 s65, s65, s13
	global_load_lds_dwordx4 v[232:233], off
	v_lshl_add_u64 v[234:235], s[64:65], 0, v[130:131]
	s_mov_b32 m0, s30
	v_lshl_add_u64 v[236:237], s[64:65], 0, v[134:135]
	global_load_lds_dwordx4 v[234:235], off
	s_mov_b32 m0, s31
	v_lshl_add_u64 v[238:239], s[54:55], 0, v[128:129]
	global_load_lds_dwordx4 v[236:237], off
	s_mov_b32 m0, s3
	v_lshl_add_u64 v[240:241], s[54:55], 0, v[132:133]
	global_load_lds_dwordx4 v[238:239], off
	s_mov_b32 m0, s33
	s_nop 0
	global_load_lds_dwordx4 v[240:241], off
	s_cmp_lg_u32 s99, 0
	s_cbranch_scc1 .Lsw_10_1
	s_waitcnt vmcnt(8)
.Lsw_10_1:
	s_waitcnt vmcnt(24)
	s_waitcnt lgkmcnt(0)
	s_barrier
	s_setprio 1
	s_waitcnt lgkmcnt(0)
	v_mfma_f32_16x16x32_bf16 v[60:63], v[144:147], v[198:201], 0
	v_mfma_f32_16x16x32_bf16 v[56:59], v[174:177], v[198:201], 0
	v_mfma_f32_16x16x32_bf16 v[44:47], v[144:147], v[206:209], 0
	v_mfma_f32_16x16x32_bf16 v[40:43], v[174:177], v[206:209], 0
	v_mfma_f32_16x16x32_bf16 v[28:31], v[144:147], v[214:217], 0
	v_mfma_f32_16x16x32_bf16 v[24:27], v[174:177], v[214:217], 0
	v_mfma_f32_16x16x32_bf16 v[12:15], v[144:147], v[222:225], 0
	v_mfma_f32_16x16x32_bf16 v[8:11], v[174:177], v[222:225], 0
	v_mfma_f32_16x16x32_bf16 v[60:63], v[170:173], v[202:205], v[60:63]
	v_mfma_f32_16x16x32_bf16 v[56:59], v[178:181], v[202:205], v[56:59]
	v_mfma_f32_16x16x32_bf16 v[44:47], v[170:173], v[210:213], v[44:47]
	v_mfma_f32_16x16x32_bf16 v[40:43], v[178:181], v[210:213], v[40:43]
	v_mfma_f32_16x16x32_bf16 v[28:31], v[170:173], v[218:221], v[28:31]
	v_mfma_f32_16x16x32_bf16 v[24:27], v[178:181], v[218:221], v[24:27]
	v_mfma_f32_16x16x32_bf16 v[12:15], v[170:173], v[226:229], v[12:15]
	v_mfma_f32_16x16x32_bf16 v[8:11], v[178:181], v[226:229], v[8:11]
	s_setprio 0
	s_setprio 1
	v_mfma_f32_16x16x32_bf16 v[52:55], v[182:185], v[198:201], 0
	v_mfma_f32_16x16x32_bf16 v[48:51], v[190:193], v[198:201], 0
	v_mfma_f32_16x16x32_bf16 v[36:39], v[182:185], v[206:209], 0
	v_mfma_f32_16x16x32_bf16 v[32:35], v[190:193], v[206:209], 0
	v_mfma_f32_16x16x32_bf16 v[20:23], v[182:185], v[214:217], 0
	v_mfma_f32_16x16x32_bf16 v[16:19], v[190:193], v[214:217], 0
	v_mfma_f32_16x16x32_bf16 v[4:7], v[182:185], v[222:225], 0
	v_mfma_f32_16x16x32_bf16 v[0:3], v[190:193], v[222:225], 0
	v_mfma_f32_16x16x32_bf16 v[52:55], v[186:189], v[202:205], v[52:55]
	v_mfma_f32_16x16x32_bf16 v[48:51], v[194:197], v[202:205], v[48:51]
	v_mfma_f32_16x16x32_bf16 v[36:39], v[186:189], v[210:213], v[36:39]
	v_mfma_f32_16x16x32_bf16 v[32:35], v[194:197], v[210:213], v[32:35]
	v_mfma_f32_16x16x32_bf16 v[20:23], v[186:189], v[218:221], v[20:23]
	v_mfma_f32_16x16x32_bf16 v[16:19], v[194:197], v[218:221], v[16:19]
	v_mfma_f32_16x16x32_bf16 v[4:7], v[186:189], v[226:229], v[4:7]
	v_mfma_f32_16x16x32_bf16 v[0:3], v[194:197], v[226:229], v[0:3]
	s_setprio 0
	s_barrier
	ds_read_b128 v[144:147], v159
	ds_read_b128 v[170:173], v160
	ds_read_b128 v[174:177], v161
	ds_read_b128 v[178:181], v164
	ds_read_b128 v[182:185], v165
	ds_read_b128 v[186:189], v166
	ds_read_b128 v[190:193], v167
	ds_read_b128 v[194:197], v168
	s_add_u32 s54, s54, s10
	s_addc_u32 s55, s55, s11
	s_mov_b32 m0, s34
	v_lshl_add_u64 v[242:243], s[54:55], 0, v[128:129]
	ds_read_b128 v[198:201], v150 offset:32768
	ds_read_b128 v[202:205], v150 offset:33792
	ds_read_b128 v[206:209], v150 offset:34816
	ds_read_b128 v[210:213], v150 offset:35840
	ds_read_b128 v[214:217], v150 offset:36864
	ds_read_b128 v[218:221], v150 offset:37888
	ds_read_b128 v[222:225], v150 offset:38912
	ds_read_b128 v[226:229], v150 offset:39936
	global_load_lds_dwordx4 v[242:243], off
	v_lshl_add_u64 v[242:243], s[54:55], 0, v[132:133]
	s_mov_b32 m0, s35
	s_nop 0
	global_load_lds_dwordx4 v[242:243], off
	s_waitcnt vmcnt(8)
	s_waitcnt lgkmcnt(0)
	s_barrier
	s_setprio 1
	s_waitcnt lgkmcnt(0)
	v_mfma_f32_16x16x32_bf16 v[124:127], v[144:147], v[198:201], v[124:127]
	v_mfma_f32_16x16x32_bf16 v[120:123], v[174:177], v[198:201], v[120:123]
	v_mfma_f32_16x16x32_bf16 v[108:111], v[144:147], v[206:209], v[108:111]
	v_mfma_f32_16x16x32_bf16 v[104:107], v[174:177], v[206:209], v[104:107]
	v_mfma_f32_16x16x32_bf16 v[92:95], v[144:147], v[214:217], v[92:95]
	v_mfma_f32_16x16x32_bf16 v[88:91], v[174:177], v[214:217], v[88:91]
	v_mfma_f32_16x16x32_bf16 v[76:79], v[144:147], v[222:225], v[76:79]
	v_mfma_f32_16x16x32_bf16 v[72:75], v[174:177], v[222:225], v[72:75]
	v_mfma_f32_16x16x32_bf16 v[124:127], v[170:173], v[202:205], v[124:127]
	v_mfma_f32_16x16x32_bf16 v[120:123], v[178:181], v[202:205], v[120:123]
	v_mfma_f32_16x16x32_bf16 v[108:111], v[170:173], v[210:213], v[108:111]
	v_mfma_f32_16x16x32_bf16 v[104:107], v[178:181], v[210:213], v[104:107]
	v_mfma_f32_16x16x32_bf16 v[92:95], v[170:173], v[218:221], v[92:95]
	v_mfma_f32_16x16x32_bf16 v[88:91], v[178:181], v[218:221], v[88:91]
	v_mfma_f32_16x16x32_bf16 v[76:79], v[170:173], v[226:229], v[76:79]
	v_mfma_f32_16x16x32_bf16 v[72:75], v[178:181], v[226:229], v[72:75]
	s_setprio 0
	s_setprio 1
	v_mfma_f32_16x16x32_bf16 v[116:119], v[182:185], v[198:201], v[116:119]
	v_mfma_f32_16x16x32_bf16 v[112:115], v[190:193], v[198:201], v[112:115]
	v_mfma_f32_16x16x32_bf16 v[100:103], v[182:185], v[206:209], v[100:103]
	v_mfma_f32_16x16x32_bf16 v[96:99], v[190:193], v[206:209], v[96:99]
	v_mfma_f32_16x16x32_bf16 v[84:87], v[182:185], v[214:217], v[84:87]
	v_mfma_f32_16x16x32_bf16 v[80:83], v[190:193], v[214:217], v[80:83]
	v_mfma_f32_16x16x32_bf16 v[68:71], v[182:185], v[222:225], v[68:71]
	v_mfma_f32_16x16x32_bf16 v[64:67], v[190:193], v[222:225], v[64:67]
	v_mfma_f32_16x16x32_bf16 v[116:119], v[186:189], v[202:205], v[116:119]
	v_mfma_f32_16x16x32_bf16 v[112:115], v[194:197], v[202:205], v[112:115]
	v_mfma_f32_16x16x32_bf16 v[100:103], v[186:189], v[210:213], v[100:103]
	v_mfma_f32_16x16x32_bf16 v[96:99], v[194:197], v[210:213], v[96:99]
	v_mfma_f32_16x16x32_bf16 v[84:87], v[186:189], v[218:221], v[84:87]
	v_mfma_f32_16x16x32_bf16 v[80:83], v[194:197], v[218:221], v[80:83]
	v_mfma_f32_16x16x32_bf16 v[68:71], v[186:189], v[226:229], v[68:71]
	v_mfma_f32_16x16x32_bf16 v[64:67], v[194:197], v[226:229], v[64:67]
	s_setprio 0
	s_barrier
	s_mov_b32 m0, s84
	v_lshl_add_u64 v[230:231], v[230:231], 0, s[20:21]
	ds_read_b128 v[198:201], v150 offset:49152
	ds_read_b128 v[202:205], v150 offset:50176
	ds_read_b128 v[206:209], v150 offset:51200
	ds_read_b128 v[210:213], v150 offset:52224
	ds_read_b128 v[214:217], v150 offset:53248
	ds_read_b128 v[218:221], v150 offset:54272
	ds_read_b128 v[222:225], v150 offset:55296
	ds_read_b128 v[226:229], v150 offset:56320
	global_load_lds_dwordx4 v[230:231], off
	v_lshl_add_u64 v[230:231], v[232:233], 0, s[20:21]
	s_mov_b32 m0, s85
	s_nop 0
	global_load_lds_dwordx4 v[230:231], off
	v_lshl_add_u64 v[230:231], v[234:235], 0, s[20:21]
	s_mov_b32 m0, s88
	s_nop 0
	global_load_lds_dwordx4 v[230:231], off
	v_lshl_add_u64 v[230:231], v[236:237], 0, s[20:21]
	s_mov_b32 m0, s89
	s_nop 0
	global_load_lds_dwordx4 v[230:231], off
	v_lshl_add_u64 v[230:231], v[238:239], 0, s[20:21]
	s_mov_b32 m0, s86
	s_nop 0
	global_load_lds_dwordx4 v[230:231], off
	v_lshl_add_u64 v[230:231], v[240:241], 0, s[20:21]
	s_mov_b32 m0, s87
	s_nop 0
	global_load_lds_dwordx4 v[230:231], off
	s_waitcnt vmcnt(8)
	s_waitcnt lgkmcnt(0)
	s_barrier
	s_setprio 1
	s_waitcnt lgkmcnt(0)
	v_mfma_f32_16x16x32_bf16 v[60:63], v[144:147], v[198:201], v[60:63]
	v_mfma_f32_16x16x32_bf16 v[56:59], v[174:177], v[198:201], v[56:59]
	v_mfma_f32_16x16x32_bf16 v[44:47], v[144:147], v[206:209], v[44:47]
	v_mfma_f32_16x16x32_bf16 v[40:43], v[174:177], v[206:209], v[40:43]
	v_mfma_f32_16x16x32_bf16 v[28:31], v[144:147], v[214:217], v[28:31]
	v_mfma_f32_16x16x32_bf16 v[24:27], v[174:177], v[214:217], v[24:27]
	v_mfma_f32_16x16x32_bf16 v[12:15], v[144:147], v[222:225], v[12:15]
	v_mfma_f32_16x16x32_bf16 v[8:11], v[174:177], v[222:225], v[8:11]
	v_mfma_f32_16x16x32_bf16 v[60:63], v[170:173], v[202:205], v[60:63]
	v_mfma_f32_16x16x32_bf16 v[56:59], v[178:181], v[202:205], v[56:59]
	v_mfma_f32_16x16x32_bf16 v[44:47], v[170:173], v[210:213], v[44:47]
	v_mfma_f32_16x16x32_bf16 v[40:43], v[178:181], v[210:213], v[40:43]
	v_mfma_f32_16x16x32_bf16 v[28:31], v[170:173], v[218:221], v[28:31]
	v_mfma_f32_16x16x32_bf16 v[24:27], v[178:181], v[218:221], v[24:27]
	v_mfma_f32_16x16x32_bf16 v[12:15], v[170:173], v[226:229], v[12:15]
	v_mfma_f32_16x16x32_bf16 v[8:11], v[178:181], v[226:229], v[8:11]
	s_setprio 0
	s_setprio 1
	v_mfma_f32_16x16x32_bf16 v[52:55], v[182:185], v[198:201], v[52:55]
	v_mfma_f32_16x16x32_bf16 v[48:51], v[190:193], v[198:201], v[48:51]
	v_mfma_f32_16x16x32_bf16 v[36:39], v[182:185], v[206:209], v[36:39]
	v_mfma_f32_16x16x32_bf16 v[32:35], v[190:193], v[206:209], v[32:35]
	v_mfma_f32_16x16x32_bf16 v[20:23], v[182:185], v[214:217], v[20:23]
	v_mfma_f32_16x16x32_bf16 v[16:19], v[190:193], v[214:217], v[16:19]
	v_mfma_f32_16x16x32_bf16 v[4:7], v[182:185], v[222:225], v[4:7]
	v_mfma_f32_16x16x32_bf16 v[0:3], v[190:193], v[222:225], v[0:3]
	v_mfma_f32_16x16x32_bf16 v[52:55], v[186:189], v[202:205], v[52:55]
	v_mfma_f32_16x16x32_bf16 v[48:51], v[194:197], v[202:205], v[48:51]
	v_mfma_f32_16x16x32_bf16 v[36:39], v[186:189], v[210:213], v[36:39]
	v_mfma_f32_16x16x32_bf16 v[32:35], v[194:197], v[210:213], v[32:35]
	v_mfma_f32_16x16x32_bf16 v[20:23], v[186:189], v[218:221], v[20:23]
	v_mfma_f32_16x16x32_bf16 v[16:19], v[194:197], v[218:221], v[16:19]
	v_mfma_f32_16x16x32_bf16 v[4:7], v[186:189], v[226:229], v[4:7]
	v_mfma_f32_16x16x32_bf16 v[0:3], v[194:197], v[226:229], v[0:3]
	s_setprio 0
	s_barrier
	s_add_u32 s52, s52, 0x100
	s_addc_u32 s53, s53, 0
	s_add_u32 s51, s51, 0x100
	s_addc_u32 s77, s77, 0
	s_cmp_ge_i32 s78, s90
	s_mov_b32 s54, s78
	s_cbranch_scc1 .Lkx_10

.Lkx_10:
	s_mov_b32 s99, 1
	s_mov_b64 s[64:65], s[82:83]
